# K-loop load segments: LDS-DMA loads issued ahead of the segment's ds_reads (24 segments), on cvb
# baseline (speedup 1.0000x reference)
;     __host__ __device__ bool next(int i, Unit& u) const { const long L = (long)i * G + c; if (L >= nwg) return false; return unit_of((int)L, u); }
;     __host__ __device__ bool next(int i, Unit& u) const { const int L = i == 0 ? l0 : (i == 1 ? l1 : (i == 2 ? l2 : -1)); if (L < 0 || L >= s.nwg) return false; return s.unit_of(L, u); }
;     __host__ __device__ bool next(int i, Unit& u) const { const bool ok = s.next(i >> 1, u); u.kh = i & 1; return ok; }
; template <class Epi, class Sched, bool ALIGN_EPI = false, bool SP2 = false>
; __device__ __forceinline__ void gemm_phase(PG8_LAS unsigned char* lds, const Gemm g, const Sched& S, const Epi& E) {
;     ...
;         const bool has_next = S.next(ui + 1, nxt);
;         const char* nA = has_next ? (const char*)g.A + (size_t)nxt.pm * tstep + nxt.kh * khb : cA; const char* nB = has_next ? (const char*)g.Bt + (size_t)nxt.pn * tstep + nxt.kh * khb : cB;
;         for (int t = 0; t < nt; t += 2) {
;             const bool last = (t == nt - 2);
;             const char* a1 = cA + (size_t)(t + 1) * kstep;
;             const char* a2 = last ? nA : cA + (size_t)(t + 2) * kstep; const char* b2 = last ? nB : cB + (size_t)(t + 2) * kstep;
;             const char* a3 = a2 + kstep; const char* b3 = b2 + kstep;
;             if (last && has_next) S.a_ready(nxt);
;             if constexpr (SP2) {
;             PG8_LDB(B0, 0, 0); PG8_LDB(B1, 0, 1); PG8_SCHED; PG8_LDA(At, 0, 0); PG8_STAGE(PG8_SA(1, 1), a1 + hstep, voffA);
;             PG8_WAIT_V(8); PG8_WAIT_L(0); PG8_BAR; PG8_MMA(0, 0, At, B0); PG8_MMA(0, 1, At, B1); PG8_BAR; PG8_SCHED;
;             PG8_LDA(At, 0, 1); PG8_STAGE(PG8_SB(0, 0), b2, voffB); PG8_STAGE(PG8_SB(0, 1), b2 + hstep, voffB); PG8_STAGE(PG8_SA(0, 0), a2, voffA);
;             PG8_WAIT_V(8); PG8_WAIT_L(0); PG8_BAR; PG8_MMA(1, 0, At, B0); PG8_MMA(1, 1, At, B1); PG8_BAR; PG8_SCHED;
;             PG8_LDB(B0, 1, 0); PG8_LDB(B1, 1, 1); PG8_SCHED; PG8_LDA(At, 1, 0); PG8_STAGE(PG8_SA(0, 1), a2 + hstep, voffA);
;             PG8_WAIT_V(8); PG8_WAIT_L(0); PG8_BAR; PG8_MMA(0, 0, At, B0); PG8_MMA(0, 1, At, B1); PG8_BAR; PG8_SCHED;
;             PG8_LDA(At, 1, 1); PG8_STAGE(PG8_SB(1, 0), b3, voffB); PG8_STAGE(PG8_SB(1, 1), b3 + hstep, voffB); PG8_STAGE(PG8_SA(1, 0), a3, voffA);
;             PG8_WAIT_V(8); PG8_WAIT_L(0); PG8_BAR; PG8_MMA(1, 0, At, B0); PG8_MMA(1, 1, At, B1); PG8_BAR; PG8_SCHED;
.LBB0_95:
	s_waitcnt lgkmcnt(0)
	s_ashr_i32 s55, s54, 31
	s_lshl_b64 s[34:35], s[54:55], 19
	s_add_u32 s76, s50, s34
	s_addc_u32 s77, s51, s35
	s_and_b64 s[34:35], s[2:3], exec
	s_cselect_b32 s8, s77, s81
	s_cselect_b32 s55, s76, s80
	s_ashr_i32 s49, s48, 31
	s_lshl_b64 s[34:35], s[48:49], 19
	s_add_u32 s78, s88, s34
	s_addc_u32 s79, s89, s35
	s_and_b64 s[34:35], s[2:3], exec
	s_cselect_b32 s49, s79, s83
	s_cselect_b32 vcc_lo, s78, s82
	s_add_u32 s80, s80, 0x40080
	s_addc_u32 s81, s81, 0
	s_add_u32 vcc_hi, s82, 0x100
	s_addc_u32 s34, s83, 0
	s_mov_b32 s35, -2
	ds_read_b128 v[128:131], v178
	ds_read_b128 v[132:135], v178 offset:1024
	ds_read_b128 v[136:139], v178 offset:2048
	ds_read_b128 v[140:143], v178 offset:3072
	ds_read_b128 v[166:169], v179
	ds_read_b128 v[170:173], v179 offset:1024
	ds_read_b128 v[190:193], v179 offset:2048
	ds_read_b128 v[194:197], v179 offset:3072
	s_add_u32 s36, s80, 0xfffc0080
	s_addc_u32 s37, s81, -1
	s_cmp_eq_u32 s35, 12
	s_cselect_b32 s87, s8, s37
	s_cselect_b32 s86, s55, s36
	s_cselect_b32 s83, s49, s34
	s_cselect_b32 s82, vcc_lo, vcc_hi
	s_add_i32 m0, s93, 0xc000
	ds_read_b128 v[198:201], v181
	ds_read_b128 v[202:205], v181 offset:1024
	ds_read_b128 v[206:209], v181 offset:2048
	ds_read_b128 v[210:213], v181 offset:3072
	ds_read_b128 v[214:217], v181 offset:4096
	ds_read_b128 v[218:221], v181 offset:5120
	ds_read_b128 v[222:225], v181 offset:6144
	ds_read_b128 v[226:229], v181 offset:7168
	global_load_lds_dwordx4 v158, s[80:81]
	s_add_i32 m0, s93, 0xe000
	s_nop 0
	global_load_lds_dwordx4 v160, s[80:81]
	s_waitcnt vmcnt(8)
	s_waitcnt lgkmcnt(0)
	s_barrier
	s_setprio 1
	v_mfma_f32_16x16x32_bf16 v[124:127], v[128:131], v[198:201], 0
	v_mfma_f32_16x16x32_bf16 v[120:123], v[136:139], v[198:201], 0
	v_mfma_f32_16x16x32_bf16 v[108:111], v[128:131], v[206:209], 0
	v_mfma_f32_16x16x32_bf16 v[104:107], v[136:139], v[206:209], 0
	v_mfma_f32_16x16x32_bf16 v[92:95], v[128:131], v[214:217], 0
	v_mfma_f32_16x16x32_bf16 v[88:91], v[136:139], v[214:217], 0
	v_mfma_f32_16x16x32_bf16 v[76:79], v[128:131], v[222:225], 0
	v_mfma_f32_16x16x32_bf16 v[72:75], v[136:139], v[222:225], 0
	v_mfma_f32_16x16x32_bf16 v[124:127], v[132:135], v[202:205], v[124:127]
	v_mfma_f32_16x16x32_bf16 v[120:123], v[140:143], v[202:205], v[120:123]
	v_mfma_f32_16x16x32_bf16 v[108:111], v[132:135], v[210:213], v[108:111]
	v_mfma_f32_16x16x32_bf16 v[104:107], v[140:143], v[210:213], v[104:107]
	v_mfma_f32_16x16x32_bf16 v[92:95], v[132:135], v[218:221], v[92:95]
	v_mfma_f32_16x16x32_bf16 v[88:91], v[140:143], v[218:221], v[88:91]
	v_mfma_f32_16x16x32_bf16 v[76:79], v[132:135], v[226:229], v[76:79]
	v_mfma_f32_16x16x32_bf16 v[72:75], v[140:143], v[226:229], v[72:75]
	v_mfma_f32_16x16x32_bf16 v[116:119], v[166:169], v[198:201], 0
	v_mfma_f32_16x16x32_bf16 v[112:115], v[190:193], v[198:201], 0
	v_mfma_f32_16x16x32_bf16 v[100:103], v[166:169], v[206:209], 0
	v_mfma_f32_16x16x32_bf16 v[96:99], v[190:193], v[206:209], 0
	v_mfma_f32_16x16x32_bf16 v[84:87], v[166:169], v[214:217], 0
	v_mfma_f32_16x16x32_bf16 v[80:83], v[190:193], v[214:217], 0
	v_mfma_f32_16x16x32_bf16 v[68:71], v[166:169], v[222:225], 0
	v_mfma_f32_16x16x32_bf16 v[64:67], v[190:193], v[222:225], 0
	v_mfma_f32_16x16x32_bf16 v[116:119], v[170:173], v[202:205], v[116:119]
	v_mfma_f32_16x16x32_bf16 v[112:115], v[194:197], v[202:205], v[112:115]
	v_mfma_f32_16x16x32_bf16 v[100:103], v[170:173], v[210:213], v[100:103]
	v_mfma_f32_16x16x32_bf16 v[96:99], v[194:197], v[210:213], v[96:99]
	v_mfma_f32_16x16x32_bf16 v[84:87], v[170:173], v[218:221], v[84:87]
	v_mfma_f32_16x16x32_bf16 v[80:83], v[194:197], v[218:221], v[80:83]
	v_mfma_f32_16x16x32_bf16 v[68:71], v[170:173], v[226:229], v[68:71]
	v_mfma_f32_16x16x32_bf16 v[64:67], v[194:197], v[226:229], v[64:67]
	s_setprio 0
	s_barrier
	s_add_u32 s98, s82, s26
	s_addc_u32 s99, s83, s27
	s_add_u32 s100, s86, s26
	s_addc_u32 s101, s87, s27
	s_add_i32 s36, s23, s90
	s_mov_b32 m0, s36
	s_nop 0
	global_load_lds_dwordx4 v148, s[82:83]
	s_add_i32 m0, s36, 0x2000
	s_add_u32 s36, s82, 0x40000
	s_addc_u32 s37, s83, 0
	s_add_i32 s20, s41, s90
	global_load_lds_dwordx4 v144, s[82:83]
	s_mov_b32 m0, s20
	s_nop 0
	global_load_lds_dwordx4 v148, s[36:37]
	s_add_i32 m0, s20, 0x2000
	s_nop 0
	global_load_lds_dwordx4 v144, s[36:37]
	s_mov_b32 m0, s93
	s_nop 0
	global_load_lds_dwordx4 v150, s[86:87]
	s_mov_b32 m0, s94
	s_nop 0
	global_load_lds_dwordx4 v146, s[86:87]
	ds_read_b128 v[198:201], v181 offset:16384
	ds_read_b128 v[202:205], v181 offset:17408
	ds_read_b128 v[206:209], v181 offset:18432
	ds_read_b128 v[210:213], v181 offset:19456
	ds_read_b128 v[214:217], v181 offset:20480
	ds_read_b128 v[218:221], v181 offset:21504
	ds_read_b128 v[222:225], v181 offset:22528
	ds_read_b128 v[226:229], v181 offset:23552
	s_waitcnt vmcnt(8)
	s_waitcnt lgkmcnt(0)
	s_barrier
	s_setprio 1
	v_mfma_f32_16x16x32_bf16 v[60:63], v[128:131], v[198:201], 0
	v_mfma_f32_16x16x32_bf16 v[56:59], v[136:139], v[198:201], 0
	v_mfma_f32_16x16x32_bf16 v[44:47], v[128:131], v[206:209], 0
	v_mfma_f32_16x16x32_bf16 v[40:43], v[136:139], v[206:209], 0
	v_mfma_f32_16x16x32_bf16 v[28:31], v[128:131], v[214:217], 0
	v_mfma_f32_16x16x32_bf16 v[24:27], v[136:139], v[214:217], 0
	v_mfma_f32_16x16x32_bf16 v[12:15], v[128:131], v[222:225], 0
	v_mfma_f32_16x16x32_bf16 v[8:11], v[136:139], v[222:225], 0
	v_mfma_f32_16x16x32_bf16 v[60:63], v[132:135], v[202:205], v[60:63]
	v_mfma_f32_16x16x32_bf16 v[56:59], v[140:143], v[202:205], v[56:59]
	v_mfma_f32_16x16x32_bf16 v[44:47], v[132:135], v[210:213], v[44:47]
	v_mfma_f32_16x16x32_bf16 v[40:43], v[140:143], v[210:213], v[40:43]
	v_mfma_f32_16x16x32_bf16 v[28:31], v[132:135], v[218:221], v[28:31]
	v_mfma_f32_16x16x32_bf16 v[24:27], v[140:143], v[218:221], v[24:27]
	v_mfma_f32_16x16x32_bf16 v[12:15], v[132:135], v[226:229], v[12:15]
	v_mfma_f32_16x16x32_bf16 v[8:11], v[140:143], v[226:229], v[8:11]
	v_mfma_f32_16x16x32_bf16 v[52:55], v[166:169], v[198:201], 0
	v_mfma_f32_16x16x32_bf16 v[48:51], v[190:193], v[198:201], 0
	v_mfma_f32_16x16x32_bf16 v[36:39], v[166:169], v[206:209], 0
	v_mfma_f32_16x16x32_bf16 v[32:35], v[190:193], v[206:209], 0
	v_mfma_f32_16x16x32_bf16 v[20:23], v[166:169], v[214:217], 0
	v_mfma_f32_16x16x32_bf16 v[16:19], v[190:193], v[214:217], 0
	v_mfma_f32_16x16x32_bf16 v[4:7], v[166:169], v[222:225], 0
	v_mfma_f32_16x16x32_bf16 v[0:3], v[190:193], v[222:225], 0
	v_mfma_f32_16x16x32_bf16 v[52:55], v[170:173], v[202:205], v[52:55]
	v_mfma_f32_16x16x32_bf16 v[48:51], v[194:197], v[202:205], v[48:51]
	v_mfma_f32_16x16x32_bf16 v[36:39], v[170:173], v[210:213], v[36:39]
	v_mfma_f32_16x16x32_bf16 v[32:35], v[194:197], v[210:213], v[32:35]
	v_mfma_f32_16x16x32_bf16 v[20:23], v[170:173], v[218:221], v[20:23]
	v_mfma_f32_16x16x32_bf16 v[16:19], v[194:197], v[218:221], v[16:19]
	v_mfma_f32_16x16x32_bf16 v[4:7], v[170:173], v[226:229], v[4:7]
	v_mfma_f32_16x16x32_bf16 v[0:3], v[194:197], v[226:229], v[0:3]
	s_setprio 0
	s_barrier
	s_branch .Lmy_peel_96_mid
; #define PG8_STAGE(bufoff, gbase, voff) do { _Pragma("unroll") for (int _i = 0; _i < 2; ++_i) \
;         __builtin_amdgcn_global_load_lds((const unsigned*)((const char*)(gbase) + (voff)[_i]), (PG8_LAS unsigned*)(lds + (bufoff) + ldsw + _i * 8192), 16, 0, 0); } while (0)
; #define PG8_LDA(dst, b, h) do { _Pragma("unroll") for (int m = 0; m < 4; ++m) _Pragma("unroll") for (int k = 0; k < 2; ++k) dst[m][k] = *(const PG8_LAS bf16x8*)(lds + PG8_SA(b, h) + aoff + m * 2048 + k * 1024); } while (0)
; #define PG8_LDB(dst, b, h) do { _Pragma("unroll") for (int n = 0; n < 2; ++n) _Pragma("unroll") for (int k = 0; k < 2; ++k) dst[n][k] = *(const PG8_LAS bf16x8*)(lds + PG8_SB(b, h) + boff + n * 2048 + k * 1024); } while (0)
; #define PG8_MMA(ai, bj, At, Bt) do { __builtin_amdgcn_s_setprio(1); _Pragma("unroll") for (int m = 0; m < 4; ++m) _Pragma("unroll") for (int n = 0; n < 2; ++n) _Pragma("unroll") for (int k = 0; k < 2; ++k) \
;         acc[ai][bj][m][n] = __builtin_amdgcn_mfma_f32_16x16x32_bf16(Bt[n][k], At[m][k], acc[ai][bj][m][n], 0, 0, 0); __builtin_amdgcn_s_setprio(0); } while (0)
; #define PG8_WAIT_V(n) asm volatile("s_waitcnt vmcnt(" #n ")" ::: "memory")
; template <class Epi, class Sched, bool ALIGN_EPI = false, bool SP2 = false>
; __device__ __forceinline__ void gemm_phase(PG8_LAS unsigned char* lds, const Gemm g, const Sched& S, const Epi& E) {
;     ...
;             PG8_LDB(B0, 0, 0); PG8_LDB(B1, 0, 1); PG8_SCHED; PG8_LDA(At, 0, 0); PG8_STAGE(PG8_SA(1, 1), a1 + hstep, voffA);
;             PG8_WAIT_V(8); PG8_WAIT_L(0); PG8_BAR; PG8_MMA(0, 0, At, B0); PG8_MMA(0, 1, At, B1); PG8_BAR; PG8_SCHED;
;             PG8_LDA(At, 0, 1); PG8_STAGE(PG8_SB(0, 0), b2, voffB); PG8_STAGE(PG8_SB(0, 1), b2 + hstep, voffB); PG8_STAGE(PG8_SA(0, 0), a2, voffA);
;             PG8_WAIT_V(8); PG8_WAIT_L(0); PG8_BAR; PG8_MMA(1, 0, At, B0); PG8_MMA(1, 1, At, B1); PG8_BAR; PG8_SCHED;
;             PG8_LDB(B0, 1, 0); PG8_LDB(B1, 1, 1); PG8_SCHED; PG8_LDA(At, 1, 0); PG8_STAGE(PG8_SA(0, 1), a2 + hstep, voffA);
;             PG8_WAIT_V(8); PG8_WAIT_L(0); PG8_BAR; PG8_MMA(0, 0, At, B0); PG8_MMA(0, 1, At, B1); PG8_BAR; PG8_SCHED;
;             PG8_LDA(At, 1, 1); PG8_STAGE(PG8_SB(1, 0), b3, voffB); PG8_STAGE(PG8_SB(1, 1), b3 + hstep, voffB); PG8_STAGE(PG8_SA(1, 0), a3, voffA);
;             PG8_WAIT_V(8); PG8_WAIT_L(0); PG8_BAR; PG8_MMA(1, 0, At, B0); PG8_MMA(1, 1, At, B1); PG8_BAR; PG8_SCHED;
.LBB0_96:
	ds_read_b128 v[128:131], v178
	ds_read_b128 v[132:135], v178 offset:1024
	ds_read_b128 v[136:139], v178 offset:2048
	ds_read_b128 v[140:143], v178 offset:3072
	ds_read_b128 v[166:169], v179
	ds_read_b128 v[170:173], v179 offset:1024
	ds_read_b128 v[190:193], v179 offset:2048
	ds_read_b128 v[194:197], v179 offset:3072
	s_add_u32 s36, s80, 0xfffc0080
	s_addc_u32 s37, s81, -1
	s_cmp_eq_u32 s35, 12
	s_cselect_b32 s87, s8, s37
	s_cselect_b32 s86, s55, s36
	s_cselect_b32 s83, s49, s34
	s_cselect_b32 s82, vcc_lo, vcc_hi
	s_add_i32 m0, s93, 0xc000
	ds_read_b128 v[198:201], v181
	ds_read_b128 v[202:205], v181 offset:1024
	ds_read_b128 v[206:209], v181 offset:2048
	ds_read_b128 v[210:213], v181 offset:3072
	ds_read_b128 v[214:217], v181 offset:4096
	ds_read_b128 v[218:221], v181 offset:5120
	ds_read_b128 v[222:225], v181 offset:6144
	ds_read_b128 v[226:229], v181 offset:7168
	global_load_lds_dwordx4 v158, s[80:81]
	s_add_i32 m0, s93, 0xe000
	s_nop 0
	global_load_lds_dwordx4 v160, s[80:81]
	s_waitcnt vmcnt(8)
	s_waitcnt lgkmcnt(0)
	s_barrier
	s_setprio 1
	v_mfma_f32_16x16x32_bf16 v[124:127], v[128:131], v[198:201], v[124:127]
	v_mfma_f32_16x16x32_bf16 v[120:123], v[136:139], v[198:201], v[120:123]
	v_mfma_f32_16x16x32_bf16 v[108:111], v[128:131], v[206:209], v[108:111]
	v_mfma_f32_16x16x32_bf16 v[104:107], v[136:139], v[206:209], v[104:107]
	v_mfma_f32_16x16x32_bf16 v[92:95], v[128:131], v[214:217], v[92:95]
	v_mfma_f32_16x16x32_bf16 v[88:91], v[136:139], v[214:217], v[88:91]
	v_mfma_f32_16x16x32_bf16 v[76:79], v[128:131], v[222:225], v[76:79]
	v_mfma_f32_16x16x32_bf16 v[72:75], v[136:139], v[222:225], v[72:75]
	v_mfma_f32_16x16x32_bf16 v[124:127], v[132:135], v[202:205], v[124:127]
	v_mfma_f32_16x16x32_bf16 v[120:123], v[140:143], v[202:205], v[120:123]
	v_mfma_f32_16x16x32_bf16 v[108:111], v[132:135], v[210:213], v[108:111]
	v_mfma_f32_16x16x32_bf16 v[104:107], v[140:143], v[210:213], v[104:107]
	v_mfma_f32_16x16x32_bf16 v[92:95], v[132:135], v[218:221], v[92:95]
	v_mfma_f32_16x16x32_bf16 v[88:91], v[140:143], v[218:221], v[88:91]
	v_mfma_f32_16x16x32_bf16 v[76:79], v[132:135], v[226:229], v[76:79]
	v_mfma_f32_16x16x32_bf16 v[72:75], v[140:143], v[226:229], v[72:75]
	v_mfma_f32_16x16x32_bf16 v[116:119], v[166:169], v[198:201], v[116:119]
	v_mfma_f32_16x16x32_bf16 v[112:115], v[190:193], v[198:201], v[112:115]
	v_mfma_f32_16x16x32_bf16 v[100:103], v[166:169], v[206:209], v[100:103]
	v_mfma_f32_16x16x32_bf16 v[96:99], v[190:193], v[206:209], v[96:99]
	v_mfma_f32_16x16x32_bf16 v[84:87], v[166:169], v[214:217], v[84:87]
	v_mfma_f32_16x16x32_bf16 v[80:83], v[190:193], v[214:217], v[80:83]
	v_mfma_f32_16x16x32_bf16 v[68:71], v[166:169], v[222:225], v[68:71]
	v_mfma_f32_16x16x32_bf16 v[64:67], v[190:193], v[222:225], v[64:67]
	v_mfma_f32_16x16x32_bf16 v[116:119], v[170:173], v[202:205], v[116:119]
	v_mfma_f32_16x16x32_bf16 v[112:115], v[194:197], v[202:205], v[112:115]
	v_mfma_f32_16x16x32_bf16 v[100:103], v[170:173], v[210:213], v[100:103]
	v_mfma_f32_16x16x32_bf16 v[96:99], v[194:197], v[210:213], v[96:99]
	v_mfma_f32_16x16x32_bf16 v[84:87], v[170:173], v[218:221], v[84:87]
	v_mfma_f32_16x16x32_bf16 v[80:83], v[194:197], v[218:221], v[80:83]
	v_mfma_f32_16x16x32_bf16 v[68:71], v[170:173], v[226:229], v[68:71]
	v_mfma_f32_16x16x32_bf16 v[64:67], v[194:197], v[226:229], v[64:67]
	s_setprio 0
	s_barrier
	s_add_u32 s98, s82, s26
	s_addc_u32 s99, s83, s27
	s_add_u32 s100, s86, s26
	s_addc_u32 s101, s87, s27
	s_add_i32 s36, s23, s90
	s_mov_b32 m0, s36
	s_nop 0
	global_load_lds_dwordx4 v148, s[82:83]
	s_add_i32 m0, s36, 0x2000
	s_add_u32 s36, s82, 0x40000
	s_addc_u32 s37, s83, 0
	s_add_i32 s20, s41, s90
	global_load_lds_dwordx4 v144, s[82:83]
	s_mov_b32 m0, s20
	s_nop 0
	global_load_lds_dwordx4 v148, s[36:37]
	s_add_i32 m0, s20, 0x2000
	s_nop 0
	global_load_lds_dwordx4 v144, s[36:37]
	s_mov_b32 m0, s93
	s_nop 0
	global_load_lds_dwordx4 v150, s[86:87]
	s_mov_b32 m0, s94
	s_nop 0
	global_load_lds_dwordx4 v146, s[86:87]
	ds_read_b128 v[198:201], v181 offset:16384
	ds_read_b128 v[202:205], v181 offset:17408
	ds_read_b128 v[206:209], v181 offset:18432
	ds_read_b128 v[210:213], v181 offset:19456
	ds_read_b128 v[214:217], v181 offset:20480
	ds_read_b128 v[218:221], v181 offset:21504
	ds_read_b128 v[222:225], v181 offset:22528
	ds_read_b128 v[226:229], v181 offset:23552
	s_waitcnt vmcnt(8)
	s_waitcnt lgkmcnt(0)
	s_barrier
	s_setprio 1
	v_mfma_f32_16x16x32_bf16 v[60:63], v[128:131], v[198:201], v[60:63]
	v_mfma_f32_16x16x32_bf16 v[56:59], v[136:139], v[198:201], v[56:59]
	v_mfma_f32_16x16x32_bf16 v[44:47], v[128:131], v[206:209], v[44:47]
	v_mfma_f32_16x16x32_bf16 v[40:43], v[136:139], v[206:209], v[40:43]
	v_mfma_f32_16x16x32_bf16 v[28:31], v[128:131], v[214:217], v[28:31]
	v_mfma_f32_16x16x32_bf16 v[24:27], v[136:139], v[214:217], v[24:27]
	v_mfma_f32_16x16x32_bf16 v[12:15], v[128:131], v[222:225], v[12:15]
	v_mfma_f32_16x16x32_bf16 v[8:11], v[136:139], v[222:225], v[8:11]
	v_mfma_f32_16x16x32_bf16 v[60:63], v[132:135], v[202:205], v[60:63]
	v_mfma_f32_16x16x32_bf16 v[56:59], v[140:143], v[202:205], v[56:59]
	v_mfma_f32_16x16x32_bf16 v[44:47], v[132:135], v[210:213], v[44:47]
	v_mfma_f32_16x16x32_bf16 v[40:43], v[140:143], v[210:213], v[40:43]
	v_mfma_f32_16x16x32_bf16 v[28:31], v[132:135], v[218:221], v[28:31]
	v_mfma_f32_16x16x32_bf16 v[24:27], v[140:143], v[218:221], v[24:27]
	v_mfma_f32_16x16x32_bf16 v[12:15], v[132:135], v[226:229], v[12:15]
	v_mfma_f32_16x16x32_bf16 v[8:11], v[140:143], v[226:229], v[8:11]
	v_mfma_f32_16x16x32_bf16 v[52:55], v[166:169], v[198:201], v[52:55]
	v_mfma_f32_16x16x32_bf16 v[48:51], v[190:193], v[198:201], v[48:51]
	v_mfma_f32_16x16x32_bf16 v[36:39], v[166:169], v[206:209], v[36:39]
	v_mfma_f32_16x16x32_bf16 v[32:35], v[190:193], v[206:209], v[32:35]
	v_mfma_f32_16x16x32_bf16 v[20:23], v[166:169], v[214:217], v[20:23]
	v_mfma_f32_16x16x32_bf16 v[16:19], v[190:193], v[214:217], v[16:19]
	v_mfma_f32_16x16x32_bf16 v[4:7], v[166:169], v[222:225], v[4:7]
	v_mfma_f32_16x16x32_bf16 v[0:3], v[190:193], v[222:225], v[0:3]
	v_mfma_f32_16x16x32_bf16 v[52:55], v[170:173], v[202:205], v[52:55]
	v_mfma_f32_16x16x32_bf16 v[48:51], v[194:197], v[202:205], v[48:51]
	v_mfma_f32_16x16x32_bf16 v[36:39], v[170:173], v[210:213], v[36:39]
	v_mfma_f32_16x16x32_bf16 v[32:35], v[194:197], v[210:213], v[32:35]
	v_mfma_f32_16x16x32_bf16 v[20:23], v[170:173], v[218:221], v[20:23]
	v_mfma_f32_16x16x32_bf16 v[16:19], v[194:197], v[218:221], v[16:19]
	v_mfma_f32_16x16x32_bf16 v[4:7], v[170:173], v[226:229], v[4:7]
	v_mfma_f32_16x16x32_bf16 v[0:3], v[194:197], v[226:229], v[0:3]
	s_setprio 0
	s_barrier
; #define PG8_STAGE(bufoff, gbase, voff) do { _Pragma("unroll") for (int _i = 0; _i < 2; ++_i) \
;         __builtin_amdgcn_global_load_lds((const unsigned*)((const char*)(gbase) + (voff)[_i]), (PG8_LAS unsigned*)(lds + (bufoff) + ldsw + _i * 8192), 16, 0, 0); } while (0)
; #define PG8_LDA(dst, b, h) do { _Pragma("unroll") for (int m = 0; m < 4; ++m) _Pragma("unroll") for (int k = 0; k < 2; ++k) dst[m][k] = *(const PG8_LAS bf16x8*)(lds + PG8_SA(b, h) + aoff + m * 2048 + k * 1024); } while (0)
; #define PG8_LDB(dst, b, h) do { _Pragma("unroll") for (int n = 0; n < 2; ++n) _Pragma("unroll") for (int k = 0; k < 2; ++k) dst[n][k] = *(const PG8_LAS bf16x8*)(lds + PG8_SB(b, h) + boff + n * 2048 + k * 1024); } while (0)
; #define PG8_MMA(ai, bj, At, Bt) do { __builtin_amdgcn_s_setprio(1); _Pragma("unroll") for (int m = 0; m < 4; ++m) _Pragma("unroll") for (int n = 0; n < 2; ++n) _Pragma("unroll") for (int k = 0; k < 2; ++k) \
;         acc[ai][bj][m][n] = __builtin_amdgcn_mfma_f32_16x16x32_bf16(Bt[n][k], At[m][k], acc[ai][bj][m][n], 0, 0, 0); __builtin_amdgcn_s_setprio(0); } while (0)
; #define PG8_WAIT_V(n) asm volatile("s_waitcnt vmcnt(" #n ")" ::: "memory")
; template <class Epi, class Sched, bool ALIGN_EPI = false, bool SP2 = false>
; __device__ __forceinline__ void gemm_phase(PG8_LAS unsigned char* lds, const Gemm g, const Sched& S, const Epi& E) {
;     ...
;             PG8_LDB(B0, 0, 0); PG8_LDB(B1, 0, 1); PG8_SCHED; PG8_LDA(At, 0, 0); PG8_STAGE(PG8_SA(1, 1), a1 + hstep, voffA);
;             PG8_WAIT_V(8); PG8_WAIT_L(0); PG8_BAR; PG8_MMA(0, 0, At, B0); PG8_MMA(0, 1, At, B1); PG8_BAR; PG8_SCHED;
;             PG8_LDA(At, 0, 1); PG8_STAGE(PG8_SB(0, 0), b2, voffB); PG8_STAGE(PG8_SB(0, 1), b2 + hstep, voffB); PG8_STAGE(PG8_SA(0, 0), a2, voffA);
;             PG8_WAIT_V(8); PG8_WAIT_L(0); PG8_BAR; PG8_MMA(1, 0, At, B0); PG8_MMA(1, 1, At, B1); PG8_BAR; PG8_SCHED;
;             PG8_LDB(B0, 1, 0); PG8_LDB(B1, 1, 1); PG8_SCHED; PG8_LDA(At, 1, 0); PG8_STAGE(PG8_SA(0, 1), a2 + hstep, voffA);
;             PG8_WAIT_V(8); PG8_WAIT_L(0); PG8_BAR; PG8_MMA(0, 0, At, B0); PG8_MMA(0, 1, At, B1); PG8_BAR; PG8_SCHED;
;             PG8_LDA(At, 1, 1); PG8_STAGE(PG8_SB(1, 0), b3, voffB); PG8_STAGE(PG8_SB(1, 1), b3 + hstep, voffB); PG8_STAGE(PG8_SA(1, 0), a3, voffA);
;             PG8_WAIT_V(8); PG8_WAIT_L(0); PG8_BAR; PG8_MMA(1, 0, At, B0); PG8_MMA(1, 1, At, B1); PG8_BAR; PG8_SCHED;
.Lmy_peel_96_mid:
	s_add_i32 s20, 0, 0x18000
	s_add_i32 s21, 0, 0x1c000
	v_add_u32_e32 v140, s20, v176
	v_add_u32_e32 v152, s21, v176
	ds_read_b128 v[128:131], v140
	ds_read_b128 v[132:135], v140 offset:1024
	ds_read_b128 v[136:139], v140 offset:2048
	ds_read_b128 v[140:143], v140 offset:3072
	ds_read_b128 v[166:169], v152
	ds_read_b128 v[170:173], v152 offset:1024
	ds_read_b128 v[190:193], v152 offset:2048
	ds_read_b128 v[194:197], v152 offset:3072
	s_add_u32 s36, s86, 0x40000
	s_addc_u32 s37, s87, 0
	s_mov_b32 m0, s95
	ds_read_b128 v[198:201], v181 offset:32768
	ds_read_b128 v[202:205], v181 offset:33792
	ds_read_b128 v[206:209], v181 offset:34816
	ds_read_b128 v[210:213], v181 offset:35840
	ds_read_b128 v[214:217], v181 offset:36864
	ds_read_b128 v[218:221], v181 offset:37888
	ds_read_b128 v[222:225], v181 offset:38912
	ds_read_b128 v[226:229], v181 offset:39936
	global_load_lds_dwordx4 v150, s[36:37]
	s_mov_b32 m0, s97
	s_nop 0
	global_load_lds_dwordx4 v146, s[36:37]
	s_waitcnt vmcnt(8)
	s_waitcnt lgkmcnt(0)
	s_barrier
	s_setprio 1
	v_mfma_f32_16x16x32_bf16 v[124:127], v[128:131], v[198:201], v[124:127]
	v_mfma_f32_16x16x32_bf16 v[120:123], v[136:139], v[198:201], v[120:123]
	v_mfma_f32_16x16x32_bf16 v[108:111], v[128:131], v[206:209], v[108:111]
	v_mfma_f32_16x16x32_bf16 v[104:107], v[136:139], v[206:209], v[104:107]
	v_mfma_f32_16x16x32_bf16 v[92:95], v[128:131], v[214:217], v[92:95]
	v_mfma_f32_16x16x32_bf16 v[88:91], v[136:139], v[214:217], v[88:91]
	v_mfma_f32_16x16x32_bf16 v[76:79], v[128:131], v[222:225], v[76:79]
	v_mfma_f32_16x16x32_bf16 v[72:75], v[136:139], v[222:225], v[72:75]
	v_mfma_f32_16x16x32_bf16 v[124:127], v[132:135], v[202:205], v[124:127]
	v_mfma_f32_16x16x32_bf16 v[120:123], v[140:143], v[202:205], v[120:123]
	v_mfma_f32_16x16x32_bf16 v[108:111], v[132:135], v[210:213], v[108:111]
	v_mfma_f32_16x16x32_bf16 v[104:107], v[140:143], v[210:213], v[104:107]
	v_mfma_f32_16x16x32_bf16 v[92:95], v[132:135], v[218:221], v[92:95]
	v_mfma_f32_16x16x32_bf16 v[88:91], v[140:143], v[218:221], v[88:91]
	v_mfma_f32_16x16x32_bf16 v[76:79], v[132:135], v[226:229], v[76:79]
	v_mfma_f32_16x16x32_bf16 v[72:75], v[140:143], v[226:229], v[72:75]
	v_mfma_f32_16x16x32_bf16 v[116:119], v[166:169], v[198:201], v[116:119]
	v_mfma_f32_16x16x32_bf16 v[112:115], v[190:193], v[198:201], v[112:115]
	v_mfma_f32_16x16x32_bf16 v[100:103], v[166:169], v[206:209], v[100:103]
	v_mfma_f32_16x16x32_bf16 v[96:99], v[190:193], v[206:209], v[96:99]
	v_mfma_f32_16x16x32_bf16 v[84:87], v[166:169], v[214:217], v[84:87]
	v_mfma_f32_16x16x32_bf16 v[80:83], v[190:193], v[214:217], v[80:83]
	v_mfma_f32_16x16x32_bf16 v[68:71], v[166:169], v[222:225], v[68:71]
	v_mfma_f32_16x16x32_bf16 v[64:67], v[190:193], v[222:225], v[64:67]
	v_mfma_f32_16x16x32_bf16 v[116:119], v[170:173], v[202:205], v[116:119]
	v_mfma_f32_16x16x32_bf16 v[112:115], v[194:197], v[202:205], v[112:115]
	v_mfma_f32_16x16x32_bf16 v[100:103], v[170:173], v[210:213], v[100:103]
	v_mfma_f32_16x16x32_bf16 v[96:99], v[194:197], v[210:213], v[96:99]
	v_mfma_f32_16x16x32_bf16 v[84:87], v[170:173], v[218:221], v[84:87]
	v_mfma_f32_16x16x32_bf16 v[80:83], v[194:197], v[218:221], v[80:83]
	v_mfma_f32_16x16x32_bf16 v[68:71], v[170:173], v[226:229], v[68:71]
	v_mfma_f32_16x16x32_bf16 v[64:67], v[194:197], v[226:229], v[64:67]
	s_setprio 0
	s_barrier
	s_add_i32 s20, s20, s90
	s_mov_b32 m0, s20
	s_nop 0
	global_load_lds_dwordx4 v148, s[98:99]
	s_add_i32 m0, s20, 0x2000
	s_add_u32 s36, s82, 0x40080
	s_addc_u32 s37, s83, 0
	s_add_i32 s20, s21, s90
	global_load_lds_dwordx4 v144, s[98:99]
	s_mov_b32 m0, s20
	s_nop 0
	global_load_lds_dwordx4 v148, s[36:37]
	s_add_i32 m0, s20, 0x2000
	s_nop 0
	global_load_lds_dwordx4 v144, s[36:37]
	s_mov_b32 m0, s42
	s_nop 0
	global_load_lds_dwordx4 v150, s[100:101]
	s_mov_b32 m0, s43
	s_nop 0
	global_load_lds_dwordx4 v146, s[100:101]
	ds_read_b128 v[198:201], v181 offset:49152
	ds_read_b128 v[202:205], v181 offset:50176
	ds_read_b128 v[206:209], v181 offset:51200
	ds_read_b128 v[210:213], v181 offset:52224
	ds_read_b128 v[214:217], v181 offset:53248
	ds_read_b128 v[218:221], v181 offset:54272
	ds_read_b128 v[222:225], v181 offset:55296
	ds_read_b128 v[226:229], v181 offset:56320
	s_waitcnt vmcnt(8)
	s_waitcnt lgkmcnt(0)
	s_barrier
	s_setprio 1
	v_mfma_f32_16x16x32_bf16 v[60:63], v[128:131], v[198:201], v[60:63]
	v_mfma_f32_16x16x32_bf16 v[56:59], v[136:139], v[198:201], v[56:59]
	v_mfma_f32_16x16x32_bf16 v[44:47], v[128:131], v[206:209], v[44:47]
	v_mfma_f32_16x16x32_bf16 v[40:43], v[136:139], v[206:209], v[40:43]
	v_mfma_f32_16x16x32_bf16 v[28:31], v[128:131], v[214:217], v[28:31]
	v_mfma_f32_16x16x32_bf16 v[24:27], v[136:139], v[214:217], v[24:27]
	v_mfma_f32_16x16x32_bf16 v[12:15], v[128:131], v[222:225], v[12:15]
	v_mfma_f32_16x16x32_bf16 v[8:11], v[136:139], v[222:225], v[8:11]
	v_mfma_f32_16x16x32_bf16 v[60:63], v[132:135], v[202:205], v[60:63]
	v_mfma_f32_16x16x32_bf16 v[56:59], v[140:143], v[202:205], v[56:59]
	v_mfma_f32_16x16x32_bf16 v[44:47], v[132:135], v[210:213], v[44:47]
	v_mfma_f32_16x16x32_bf16 v[40:43], v[140:143], v[210:213], v[40:43]
	v_mfma_f32_16x16x32_bf16 v[28:31], v[132:135], v[218:221], v[28:31]
	v_mfma_f32_16x16x32_bf16 v[24:27], v[140:143], v[218:221], v[24:27]
	v_mfma_f32_16x16x32_bf16 v[12:15], v[132:135], v[226:229], v[12:15]
	v_mfma_f32_16x16x32_bf16 v[8:11], v[140:143], v[226:229], v[8:11]
	v_mfma_f32_16x16x32_bf16 v[52:55], v[166:169], v[198:201], v[52:55]
	v_mfma_f32_16x16x32_bf16 v[48:51], v[190:193], v[198:201], v[48:51]
	v_mfma_f32_16x16x32_bf16 v[36:39], v[166:169], v[206:209], v[36:39]
	v_mfma_f32_16x16x32_bf16 v[32:35], v[190:193], v[206:209], v[32:35]
	v_mfma_f32_16x16x32_bf16 v[20:23], v[166:169], v[214:217], v[20:23]
	v_mfma_f32_16x16x32_bf16 v[16:19], v[190:193], v[214:217], v[16:19]
	v_mfma_f32_16x16x32_bf16 v[4:7], v[166:169], v[222:225], v[4:7]
	v_mfma_f32_16x16x32_bf16 v[0:3], v[190:193], v[222:225], v[0:3]
	v_mfma_f32_16x16x32_bf16 v[52:55], v[170:173], v[202:205], v[52:55]
	v_mfma_f32_16x16x32_bf16 v[48:51], v[194:197], v[202:205], v[48:51]
	v_mfma_f32_16x16x32_bf16 v[36:39], v[170:173], v[210:213], v[36:39]
	v_mfma_f32_16x16x32_bf16 v[32:35], v[194:197], v[210:213], v[32:35]
	v_mfma_f32_16x16x32_bf16 v[20:23], v[170:173], v[218:221], v[20:23]
	v_mfma_f32_16x16x32_bf16 v[16:19], v[194:197], v[218:221], v[16:19]
	v_mfma_f32_16x16x32_bf16 v[4:7], v[170:173], v[226:229], v[4:7]
	v_mfma_f32_16x16x32_bf16 v[0:3], v[194:197], v[226:229], v[0:3]
	s_setprio 0
	s_barrier
	s_add_i32 s35, s35, 2
	s_add_u32 s80, s80, 0x100
	s_addc_u32 s81, s81, 0
	s_add_u32 vcc_hi, vcc_hi, 0x100
	s_addc_u32 s34, s34, 0
	s_cmp_gt_u32 s35, 13
	s_cbranch_scc0 .LBB0_96
	s_and_b64 vcc, exec, s[28:29]
	s_cbranch_vccz .LBB0_99
	s_barrier

;     __host__ __device__ bool next(int i, Unit& u) const { const long L = (long)i * G + c; if (L >= nwg) return false; return unit_of((int)L, u); }
;     __host__ __device__ bool next(int i, Unit& u) const { const int L = i == 0 ? l0 : (i == 1 ? l1 : (i == 2 ? l2 : -1)); if (L < 0 || L >= s.nwg) return false; return s.unit_of(L, u); }
;     __host__ __device__ bool next(int i, Unit& u) const { const bool ok = s.next(i >> 1, u); u.kh = i & 1; return ok; }
; template <class Epi, class Sched, bool ALIGN_EPI = false, bool SP2 = false>
; __device__ __forceinline__ void gemm_phase(PG8_LAS unsigned char* lds, const Gemm g, const Sched& S, const Epi& E) {
;     ...
;         const bool has_next = S.next(ui + 1, nxt);
;         const char* nA = has_next ? (const char*)g.A + (size_t)nxt.pm * tstep + nxt.kh * khb : cA; const char* nB = has_next ? (const char*)g.Bt + (size_t)nxt.pn * tstep + nxt.kh * khb : cB;
;         for (int t = 0; t < nt; t += 2) {
;             const bool last = (t == nt - 2);
;             const char* a1 = cA + (size_t)(t + 1) * kstep;
;             const char* a2 = last ? nA : cA + (size_t)(t + 2) * kstep; const char* b2 = last ? nB : cB + (size_t)(t + 2) * kstep;
;             const char* a3 = a2 + kstep; const char* b3 = b2 + kstep;
;             if (last && has_next) S.a_ready(nxt);
;             if constexpr (SP2) {
;             PG8_LDB(B0, 0, 0); PG8_LDB(B1, 0, 1); PG8_SCHED; PG8_LDA(At, 0, 0); PG8_STAGE(PG8_SA(1, 1), a1 + hstep, voffA);
;             PG8_WAIT_V(8); PG8_WAIT_L(0); PG8_BAR; PG8_MMA(0, 0, At, B0); PG8_MMA(0, 1, At, B1); PG8_BAR; PG8_SCHED;
;             PG8_LDA(At, 0, 1); PG8_STAGE(PG8_SB(0, 0), b2, voffB); PG8_STAGE(PG8_SB(0, 1), b2 + hstep, voffB); PG8_STAGE(PG8_SA(0, 0), a2, voffA);
;             PG8_WAIT_V(8); PG8_WAIT_L(0); PG8_BAR; PG8_MMA(1, 0, At, B0); PG8_MMA(1, 1, At, B1); PG8_BAR; PG8_SCHED;
;             PG8_LDB(B0, 1, 0); PG8_LDB(B1, 1, 1); PG8_SCHED; PG8_LDA(At, 1, 0); PG8_STAGE(PG8_SA(0, 1), a2 + hstep, voffA);
;             PG8_WAIT_V(8); PG8_WAIT_L(0); PG8_BAR; PG8_MMA(0, 0, At, B0); PG8_MMA(0, 1, At, B1); PG8_BAR; PG8_SCHED;
;             PG8_LDA(At, 1, 1); PG8_STAGE(PG8_SB(1, 0), b3, voffB); PG8_STAGE(PG8_SB(1, 1), b3 + hstep, voffB); PG8_STAGE(PG8_SA(1, 0), a3, voffA);
;             PG8_WAIT_V(8); PG8_WAIT_L(0); PG8_BAR; PG8_MMA(1, 0, At, B0); PG8_MMA(1, 1, At, B1); PG8_BAR; PG8_SCHED;
.LBB0_149:
	s_ashr_i32 s17, s16, 31
	s_lshl_b64 s[18:19], s[16:17], 19
	s_add_u32 s18, s29, s18
	s_addc_u32 s19, s30, s19
	s_and_b64 s[20:21], s[2:3], exec
	s_cselect_b32 s17, s19, s23
	s_cselect_b32 s45, s18, s22
	s_ashr_i32 s15, s14, 31
	s_lshl_b64 s[20:21], s[14:15], 19
	s_add_u32 s20, s50, s20
	s_addc_u32 s21, s51, s21
	s_and_b64 s[26:27], s[2:3], exec
	s_cselect_b32 s15, s21, s25
	s_cselect_b32 s46, s20, s24
	s_add_u32 s22, s22, 0x40080
	s_addc_u32 s23, s23, 0
	s_add_u32 s47, s24, 0x100
	s_addc_u32 s48, s25, 0
	s_mov_b32 s49, -2
	s_add_u32 s24, s22, 0xfffc0080
	s_addc_u32 s25, s23, -1
	s_waitcnt lgkmcnt(0)
	s_add_i32 s54, 0, 0x10000
	v_add_u32_e32 v147, s54, v152
	ds_read_b128 v[156:159], v147
	ds_read_b128 v[160:163], v147 offset:1024
	ds_read_b128 v[164:167], v147 offset:2048
	ds_read_b128 v[168:171], v147 offset:3072
	ds_read_b128 v[172:175], v154
	ds_read_b128 v[176:179], v154 offset:1024
	ds_read_b128 v[182:185], v154 offset:2048
	ds_read_b128 v[190:193], v154 offset:3072
	s_cmp_eq_u32 s49, 12
	s_cselect_b32 s27, s17, s25
	s_cselect_b32 s26, s45, s24
	s_cselect_b32 s25, s15, s48
	s_cselect_b32 s24, s46, s47
	s_add_i32 m0, s13, 0xc000
	ds_read_b128 v[194:197], v155
	ds_read_b128 v[198:201], v155 offset:1024
	ds_read_b128 v[202:205], v155 offset:2048
	ds_read_b128 v[206:209], v155 offset:3072
	ds_read_b128 v[210:213], v155 offset:4096
	ds_read_b128 v[214:217], v155 offset:5120
	ds_read_b128 v[218:221], v155 offset:6144
	ds_read_b128 v[222:225], v155 offset:7168
	global_load_lds_dwordx4 v138, s[22:23]
	s_add_i32 m0, s13, 0xe000
	s_nop 0
	global_load_lds_dwordx4 v140, s[22:23]
	s_waitcnt vmcnt(8)
	s_waitcnt lgkmcnt(0)
	s_barrier
	s_setprio 1
	v_mfma_f32_16x16x32_bf16 v[124:127], v[156:159], v[194:197], 0
	v_mfma_f32_16x16x32_bf16 v[120:123], v[164:167], v[194:197], 0
	v_mfma_f32_16x16x32_bf16 v[116:119], v[156:159], v[202:205], 0
	v_mfma_f32_16x16x32_bf16 v[112:115], v[164:167], v[202:205], 0
	v_mfma_f32_16x16x32_bf16 v[100:103], v[156:159], v[210:213], 0
	v_mfma_f32_16x16x32_bf16 v[96:99], v[164:167], v[210:213], 0
	v_mfma_f32_16x16x32_bf16 v[84:87], v[156:159], v[218:221], 0
	v_mfma_f32_16x16x32_bf16 v[80:83], v[164:167], v[218:221], 0
	v_mfma_f32_16x16x32_bf16 v[124:127], v[160:163], v[198:201], v[124:127]
	v_mfma_f32_16x16x32_bf16 v[120:123], v[168:171], v[198:201], v[120:123]
	v_mfma_f32_16x16x32_bf16 v[116:119], v[160:163], v[206:209], v[116:119]
	v_mfma_f32_16x16x32_bf16 v[112:115], v[168:171], v[206:209], v[112:115]
	v_mfma_f32_16x16x32_bf16 v[100:103], v[160:163], v[214:217], v[100:103]
	v_mfma_f32_16x16x32_bf16 v[96:99], v[168:171], v[214:217], v[96:99]
	v_mfma_f32_16x16x32_bf16 v[84:87], v[160:163], v[222:225], v[84:87]
	v_mfma_f32_16x16x32_bf16 v[80:83], v[168:171], v[222:225], v[80:83]
	v_mfma_f32_16x16x32_bf16 v[108:111], v[172:175], v[194:197], 0
	v_mfma_f32_16x16x32_bf16 v[104:107], v[182:185], v[194:197], 0
	v_mfma_f32_16x16x32_bf16 v[92:95], v[172:175], v[202:205], 0
	v_mfma_f32_16x16x32_bf16 v[88:91], v[182:185], v[202:205], 0
	v_mfma_f32_16x16x32_bf16 v[76:79], v[172:175], v[210:213], 0
	v_mfma_f32_16x16x32_bf16 v[72:75], v[182:185], v[210:213], 0
	v_mfma_f32_16x16x32_bf16 v[68:71], v[172:175], v[218:221], 0
	v_mfma_f32_16x16x32_bf16 v[64:67], v[182:185], v[218:221], 0
	v_mfma_f32_16x16x32_bf16 v[108:111], v[176:179], v[198:201], v[108:111]
	v_mfma_f32_16x16x32_bf16 v[104:107], v[190:193], v[198:201], v[104:107]
	v_mfma_f32_16x16x32_bf16 v[92:95], v[176:179], v[206:209], v[92:95]
	v_mfma_f32_16x16x32_bf16 v[88:91], v[190:193], v[206:209], v[88:91]
	v_mfma_f32_16x16x32_bf16 v[76:79], v[176:179], v[214:217], v[76:79]
	v_mfma_f32_16x16x32_bf16 v[72:75], v[190:193], v[214:217], v[72:75]
	v_mfma_f32_16x16x32_bf16 v[68:71], v[176:179], v[222:225], v[68:71]
	v_mfma_f32_16x16x32_bf16 v[64:67], v[190:193], v[222:225], v[64:67]
	s_setprio 0
	s_barrier
	s_add_u32 s98, s24, s8
	s_addc_u32 s99, s25, s9
	s_add_u32 s100, s26, s8
	s_addc_u32 s101, s27, s9
	s_add_i32 s54, s54, s31
	s_mov_b32 m0, s54
	s_nop 0
	global_load_lds_dwordx4 v130, s[24:25]
	s_add_i32 m0, s54, 0x2000
	s_add_u32 s54, s24, 0x40000
	s_addc_u32 s55, s25, 0
	s_add_i32 s76, s43, s31
	global_load_lds_dwordx4 v134, s[24:25]
	s_mov_b32 m0, s76
	s_nop 0
	global_load_lds_dwordx4 v130, s[54:55]
	s_add_i32 m0, s76, 0x2000
	s_nop 0
	global_load_lds_dwordx4 v134, s[54:55]
	s_mov_b32 m0, s13
	s_nop 0
	global_load_lds_dwordx4 v128, s[26:27]
	s_mov_b32 m0, s34
	s_nop 0
	global_load_lds_dwordx4 v132, s[26:27]
	ds_read_b128 v[194:197], v155 offset:16384
	ds_read_b128 v[198:201], v155 offset:17408
	ds_read_b128 v[202:205], v155 offset:18432
	ds_read_b128 v[206:209], v155 offset:19456
	ds_read_b128 v[210:213], v155 offset:20480
	ds_read_b128 v[214:217], v155 offset:21504
	ds_read_b128 v[218:221], v155 offset:22528
	ds_read_b128 v[222:225], v155 offset:23552
	s_waitcnt vmcnt(8)
	s_waitcnt lgkmcnt(0)
	s_barrier
	s_setprio 1
	v_mfma_f32_16x16x32_bf16 v[60:63], v[156:159], v[194:197], 0
	v_mfma_f32_16x16x32_bf16 v[56:59], v[164:167], v[194:197], 0
	v_mfma_f32_16x16x32_bf16 v[52:55], v[156:159], v[202:205], 0
	v_mfma_f32_16x16x32_bf16 v[48:51], v[164:167], v[202:205], 0
	v_mfma_f32_16x16x32_bf16 v[36:39], v[156:159], v[210:213], 0
	v_mfma_f32_16x16x32_bf16 v[32:35], v[164:167], v[210:213], 0
	v_mfma_f32_16x16x32_bf16 v[20:23], v[156:159], v[218:221], 0
	v_mfma_f32_16x16x32_bf16 v[16:19], v[164:167], v[218:221], 0
	v_mfma_f32_16x16x32_bf16 v[60:63], v[160:163], v[198:201], v[60:63]
	v_mfma_f32_16x16x32_bf16 v[56:59], v[168:171], v[198:201], v[56:59]
	v_mfma_f32_16x16x32_bf16 v[52:55], v[160:163], v[206:209], v[52:55]
	v_mfma_f32_16x16x32_bf16 v[48:51], v[168:171], v[206:209], v[48:51]
	v_mfma_f32_16x16x32_bf16 v[36:39], v[160:163], v[214:217], v[36:39]
	v_mfma_f32_16x16x32_bf16 v[32:35], v[168:171], v[214:217], v[32:35]
	v_mfma_f32_16x16x32_bf16 v[20:23], v[160:163], v[222:225], v[20:23]
	v_mfma_f32_16x16x32_bf16 v[16:19], v[168:171], v[222:225], v[16:19]
	v_mfma_f32_16x16x32_bf16 v[44:47], v[172:175], v[194:197], 0
	v_mfma_f32_16x16x32_bf16 v[40:43], v[182:185], v[194:197], 0
	v_mfma_f32_16x16x32_bf16 v[28:31], v[172:175], v[202:205], 0
	v_mfma_f32_16x16x32_bf16 v[24:27], v[182:185], v[202:205], 0
	v_mfma_f32_16x16x32_bf16 v[12:15], v[172:175], v[210:213], 0
	v_mfma_f32_16x16x32_bf16 v[8:11], v[182:185], v[210:213], 0
	v_mfma_f32_16x16x32_bf16 v[4:7], v[172:175], v[218:221], 0
	v_mfma_f32_16x16x32_bf16 v[0:3], v[182:185], v[218:221], 0
	v_mfma_f32_16x16x32_bf16 v[44:47], v[176:179], v[198:201], v[44:47]
	v_mfma_f32_16x16x32_bf16 v[40:43], v[190:193], v[198:201], v[40:43]
	v_mfma_f32_16x16x32_bf16 v[28:31], v[176:179], v[206:209], v[28:31]
	v_mfma_f32_16x16x32_bf16 v[24:27], v[190:193], v[206:209], v[24:27]
	v_mfma_f32_16x16x32_bf16 v[12:15], v[176:179], v[214:217], v[12:15]
	v_mfma_f32_16x16x32_bf16 v[8:11], v[190:193], v[214:217], v[8:11]
	v_mfma_f32_16x16x32_bf16 v[4:7], v[176:179], v[222:225], v[4:7]
	v_mfma_f32_16x16x32_bf16 v[0:3], v[190:193], v[222:225], v[0:3]
	s_setprio 0
	s_barrier
	s_branch .Lmy_peel_150_mid
; #define PG8_STAGE(bufoff, gbase, voff) do { _Pragma("unroll") for (int _i = 0; _i < 2; ++_i) \
;         __builtin_amdgcn_global_load_lds((const unsigned*)((const char*)(gbase) + (voff)[_i]), (PG8_LAS unsigned*)(lds + (bufoff) + ldsw + _i * 8192), 16, 0, 0); } while (0)
; #define PG8_LDA(dst, b, h) do { _Pragma("unroll") for (int m = 0; m < 4; ++m) _Pragma("unroll") for (int k = 0; k < 2; ++k) dst[m][k] = *(const PG8_LAS bf16x8*)(lds + PG8_SA(b, h) + aoff + m * 2048 + k * 1024); } while (0)
; #define PG8_LDB(dst, b, h) do { _Pragma("unroll") for (int n = 0; n < 2; ++n) _Pragma("unroll") for (int k = 0; k < 2; ++k) dst[n][k] = *(const PG8_LAS bf16x8*)(lds + PG8_SB(b, h) + boff + n * 2048 + k * 1024); } while (0)
; #define PG8_MMA(ai, bj, At, Bt) do { __builtin_amdgcn_s_setprio(1); _Pragma("unroll") for (int m = 0; m < 4; ++m) _Pragma("unroll") for (int n = 0; n < 2; ++n) _Pragma("unroll") for (int k = 0; k < 2; ++k) \
;         acc[ai][bj][m][n] = __builtin_amdgcn_mfma_f32_16x16x32_bf16(Bt[n][k], At[m][k], acc[ai][bj][m][n], 0, 0, 0); __builtin_amdgcn_s_setprio(0); } while (0)
; #define PG8_WAIT_V(n) asm volatile("s_waitcnt vmcnt(" #n ")" ::: "memory")
; template <class Epi, class Sched, bool ALIGN_EPI = false, bool SP2 = false>
; __device__ __forceinline__ void gemm_phase(PG8_LAS unsigned char* lds, const Gemm g, const Sched& S, const Epi& E) {
;     ...
;             PG8_LDB(B0, 0, 0); PG8_LDB(B1, 0, 1); PG8_SCHED; PG8_LDA(At, 0, 0); PG8_STAGE(PG8_SA(1, 1), a1 + hstep, voffA);
;             PG8_WAIT_V(8); PG8_WAIT_L(0); PG8_BAR; PG8_MMA(0, 0, At, B0); PG8_MMA(0, 1, At, B1); PG8_BAR; PG8_SCHED;
;             PG8_LDA(At, 0, 1); PG8_STAGE(PG8_SB(0, 0), b2, voffB); PG8_STAGE(PG8_SB(0, 1), b2 + hstep, voffB); PG8_STAGE(PG8_SA(0, 0), a2, voffA);
;             PG8_WAIT_V(8); PG8_WAIT_L(0); PG8_BAR; PG8_MMA(1, 0, At, B0); PG8_MMA(1, 1, At, B1); PG8_BAR; PG8_SCHED;
;             PG8_LDB(B0, 1, 0); PG8_LDB(B1, 1, 1); PG8_SCHED; PG8_LDA(At, 1, 0); PG8_STAGE(PG8_SA(0, 1), a2 + hstep, voffA);
;             PG8_WAIT_V(8); PG8_WAIT_L(0); PG8_BAR; PG8_MMA(0, 0, At, B0); PG8_MMA(0, 1, At, B1); PG8_BAR; PG8_SCHED;
;             PG8_LDA(At, 1, 1); PG8_STAGE(PG8_SB(1, 0), b3, voffB); PG8_STAGE(PG8_SB(1, 1), b3 + hstep, voffB); PG8_STAGE(PG8_SA(1, 0), a3, voffA);
;             PG8_WAIT_V(8); PG8_WAIT_L(0); PG8_BAR; PG8_MMA(1, 0, At, B0); PG8_MMA(1, 1, At, B1); PG8_BAR; PG8_SCHED;
.LBB0_150:
	s_add_u32 s24, s22, 0xfffc0080
	s_addc_u32 s25, s23, -1
	s_waitcnt lgkmcnt(0)
	s_add_i32 s54, 0, 0x10000
	v_add_u32_e32 v147, s54, v152
	ds_read_b128 v[156:159], v147
	ds_read_b128 v[160:163], v147 offset:1024
	ds_read_b128 v[164:167], v147 offset:2048
	ds_read_b128 v[168:171], v147 offset:3072
	ds_read_b128 v[172:175], v154
	ds_read_b128 v[176:179], v154 offset:1024
	ds_read_b128 v[182:185], v154 offset:2048
	ds_read_b128 v[190:193], v154 offset:3072
	s_cmp_eq_u32 s49, 12
	s_cselect_b32 s27, s17, s25
	s_cselect_b32 s26, s45, s24
	s_cselect_b32 s25, s15, s48
	s_cselect_b32 s24, s46, s47
	s_add_i32 m0, s13, 0xc000
	ds_read_b128 v[194:197], v155
	ds_read_b128 v[198:201], v155 offset:1024
	ds_read_b128 v[202:205], v155 offset:2048
	ds_read_b128 v[206:209], v155 offset:3072
	ds_read_b128 v[210:213], v155 offset:4096
	ds_read_b128 v[214:217], v155 offset:5120
	ds_read_b128 v[218:221], v155 offset:6144
	ds_read_b128 v[222:225], v155 offset:7168
	global_load_lds_dwordx4 v138, s[22:23]
	s_add_i32 m0, s13, 0xe000
	s_nop 0
	global_load_lds_dwordx4 v140, s[22:23]
	s_waitcnt vmcnt(8)
	s_waitcnt lgkmcnt(0)
	s_barrier
	s_setprio 1
	v_mfma_f32_16x16x32_bf16 v[124:127], v[156:159], v[194:197], v[124:127]
	v_mfma_f32_16x16x32_bf16 v[120:123], v[164:167], v[194:197], v[120:123]
	v_mfma_f32_16x16x32_bf16 v[116:119], v[156:159], v[202:205], v[116:119]
	v_mfma_f32_16x16x32_bf16 v[112:115], v[164:167], v[202:205], v[112:115]
	v_mfma_f32_16x16x32_bf16 v[100:103], v[156:159], v[210:213], v[100:103]
	v_mfma_f32_16x16x32_bf16 v[96:99], v[164:167], v[210:213], v[96:99]
	v_mfma_f32_16x16x32_bf16 v[84:87], v[156:159], v[218:221], v[84:87]
	v_mfma_f32_16x16x32_bf16 v[80:83], v[164:167], v[218:221], v[80:83]
	v_mfma_f32_16x16x32_bf16 v[124:127], v[160:163], v[198:201], v[124:127]
	v_mfma_f32_16x16x32_bf16 v[120:123], v[168:171], v[198:201], v[120:123]
	v_mfma_f32_16x16x32_bf16 v[116:119], v[160:163], v[206:209], v[116:119]
	v_mfma_f32_16x16x32_bf16 v[112:115], v[168:171], v[206:209], v[112:115]
	v_mfma_f32_16x16x32_bf16 v[100:103], v[160:163], v[214:217], v[100:103]
	v_mfma_f32_16x16x32_bf16 v[96:99], v[168:171], v[214:217], v[96:99]
	v_mfma_f32_16x16x32_bf16 v[84:87], v[160:163], v[222:225], v[84:87]
	v_mfma_f32_16x16x32_bf16 v[80:83], v[168:171], v[222:225], v[80:83]
	v_mfma_f32_16x16x32_bf16 v[108:111], v[172:175], v[194:197], v[108:111]
	v_mfma_f32_16x16x32_bf16 v[104:107], v[182:185], v[194:197], v[104:107]
	v_mfma_f32_16x16x32_bf16 v[92:95], v[172:175], v[202:205], v[92:95]
	v_mfma_f32_16x16x32_bf16 v[88:91], v[182:185], v[202:205], v[88:91]
	v_mfma_f32_16x16x32_bf16 v[76:79], v[172:175], v[210:213], v[76:79]
	v_mfma_f32_16x16x32_bf16 v[72:75], v[182:185], v[210:213], v[72:75]
	v_mfma_f32_16x16x32_bf16 v[68:71], v[172:175], v[218:221], v[68:71]
	v_mfma_f32_16x16x32_bf16 v[64:67], v[182:185], v[218:221], v[64:67]
	v_mfma_f32_16x16x32_bf16 v[108:111], v[176:179], v[198:201], v[108:111]
	v_mfma_f32_16x16x32_bf16 v[104:107], v[190:193], v[198:201], v[104:107]
	v_mfma_f32_16x16x32_bf16 v[92:95], v[176:179], v[206:209], v[92:95]
	v_mfma_f32_16x16x32_bf16 v[88:91], v[190:193], v[206:209], v[88:91]
	v_mfma_f32_16x16x32_bf16 v[76:79], v[176:179], v[214:217], v[76:79]
	v_mfma_f32_16x16x32_bf16 v[72:75], v[190:193], v[214:217], v[72:75]
	v_mfma_f32_16x16x32_bf16 v[68:71], v[176:179], v[222:225], v[68:71]
	v_mfma_f32_16x16x32_bf16 v[64:67], v[190:193], v[222:225], v[64:67]
	s_setprio 0
	s_barrier
	s_add_u32 s98, s24, s8
	s_addc_u32 s99, s25, s9
	s_add_u32 s100, s26, s8
	s_addc_u32 s101, s27, s9
	s_add_i32 s54, s54, s31
	s_mov_b32 m0, s54
	s_nop 0
	global_load_lds_dwordx4 v130, s[24:25]
	s_add_i32 m0, s54, 0x2000
	s_add_u32 s54, s24, 0x40000
	s_addc_u32 s55, s25, 0
	s_add_i32 s76, s43, s31
	global_load_lds_dwordx4 v134, s[24:25]
	s_mov_b32 m0, s76
	s_nop 0
	global_load_lds_dwordx4 v130, s[54:55]
	s_add_i32 m0, s76, 0x2000
	s_nop 0
	global_load_lds_dwordx4 v134, s[54:55]
	s_mov_b32 m0, s13
	s_nop 0
	global_load_lds_dwordx4 v128, s[26:27]
	s_mov_b32 m0, s34
	s_nop 0
	global_load_lds_dwordx4 v132, s[26:27]
	ds_read_b128 v[194:197], v155 offset:16384
	ds_read_b128 v[198:201], v155 offset:17408
	ds_read_b128 v[202:205], v155 offset:18432
	ds_read_b128 v[206:209], v155 offset:19456
	ds_read_b128 v[210:213], v155 offset:20480
	ds_read_b128 v[214:217], v155 offset:21504
	ds_read_b128 v[218:221], v155 offset:22528
	ds_read_b128 v[222:225], v155 offset:23552
	s_waitcnt vmcnt(8)
	s_waitcnt lgkmcnt(0)
	s_barrier
	s_setprio 1
	v_mfma_f32_16x16x32_bf16 v[60:63], v[156:159], v[194:197], v[60:63]
	v_mfma_f32_16x16x32_bf16 v[56:59], v[164:167], v[194:197], v[56:59]
	v_mfma_f32_16x16x32_bf16 v[52:55], v[156:159], v[202:205], v[52:55]
	v_mfma_f32_16x16x32_bf16 v[48:51], v[164:167], v[202:205], v[48:51]
	v_mfma_f32_16x16x32_bf16 v[36:39], v[156:159], v[210:213], v[36:39]
	v_mfma_f32_16x16x32_bf16 v[32:35], v[164:167], v[210:213], v[32:35]
	v_mfma_f32_16x16x32_bf16 v[20:23], v[156:159], v[218:221], v[20:23]
	v_mfma_f32_16x16x32_bf16 v[16:19], v[164:167], v[218:221], v[16:19]
	v_mfma_f32_16x16x32_bf16 v[60:63], v[160:163], v[198:201], v[60:63]
	v_mfma_f32_16x16x32_bf16 v[56:59], v[168:171], v[198:201], v[56:59]
	v_mfma_f32_16x16x32_bf16 v[52:55], v[160:163], v[206:209], v[52:55]
	v_mfma_f32_16x16x32_bf16 v[48:51], v[168:171], v[206:209], v[48:51]
	v_mfma_f32_16x16x32_bf16 v[36:39], v[160:163], v[214:217], v[36:39]
	v_mfma_f32_16x16x32_bf16 v[32:35], v[168:171], v[214:217], v[32:35]
	v_mfma_f32_16x16x32_bf16 v[20:23], v[160:163], v[222:225], v[20:23]
	v_mfma_f32_16x16x32_bf16 v[16:19], v[168:171], v[222:225], v[16:19]
	v_mfma_f32_16x16x32_bf16 v[44:47], v[172:175], v[194:197], v[44:47]
	v_mfma_f32_16x16x32_bf16 v[40:43], v[182:185], v[194:197], v[40:43]
	v_mfma_f32_16x16x32_bf16 v[28:31], v[172:175], v[202:205], v[28:31]
	v_mfma_f32_16x16x32_bf16 v[24:27], v[182:185], v[202:205], v[24:27]
	v_mfma_f32_16x16x32_bf16 v[12:15], v[172:175], v[210:213], v[12:15]
	v_mfma_f32_16x16x32_bf16 v[8:11], v[182:185], v[210:213], v[8:11]
	v_mfma_f32_16x16x32_bf16 v[4:7], v[172:175], v[218:221], v[4:7]
	v_mfma_f32_16x16x32_bf16 v[0:3], v[182:185], v[218:221], v[0:3]
	v_mfma_f32_16x16x32_bf16 v[44:47], v[176:179], v[198:201], v[44:47]
	v_mfma_f32_16x16x32_bf16 v[40:43], v[190:193], v[198:201], v[40:43]
	v_mfma_f32_16x16x32_bf16 v[28:31], v[176:179], v[206:209], v[28:31]
	v_mfma_f32_16x16x32_bf16 v[24:27], v[190:193], v[206:209], v[24:27]
	v_mfma_f32_16x16x32_bf16 v[12:15], v[176:179], v[214:217], v[12:15]
	v_mfma_f32_16x16x32_bf16 v[8:11], v[190:193], v[214:217], v[8:11]
	v_mfma_f32_16x16x32_bf16 v[4:7], v[176:179], v[222:225], v[4:7]
	v_mfma_f32_16x16x32_bf16 v[0:3], v[190:193], v[222:225], v[0:3]
	s_setprio 0
	s_barrier
; #define PG8_STAGE(bufoff, gbase, voff) do { _Pragma("unroll") for (int _i = 0; _i < 2; ++_i) \
;         __builtin_amdgcn_global_load_lds((const unsigned*)((const char*)(gbase) + (voff)[_i]), (PG8_LAS unsigned*)(lds + (bufoff) + ldsw + _i * 8192), 16, 0, 0); } while (0)
; #define PG8_LDA(dst, b, h) do { _Pragma("unroll") for (int m = 0; m < 4; ++m) _Pragma("unroll") for (int k = 0; k < 2; ++k) dst[m][k] = *(const PG8_LAS bf16x8*)(lds + PG8_SA(b, h) + aoff + m * 2048 + k * 1024); } while (0)
; #define PG8_LDB(dst, b, h) do { _Pragma("unroll") for (int n = 0; n < 2; ++n) _Pragma("unroll") for (int k = 0; k < 2; ++k) dst[n][k] = *(const PG8_LAS bf16x8*)(lds + PG8_SB(b, h) + boff + n * 2048 + k * 1024); } while (0)
; #define PG8_MMA(ai, bj, At, Bt) do { __builtin_amdgcn_s_setprio(1); _Pragma("unroll") for (int m = 0; m < 4; ++m) _Pragma("unroll") for (int n = 0; n < 2; ++n) _Pragma("unroll") for (int k = 0; k < 2; ++k) \
;         acc[ai][bj][m][n] = __builtin_amdgcn_mfma_f32_16x16x32_bf16(Bt[n][k], At[m][k], acc[ai][bj][m][n], 0, 0, 0); __builtin_amdgcn_s_setprio(0); } while (0)
; #define PG8_WAIT_V(n) asm volatile("s_waitcnt vmcnt(" #n ")" ::: "memory")
; template <class Epi, class Sched, bool ALIGN_EPI = false, bool SP2 = false>
; __device__ __forceinline__ void gemm_phase(PG8_LAS unsigned char* lds, const Gemm g, const Sched& S, const Epi& E) {
;     ...
;             PG8_LDB(B0, 0, 0); PG8_LDB(B1, 0, 1); PG8_SCHED; PG8_LDA(At, 0, 0); PG8_STAGE(PG8_SA(1, 1), a1 + hstep, voffA);
;             PG8_WAIT_V(8); PG8_WAIT_L(0); PG8_BAR; PG8_MMA(0, 0, At, B0); PG8_MMA(0, 1, At, B1); PG8_BAR; PG8_SCHED;
;             PG8_LDA(At, 0, 1); PG8_STAGE(PG8_SB(0, 0), b2, voffB); PG8_STAGE(PG8_SB(0, 1), b2 + hstep, voffB); PG8_STAGE(PG8_SA(0, 0), a2, voffA);
;             PG8_WAIT_V(8); PG8_WAIT_L(0); PG8_BAR; PG8_MMA(1, 0, At, B0); PG8_MMA(1, 1, At, B1); PG8_BAR; PG8_SCHED;
;             PG8_LDB(B0, 1, 0); PG8_LDB(B1, 1, 1); PG8_SCHED; PG8_LDA(At, 1, 0); PG8_STAGE(PG8_SA(0, 1), a2 + hstep, voffA);
;             PG8_WAIT_V(8); PG8_WAIT_L(0); PG8_BAR; PG8_MMA(0, 0, At, B0); PG8_MMA(0, 1, At, B1); PG8_BAR; PG8_SCHED;
;             PG8_LDA(At, 1, 1); PG8_STAGE(PG8_SB(1, 0), b3, voffB); PG8_STAGE(PG8_SB(1, 1), b3 + hstep, voffB); PG8_STAGE(PG8_SA(1, 0), a3, voffA);
;             PG8_WAIT_V(8); PG8_WAIT_L(0); PG8_BAR; PG8_MMA(1, 0, At, B0); PG8_MMA(1, 1, At, B1); PG8_BAR; PG8_SCHED;
.Lmy_peel_150_mid:
	s_add_i32 s54, 0, 0x18000
	v_add_u32_e32 v147, s54, v152
	s_add_i32 s55, 0, 0x1c000
	ds_read_b128 v[156:159], v147
	ds_read_b128 v[160:163], v147 offset:1024
	ds_read_b128 v[164:167], v147 offset:2048
	ds_read_b128 v[168:171], v147 offset:3072
	v_add_u32_e32 v147, s55, v152
	ds_read_b128 v[172:175], v147
	ds_read_b128 v[176:179], v147 offset:1024
	ds_read_b128 v[182:185], v147 offset:2048
	ds_read_b128 v[190:193], v147 offset:3072
	s_add_u32 s26, s26, 0x40000
	s_addc_u32 s27, s27, 0
	s_mov_b32 m0, s35
	ds_read_b128 v[194:197], v155 offset:32768
	ds_read_b128 v[198:201], v155 offset:33792
	ds_read_b128 v[202:205], v155 offset:34816
	ds_read_b128 v[206:209], v155 offset:35840
	ds_read_b128 v[210:213], v155 offset:36864
	ds_read_b128 v[214:217], v155 offset:37888
	ds_read_b128 v[218:221], v155 offset:38912
	ds_read_b128 v[222:225], v155 offset:39936
	global_load_lds_dwordx4 v128, s[26:27]
	s_mov_b32 m0, s36
	s_nop 0
	global_load_lds_dwordx4 v132, s[26:27]
	s_waitcnt vmcnt(8)
	s_waitcnt lgkmcnt(0)
	s_barrier
	s_setprio 1
	v_mfma_f32_16x16x32_bf16 v[124:127], v[156:159], v[194:197], v[124:127]
	v_mfma_f32_16x16x32_bf16 v[120:123], v[164:167], v[194:197], v[120:123]
	v_mfma_f32_16x16x32_bf16 v[116:119], v[156:159], v[202:205], v[116:119]
	v_mfma_f32_16x16x32_bf16 v[112:115], v[164:167], v[202:205], v[112:115]
	v_mfma_f32_16x16x32_bf16 v[100:103], v[156:159], v[210:213], v[100:103]
	v_mfma_f32_16x16x32_bf16 v[96:99], v[164:167], v[210:213], v[96:99]
	v_mfma_f32_16x16x32_bf16 v[84:87], v[156:159], v[218:221], v[84:87]
	v_mfma_f32_16x16x32_bf16 v[80:83], v[164:167], v[218:221], v[80:83]
	v_mfma_f32_16x16x32_bf16 v[124:127], v[160:163], v[198:201], v[124:127]
	v_mfma_f32_16x16x32_bf16 v[120:123], v[168:171], v[198:201], v[120:123]
	v_mfma_f32_16x16x32_bf16 v[116:119], v[160:163], v[206:209], v[116:119]
	v_mfma_f32_16x16x32_bf16 v[112:115], v[168:171], v[206:209], v[112:115]
	v_mfma_f32_16x16x32_bf16 v[100:103], v[160:163], v[214:217], v[100:103]
	v_mfma_f32_16x16x32_bf16 v[96:99], v[168:171], v[214:217], v[96:99]
	v_mfma_f32_16x16x32_bf16 v[84:87], v[160:163], v[222:225], v[84:87]
	v_mfma_f32_16x16x32_bf16 v[80:83], v[168:171], v[222:225], v[80:83]
	v_mfma_f32_16x16x32_bf16 v[108:111], v[172:175], v[194:197], v[108:111]
	v_mfma_f32_16x16x32_bf16 v[104:107], v[182:185], v[194:197], v[104:107]
	v_mfma_f32_16x16x32_bf16 v[92:95], v[172:175], v[202:205], v[92:95]
	v_mfma_f32_16x16x32_bf16 v[88:91], v[182:185], v[202:205], v[88:91]
	v_mfma_f32_16x16x32_bf16 v[76:79], v[172:175], v[210:213], v[76:79]
	v_mfma_f32_16x16x32_bf16 v[72:75], v[182:185], v[210:213], v[72:75]
	v_mfma_f32_16x16x32_bf16 v[68:71], v[172:175], v[218:221], v[68:71]
	v_mfma_f32_16x16x32_bf16 v[64:67], v[182:185], v[218:221], v[64:67]
	v_mfma_f32_16x16x32_bf16 v[108:111], v[176:179], v[198:201], v[108:111]
	v_mfma_f32_16x16x32_bf16 v[104:107], v[190:193], v[198:201], v[104:107]
	v_mfma_f32_16x16x32_bf16 v[92:95], v[176:179], v[206:209], v[92:95]
	v_mfma_f32_16x16x32_bf16 v[88:91], v[190:193], v[206:209], v[88:91]
	v_mfma_f32_16x16x32_bf16 v[76:79], v[176:179], v[214:217], v[76:79]
	v_mfma_f32_16x16x32_bf16 v[72:75], v[190:193], v[214:217], v[72:75]
	v_mfma_f32_16x16x32_bf16 v[68:71], v[176:179], v[222:225], v[68:71]
	v_mfma_f32_16x16x32_bf16 v[64:67], v[190:193], v[222:225], v[64:67]
	s_setprio 0
	s_barrier
	s_add_i32 s26, s54, s31
	s_mov_b32 m0, s26
	s_nop 0
	global_load_lds_dwordx4 v130, s[98:99]
	s_add_i32 m0, s26, 0x2000
	s_add_u32 s24, s24, 0x40080
	s_addc_u32 s25, s25, 0
	s_add_i32 s26, s55, s31
	global_load_lds_dwordx4 v134, s[98:99]
	s_mov_b32 m0, s26
	s_nop 0
	global_load_lds_dwordx4 v130, s[24:25]
	s_add_i32 m0, s26, 0x2000
	s_nop 0
	global_load_lds_dwordx4 v134, s[24:25]
	s_mov_b32 m0, s39
	s_nop 0
	global_load_lds_dwordx4 v128, s[100:101]
	s_mov_b32 m0, s40
	s_nop 0
	global_load_lds_dwordx4 v132, s[100:101]
	ds_read_b128 v[194:197], v155 offset:49152
	ds_read_b128 v[198:201], v155 offset:50176
	ds_read_b128 v[202:205], v155 offset:51200
	ds_read_b128 v[206:209], v155 offset:52224
	ds_read_b128 v[210:213], v155 offset:53248
	ds_read_b128 v[214:217], v155 offset:54272
	ds_read_b128 v[218:221], v155 offset:55296
	ds_read_b128 v[222:225], v155 offset:56320
	s_waitcnt vmcnt(8)
	s_waitcnt lgkmcnt(0)
	s_barrier
	s_setprio 1
	v_mfma_f32_16x16x32_bf16 v[60:63], v[156:159], v[194:197], v[60:63]
	v_mfma_f32_16x16x32_bf16 v[56:59], v[164:167], v[194:197], v[56:59]
	v_mfma_f32_16x16x32_bf16 v[52:55], v[156:159], v[202:205], v[52:55]
	v_mfma_f32_16x16x32_bf16 v[48:51], v[164:167], v[202:205], v[48:51]
	v_mfma_f32_16x16x32_bf16 v[36:39], v[156:159], v[210:213], v[36:39]
	v_mfma_f32_16x16x32_bf16 v[32:35], v[164:167], v[210:213], v[32:35]
	v_mfma_f32_16x16x32_bf16 v[20:23], v[156:159], v[218:221], v[20:23]
	v_mfma_f32_16x16x32_bf16 v[16:19], v[164:167], v[218:221], v[16:19]
	v_mfma_f32_16x16x32_bf16 v[60:63], v[160:163], v[198:201], v[60:63]
	v_mfma_f32_16x16x32_bf16 v[56:59], v[168:171], v[198:201], v[56:59]
	v_mfma_f32_16x16x32_bf16 v[52:55], v[160:163], v[206:209], v[52:55]
	v_mfma_f32_16x16x32_bf16 v[48:51], v[168:171], v[206:209], v[48:51]
	v_mfma_f32_16x16x32_bf16 v[36:39], v[160:163], v[214:217], v[36:39]
	v_mfma_f32_16x16x32_bf16 v[32:35], v[168:171], v[214:217], v[32:35]
	v_mfma_f32_16x16x32_bf16 v[20:23], v[160:163], v[222:225], v[20:23]
	v_mfma_f32_16x16x32_bf16 v[16:19], v[168:171], v[222:225], v[16:19]
	v_mfma_f32_16x16x32_bf16 v[44:47], v[172:175], v[194:197], v[44:47]
	v_mfma_f32_16x16x32_bf16 v[40:43], v[182:185], v[194:197], v[40:43]
	v_mfma_f32_16x16x32_bf16 v[28:31], v[172:175], v[202:205], v[28:31]
	v_mfma_f32_16x16x32_bf16 v[24:27], v[182:185], v[202:205], v[24:27]
	v_mfma_f32_16x16x32_bf16 v[12:15], v[172:175], v[210:213], v[12:15]
	v_mfma_f32_16x16x32_bf16 v[8:11], v[182:185], v[210:213], v[8:11]
	v_mfma_f32_16x16x32_bf16 v[4:7], v[172:175], v[218:221], v[4:7]
	v_mfma_f32_16x16x32_bf16 v[0:3], v[182:185], v[218:221], v[0:3]
	v_mfma_f32_16x16x32_bf16 v[44:47], v[176:179], v[198:201], v[44:47]
	v_mfma_f32_16x16x32_bf16 v[40:43], v[190:193], v[198:201], v[40:43]
	v_mfma_f32_16x16x32_bf16 v[28:31], v[176:179], v[206:209], v[28:31]
	v_mfma_f32_16x16x32_bf16 v[24:27], v[190:193], v[206:209], v[24:27]
	v_mfma_f32_16x16x32_bf16 v[12:15], v[176:179], v[214:217], v[12:15]
	v_mfma_f32_16x16x32_bf16 v[8:11], v[190:193], v[214:217], v[8:11]
	v_mfma_f32_16x16x32_bf16 v[4:7], v[176:179], v[222:225], v[4:7]
	v_mfma_f32_16x16x32_bf16 v[0:3], v[190:193], v[222:225], v[0:3]
	s_setprio 0
	s_barrier
	s_add_i32 s49, s49, 2
	s_add_u32 s22, s22, 0x100
	s_addc_u32 s23, s23, 0
	s_add_u32 s47, s47, 0x100
	s_addc_u32 s48, s48, 0
	s_cmp_gt_u32 s49, 13
	s_cbranch_scc0 .LBB0_150
	s_and_b64 vcc, exec, s[10:11]
	s_cbranch_vccz .LBB0_153
	s_barrier

; #define PG8_STAGE(bufoff, gbase, voff) do { _Pragma("unroll") for (int _i = 0; _i < 2; ++_i) \
;         __builtin_amdgcn_global_load_lds((const unsigned*)((const char*)(gbase) + (voff)[_i]), (PG8_LAS unsigned*)(lds + (bufoff) + ldsw + _i * 8192), 16, 0, 0); } while (0)
; #define PG8_LDA(dst, b, h) do { _Pragma("unroll") for (int m = 0; m < 4; ++m) _Pragma("unroll") for (int k = 0; k < 2; ++k) dst[m][k] = *(const PG8_LAS bf16x8*)(lds + PG8_SA(b, h) + aoff + m * 2048 + k * 1024); } while (0)
; #define PG8_LDB(dst, b, h) do { _Pragma("unroll") for (int n = 0; n < 2; ++n) _Pragma("unroll") for (int k = 0; k < 2; ++k) dst[n][k] = *(const PG8_LAS bf16x8*)(lds + PG8_SB(b, h) + boff + n * 2048 + k * 1024); } while (0)
; #define PG8_MMA(ai, bj, At, Bt) do { __builtin_amdgcn_s_setprio(1); _Pragma("unroll") for (int m = 0; m < 4; ++m) _Pragma("unroll") for (int n = 0; n < 2; ++n) _Pragma("unroll") for (int k = 0; k < 2; ++k) \
;         acc[ai][bj][m][n] = __builtin_amdgcn_mfma_f32_16x16x32_bf16(Bt[n][k], At[m][k], acc[ai][bj][m][n], 0, 0, 0); __builtin_amdgcn_s_setprio(0); } while (0)
; #define PG8_WAIT_V(n) asm volatile("s_waitcnt vmcnt(" #n ")" ::: "memory")
; template <class Epi, class Sched, bool ALIGN_EPI = false, bool SP2 = false>
; __device__ __forceinline__ void gemm_phase(PG8_LAS unsigned char* lds, const Gemm g, const Sched& S, const Epi& E) {
;     ...
;             PG8_LDB(B0, 0, 0); PG8_LDB(B1, 0, 1); PG8_SCHED; PG8_LDA(At, 0, 0); PG8_STAGE(PG8_SA(1, 1), a1 + hstep, voffA);
;             PG8_WAIT_V(8); PG8_WAIT_L(0); PG8_BAR; PG8_MMA(0, 0, At, B0); PG8_MMA(0, 1, At, B1); PG8_BAR; PG8_SCHED;
;             PG8_LDA(At, 0, 1); PG8_STAGE(PG8_SB(0, 0), b2, voffB); PG8_STAGE(PG8_SB(0, 1), b2 + hstep, voffB); PG8_STAGE(PG8_SA(0, 0), a2, voffA);
;             PG8_WAIT_V(8); PG8_WAIT_L(0); PG8_BAR; PG8_MMA(1, 0, At, B0); PG8_MMA(1, 1, At, B1); PG8_BAR; PG8_SCHED;
;             PG8_LDB(B0, 1, 0); PG8_LDB(B1, 1, 1); PG8_SCHED; PG8_LDA(At, 1, 0); PG8_STAGE(PG8_SA(0, 1), a2 + hstep, voffA);
;             PG8_WAIT_V(8); PG8_WAIT_L(0); PG8_BAR; PG8_MMA(0, 0, At, B0); PG8_MMA(0, 1, At, B1); PG8_BAR; PG8_SCHED;
;             PG8_LDA(At, 1, 1); PG8_STAGE(PG8_SB(1, 0), b3, voffB); PG8_STAGE(PG8_SB(1, 1), b3 + hstep, voffB); PG8_STAGE(PG8_SA(1, 0), a3, voffA);
;             PG8_WAIT_V(8); PG8_WAIT_L(0); PG8_BAR; PG8_MMA(1, 0, At, B0); PG8_MMA(1, 1, At, B1); PG8_BAR; PG8_SCHED;
.LBB0_358:
	ds_read_b128 v[128:131], v178
	ds_read_b128 v[132:135], v178 offset:1024
	ds_read_b128 v[136:139], v178 offset:2048
	ds_read_b128 v[140:143], v178 offset:3072
	ds_read_b128 v[166:169], v179
	ds_read_b128 v[170:173], v179 offset:1024
	ds_read_b128 v[190:193], v179 offset:2048
	ds_read_b128 v[194:197], v179 offset:3072
	s_add_u32 s42, s40, 0xfffc0080
	s_addc_u32 s43, s41, -1
	s_cmp_eq_u32 s25, 12
	s_cselect_b32 s45, s1, s43
	s_cselect_b32 s44, s35, s42
	s_cselect_b32 s43, s31, s24
	s_cselect_b32 s42, vcc_lo, vcc_hi
	v_lshl_add_u64 v[174:175], s[40:41], 0, v[158:159]
	s_add_i32 m0, s47, 0xc000
	ds_read_b128 v[198:201], v181
	ds_read_b128 v[202:205], v181 offset:1024
	ds_read_b128 v[206:209], v181 offset:2048
	ds_read_b128 v[210:213], v181 offset:3072
	ds_read_b128 v[214:217], v181 offset:4096
	ds_read_b128 v[218:221], v181 offset:5120
	ds_read_b128 v[222:225], v181 offset:6144
	ds_read_b128 v[226:229], v181 offset:7168
	global_load_lds_dwordx4 v[174:175], off
	v_lshl_add_u64 v[174:175], s[40:41], 0, v[160:161]
	s_add_i32 m0, s47, 0xe000
	s_nop 0
	global_load_lds_dwordx4 v[174:175], off
	s_waitcnt vmcnt(8)
	s_waitcnt lgkmcnt(0)
	s_barrier
	s_setprio 1
	v_mfma_f32_16x16x32_bf16 v[124:127], v[128:131], v[198:201], v[124:127]
	v_mfma_f32_16x16x32_bf16 v[120:123], v[136:139], v[198:201], v[120:123]
	v_mfma_f32_16x16x32_bf16 v[108:111], v[128:131], v[206:209], v[108:111]
	v_mfma_f32_16x16x32_bf16 v[104:107], v[136:139], v[206:209], v[104:107]
	v_mfma_f32_16x16x32_bf16 v[92:95], v[128:131], v[214:217], v[92:95]
	v_mfma_f32_16x16x32_bf16 v[88:91], v[136:139], v[214:217], v[88:91]
	v_mfma_f32_16x16x32_bf16 v[76:79], v[128:131], v[222:225], v[76:79]
	v_mfma_f32_16x16x32_bf16 v[72:75], v[136:139], v[222:225], v[72:75]
	v_mfma_f32_16x16x32_bf16 v[124:127], v[132:135], v[202:205], v[124:127]
	v_mfma_f32_16x16x32_bf16 v[120:123], v[140:143], v[202:205], v[120:123]
	v_mfma_f32_16x16x32_bf16 v[108:111], v[132:135], v[210:213], v[108:111]
	v_mfma_f32_16x16x32_bf16 v[104:107], v[140:143], v[210:213], v[104:107]
	v_mfma_f32_16x16x32_bf16 v[92:95], v[132:135], v[218:221], v[92:95]
	v_mfma_f32_16x16x32_bf16 v[88:91], v[140:143], v[218:221], v[88:91]
	v_mfma_f32_16x16x32_bf16 v[76:79], v[132:135], v[226:229], v[76:79]
	v_mfma_f32_16x16x32_bf16 v[72:75], v[140:143], v[226:229], v[72:75]
	v_mfma_f32_16x16x32_bf16 v[116:119], v[166:169], v[198:201], v[116:119]
	v_mfma_f32_16x16x32_bf16 v[112:115], v[190:193], v[198:201], v[112:115]
	v_mfma_f32_16x16x32_bf16 v[100:103], v[166:169], v[206:209], v[100:103]
	v_mfma_f32_16x16x32_bf16 v[96:99], v[190:193], v[206:209], v[96:99]
	v_mfma_f32_16x16x32_bf16 v[84:87], v[166:169], v[214:217], v[84:87]
	v_mfma_f32_16x16x32_bf16 v[80:83], v[190:193], v[214:217], v[80:83]
	v_mfma_f32_16x16x32_bf16 v[68:71], v[166:169], v[222:225], v[68:71]
	v_mfma_f32_16x16x32_bf16 v[64:67], v[190:193], v[222:225], v[64:67]
	v_mfma_f32_16x16x32_bf16 v[116:119], v[170:173], v[202:205], v[116:119]
	v_mfma_f32_16x16x32_bf16 v[112:115], v[194:197], v[202:205], v[112:115]
	v_mfma_f32_16x16x32_bf16 v[100:103], v[170:173], v[210:213], v[100:103]
	v_mfma_f32_16x16x32_bf16 v[96:99], v[194:197], v[210:213], v[96:99]
	v_mfma_f32_16x16x32_bf16 v[84:87], v[170:173], v[218:221], v[84:87]
	v_mfma_f32_16x16x32_bf16 v[80:83], v[194:197], v[218:221], v[80:83]
	v_mfma_f32_16x16x32_bf16 v[68:71], v[170:173], v[226:229], v[68:71]
	v_mfma_f32_16x16x32_bf16 v[64:67], v[194:197], v[226:229], v[64:67]
	s_setprio 0
	s_barrier
	s_add_i32 s54, s93, s46
	v_lshl_add_u64 v[174:175], s[42:43], 0, v[146:147]
	s_mov_b32 m0, s54
	s_nop 0
	global_load_lds_dwordx4 v[174:175], off
	s_add_i32 m0, s54, 0x2000
	s_add_u32 s54, s42, 0x40000
	v_lshl_add_u64 v[186:187], s[42:43], 0, v[150:151]
	s_addc_u32 s55, s43, 0
	s_add_i32 s23, s94, s46
	global_load_lds_dwordx4 v[186:187], off
	v_lshl_add_u64 v[230:231], s[54:55], 0, v[146:147]
	s_mov_b32 m0, s23
	v_lshl_add_u64 v[232:233], s[44:45], 0, v[148:149]
	global_load_lds_dwordx4 v[230:231], off
	v_lshl_add_u64 v[230:231], s[54:55], 0, v[150:151]
	s_add_i32 m0, s23, 0x2000
	s_nop 0
	global_load_lds_dwordx4 v[230:231], off
	v_lshl_add_u64 v[230:231], s[44:45], 0, v[144:145]
	s_mov_b32 m0, s47
	s_nop 0
	global_load_lds_dwordx4 v[230:231], off
	s_mov_b32 m0, s48
	s_nop 0
	global_load_lds_dwordx4 v[232:233], off
	ds_read_b128 v[198:201], v181 offset:16384
	ds_read_b128 v[202:205], v181 offset:17408
	ds_read_b128 v[206:209], v181 offset:18432
	ds_read_b128 v[210:213], v181 offset:19456
	ds_read_b128 v[214:217], v181 offset:20480
	ds_read_b128 v[218:221], v181 offset:21504
	ds_read_b128 v[222:225], v181 offset:22528
	ds_read_b128 v[226:229], v181 offset:23552
	s_waitcnt vmcnt(8)
	s_waitcnt lgkmcnt(0)
	s_barrier
; #define PG8_STAGE(bufoff, gbase, voff) do { _Pragma("unroll") for (int _i = 0; _i < 2; ++_i) \
;         __builtin_amdgcn_global_load_lds((const unsigned*)((const char*)(gbase) + (voff)[_i]), (PG8_LAS unsigned*)(lds + (bufoff) + ldsw + _i * 8192), 16, 0, 0); } while (0)
; #define PG8_LDA(dst, b, h) do { _Pragma("unroll") for (int m = 0; m < 4; ++m) _Pragma("unroll") for (int k = 0; k < 2; ++k) dst[m][k] = *(const PG8_LAS bf16x8*)(lds + PG8_SA(b, h) + aoff + m * 2048 + k * 1024); } while (0)
; #define PG8_LDB(dst, b, h) do { _Pragma("unroll") for (int n = 0; n < 2; ++n) _Pragma("unroll") for (int k = 0; k < 2; ++k) dst[n][k] = *(const PG8_LAS bf16x8*)(lds + PG8_SB(b, h) + boff + n * 2048 + k * 1024); } while (0)
; #define PG8_MMA(ai, bj, At, Bt) do { __builtin_amdgcn_s_setprio(1); _Pragma("unroll") for (int m = 0; m < 4; ++m) _Pragma("unroll") for (int n = 0; n < 2; ++n) _Pragma("unroll") for (int k = 0; k < 2; ++k) \
;         acc[ai][bj][m][n] = __builtin_amdgcn_mfma_f32_16x16x32_bf16(Bt[n][k], At[m][k], acc[ai][bj][m][n], 0, 0, 0); __builtin_amdgcn_s_setprio(0); } while (0)
; #define PG8_WAIT_V(n) asm volatile("s_waitcnt vmcnt(" #n ")" ::: "memory")
; template <class Epi, class Sched, bool ALIGN_EPI = false, bool SP2 = false>
; __device__ __forceinline__ void gemm_phase(PG8_LAS unsigned char* lds, const Gemm g, const Sched& S, const Epi& E) {
;     ...
;             PG8_LDB(B0, 0, 0); PG8_LDB(B1, 0, 1); PG8_SCHED; PG8_LDA(At, 0, 0); PG8_STAGE(PG8_SA(1, 1), a1 + hstep, voffA);
;             PG8_WAIT_V(8); PG8_WAIT_L(0); PG8_BAR; PG8_MMA(0, 0, At, B0); PG8_MMA(0, 1, At, B1); PG8_BAR; PG8_SCHED;
;             PG8_LDA(At, 0, 1); PG8_STAGE(PG8_SB(0, 0), b2, voffB); PG8_STAGE(PG8_SB(0, 1), b2 + hstep, voffB); PG8_STAGE(PG8_SA(0, 0), a2, voffA);
;             PG8_WAIT_V(8); PG8_WAIT_L(0); PG8_BAR; PG8_MMA(1, 0, At, B0); PG8_MMA(1, 1, At, B1); PG8_BAR; PG8_SCHED;
;             PG8_LDB(B0, 1, 0); PG8_LDB(B1, 1, 1); PG8_SCHED; PG8_LDA(At, 1, 0); PG8_STAGE(PG8_SA(0, 1), a2 + hstep, voffA);
;             PG8_WAIT_V(8); PG8_WAIT_L(0); PG8_BAR; PG8_MMA(0, 0, At, B0); PG8_MMA(0, 1, At, B1); PG8_BAR; PG8_SCHED;
;             PG8_LDA(At, 1, 1); PG8_STAGE(PG8_SB(1, 0), b3, voffB); PG8_STAGE(PG8_SB(1, 1), b3 + hstep, voffB); PG8_STAGE(PG8_SA(1, 0), a3, voffA);
;             PG8_WAIT_V(8); PG8_WAIT_L(0); PG8_BAR; PG8_MMA(1, 0, At, B0); PG8_MMA(1, 1, At, B1); PG8_BAR; PG8_SCHED;
	s_setprio 1
	v_mfma_f32_16x16x32_bf16 v[60:63], v[128:131], v[198:201], v[60:63]
	v_mfma_f32_16x16x32_bf16 v[56:59], v[136:139], v[198:201], v[56:59]
	v_mfma_f32_16x16x32_bf16 v[44:47], v[128:131], v[206:209], v[44:47]
	v_mfma_f32_16x16x32_bf16 v[40:43], v[136:139], v[206:209], v[40:43]
	v_mfma_f32_16x16x32_bf16 v[28:31], v[128:131], v[214:217], v[28:31]
	v_mfma_f32_16x16x32_bf16 v[24:27], v[136:139], v[214:217], v[24:27]
	v_mfma_f32_16x16x32_bf16 v[12:15], v[128:131], v[222:225], v[12:15]
	v_mfma_f32_16x16x32_bf16 v[8:11], v[136:139], v[222:225], v[8:11]
	v_mfma_f32_16x16x32_bf16 v[60:63], v[132:135], v[202:205], v[60:63]
	v_mfma_f32_16x16x32_bf16 v[56:59], v[140:143], v[202:205], v[56:59]
	v_mfma_f32_16x16x32_bf16 v[44:47], v[132:135], v[210:213], v[44:47]
	v_mfma_f32_16x16x32_bf16 v[40:43], v[140:143], v[210:213], v[40:43]
	v_mfma_f32_16x16x32_bf16 v[28:31], v[132:135], v[218:221], v[28:31]
	v_mfma_f32_16x16x32_bf16 v[24:27], v[140:143], v[218:221], v[24:27]
	v_mfma_f32_16x16x32_bf16 v[12:15], v[132:135], v[226:229], v[12:15]
	v_mfma_f32_16x16x32_bf16 v[8:11], v[140:143], v[226:229], v[8:11]
	v_mfma_f32_16x16x32_bf16 v[52:55], v[166:169], v[198:201], v[52:55]
	v_mfma_f32_16x16x32_bf16 v[48:51], v[190:193], v[198:201], v[48:51]
	v_mfma_f32_16x16x32_bf16 v[36:39], v[166:169], v[206:209], v[36:39]
	v_mfma_f32_16x16x32_bf16 v[32:35], v[190:193], v[206:209], v[32:35]
	v_mfma_f32_16x16x32_bf16 v[20:23], v[166:169], v[214:217], v[20:23]
	v_mfma_f32_16x16x32_bf16 v[16:19], v[190:193], v[214:217], v[16:19]
	v_mfma_f32_16x16x32_bf16 v[4:7], v[166:169], v[222:225], v[4:7]
	v_mfma_f32_16x16x32_bf16 v[0:3], v[190:193], v[222:225], v[0:3]
	v_mfma_f32_16x16x32_bf16 v[52:55], v[170:173], v[202:205], v[52:55]
	v_mfma_f32_16x16x32_bf16 v[48:51], v[194:197], v[202:205], v[48:51]
	v_mfma_f32_16x16x32_bf16 v[36:39], v[170:173], v[210:213], v[36:39]
	v_mfma_f32_16x16x32_bf16 v[32:35], v[194:197], v[210:213], v[32:35]
	v_mfma_f32_16x16x32_bf16 v[20:23], v[170:173], v[218:221], v[20:23]
	v_mfma_f32_16x16x32_bf16 v[16:19], v[194:197], v[218:221], v[16:19]
	v_mfma_f32_16x16x32_bf16 v[4:7], v[170:173], v[226:229], v[4:7]
	v_mfma_f32_16x16x32_bf16 v[0:3], v[194:197], v[226:229], v[0:3]
	s_setprio 0
	s_barrier
	s_add_i32 s23, 0, 0x18000
	s_add_i32 s54, 0, 0x1c000
	v_add_u32_e32 v140, s23, v176
	v_add_u32_e32 v152, s54, v176
	s_add_u32 s44, s44, 0x40000
	s_addc_u32 s45, s45, 0
	s_mov_b32 m0, s49
	v_lshl_add_u64 v[234:235], s[44:45], 0, v[144:145]
	global_load_lds_dwordx4 v[234:235], off
	v_lshl_add_u64 v[234:235], s[44:45], 0, v[148:149]
	s_mov_b32 m0, s51
	s_nop 0
	global_load_lds_dwordx4 v[234:235], off
	ds_read_b128 v[128:131], v140
	ds_read_b128 v[132:135], v140 offset:1024
	ds_read_b128 v[136:139], v140 offset:2048
	ds_read_b128 v[140:143], v140 offset:3072
	ds_read_b128 v[166:169], v152
	ds_read_b128 v[170:173], v152 offset:1024
	ds_read_b128 v[190:193], v152 offset:2048
	ds_read_b128 v[194:197], v152 offset:3072
	ds_read_b128 v[198:201], v181 offset:32768
	ds_read_b128 v[202:205], v181 offset:33792
	ds_read_b128 v[206:209], v181 offset:34816
	ds_read_b128 v[210:213], v181 offset:35840
	ds_read_b128 v[214:217], v181 offset:36864
	ds_read_b128 v[218:221], v181 offset:37888
	ds_read_b128 v[222:225], v181 offset:38912
	ds_read_b128 v[226:229], v181 offset:39936
	s_waitcnt vmcnt(8)
	s_waitcnt lgkmcnt(0)
	s_barrier
	s_setprio 1
	v_mfma_f32_16x16x32_bf16 v[124:127], v[128:131], v[198:201], v[124:127]
	v_mfma_f32_16x16x32_bf16 v[120:123], v[136:139], v[198:201], v[120:123]
	v_mfma_f32_16x16x32_bf16 v[108:111], v[128:131], v[206:209], v[108:111]
	v_mfma_f32_16x16x32_bf16 v[104:107], v[136:139], v[206:209], v[104:107]
	v_mfma_f32_16x16x32_bf16 v[92:95], v[128:131], v[214:217], v[92:95]
	v_mfma_f32_16x16x32_bf16 v[88:91], v[136:139], v[214:217], v[88:91]
	v_mfma_f32_16x16x32_bf16 v[76:79], v[128:131], v[222:225], v[76:79]
	v_mfma_f32_16x16x32_bf16 v[72:75], v[136:139], v[222:225], v[72:75]
	v_mfma_f32_16x16x32_bf16 v[124:127], v[132:135], v[202:205], v[124:127]
	v_mfma_f32_16x16x32_bf16 v[120:123], v[140:143], v[202:205], v[120:123]
	v_mfma_f32_16x16x32_bf16 v[108:111], v[132:135], v[210:213], v[108:111]
	v_mfma_f32_16x16x32_bf16 v[104:107], v[140:143], v[210:213], v[104:107]
	v_mfma_f32_16x16x32_bf16 v[92:95], v[132:135], v[218:221], v[92:95]
	v_mfma_f32_16x16x32_bf16 v[88:91], v[140:143], v[218:221], v[88:91]
	v_mfma_f32_16x16x32_bf16 v[76:79], v[132:135], v[226:229], v[76:79]
	v_mfma_f32_16x16x32_bf16 v[72:75], v[140:143], v[226:229], v[72:75]
	v_mfma_f32_16x16x32_bf16 v[116:119], v[166:169], v[198:201], v[116:119]
	v_mfma_f32_16x16x32_bf16 v[112:115], v[190:193], v[198:201], v[112:115]
	v_mfma_f32_16x16x32_bf16 v[100:103], v[166:169], v[206:209], v[100:103]
	v_mfma_f32_16x16x32_bf16 v[96:99], v[190:193], v[206:209], v[96:99]
	v_mfma_f32_16x16x32_bf16 v[84:87], v[166:169], v[214:217], v[84:87]
	v_mfma_f32_16x16x32_bf16 v[80:83], v[190:193], v[214:217], v[80:83]
	v_mfma_f32_16x16x32_bf16 v[68:71], v[166:169], v[222:225], v[68:71]
	v_mfma_f32_16x16x32_bf16 v[64:67], v[190:193], v[222:225], v[64:67]
	v_mfma_f32_16x16x32_bf16 v[116:119], v[170:173], v[202:205], v[116:119]
	v_mfma_f32_16x16x32_bf16 v[112:115], v[194:197], v[202:205], v[112:115]
	v_mfma_f32_16x16x32_bf16 v[100:103], v[170:173], v[210:213], v[100:103]
	v_mfma_f32_16x16x32_bf16 v[96:99], v[194:197], v[210:213], v[96:99]
	v_mfma_f32_16x16x32_bf16 v[84:87], v[170:173], v[218:221], v[84:87]
	v_mfma_f32_16x16x32_bf16 v[80:83], v[194:197], v[218:221], v[80:83]
	v_mfma_f32_16x16x32_bf16 v[68:71], v[170:173], v[226:229], v[68:71]
	v_mfma_f32_16x16x32_bf16 v[64:67], v[194:197], v[226:229], v[64:67]
	s_setprio 0
	s_barrier
; #define PG8_STAGE(bufoff, gbase, voff) do { _Pragma("unroll") for (int _i = 0; _i < 2; ++_i) \
;         __builtin_amdgcn_global_load_lds((const unsigned*)((const char*)(gbase) + (voff)[_i]), (PG8_LAS unsigned*)(lds + (bufoff) + ldsw + _i * 8192), 16, 0, 0); } while (0)
; #define PG8_LDA(dst, b, h) do { _Pragma("unroll") for (int m = 0; m < 4; ++m) _Pragma("unroll") for (int k = 0; k < 2; ++k) dst[m][k] = *(const PG8_LAS bf16x8*)(lds + PG8_SA(b, h) + aoff + m * 2048 + k * 1024); } while (0)
; #define PG8_LDB(dst, b, h) do { _Pragma("unroll") for (int n = 0; n < 2; ++n) _Pragma("unroll") for (int k = 0; k < 2; ++k) dst[n][k] = *(const PG8_LAS bf16x8*)(lds + PG8_SB(b, h) + boff + n * 2048 + k * 1024); } while (0)
; #define PG8_MMA(ai, bj, At, Bt) do { __builtin_amdgcn_s_setprio(1); _Pragma("unroll") for (int m = 0; m < 4; ++m) _Pragma("unroll") for (int n = 0; n < 2; ++n) _Pragma("unroll") for (int k = 0; k < 2; ++k) \
;         acc[ai][bj][m][n] = __builtin_amdgcn_mfma_f32_16x16x32_bf16(Bt[n][k], At[m][k], acc[ai][bj][m][n], 0, 0, 0); __builtin_amdgcn_s_setprio(0); } while (0)
; #define PG8_WAIT_V(n) asm volatile("s_waitcnt vmcnt(" #n ")" ::: "memory")
; template <class Epi, class Sched, bool ALIGN_EPI = false, bool SP2 = false>
; __device__ __forceinline__ void gemm_phase(PG8_LAS unsigned char* lds, const Gemm g, const Sched& S, const Epi& E) {
;     ...
;             PG8_LDB(B0, 0, 0); PG8_LDB(B1, 0, 1); PG8_SCHED; PG8_LDA(At, 0, 0); PG8_STAGE(PG8_SA(1, 1), a1 + hstep, voffA);
;             PG8_WAIT_V(8); PG8_WAIT_L(0); PG8_BAR; PG8_MMA(0, 0, At, B0); PG8_MMA(0, 1, At, B1); PG8_BAR; PG8_SCHED;
;             PG8_LDA(At, 0, 1); PG8_STAGE(PG8_SB(0, 0), b2, voffB); PG8_STAGE(PG8_SB(0, 1), b2 + hstep, voffB); PG8_STAGE(PG8_SA(0, 0), a2, voffA);
;             PG8_WAIT_V(8); PG8_WAIT_L(0); PG8_BAR; PG8_MMA(1, 0, At, B0); PG8_MMA(1, 1, At, B1); PG8_BAR; PG8_SCHED;
;             PG8_LDB(B0, 1, 0); PG8_LDB(B1, 1, 1); PG8_SCHED; PG8_LDA(At, 1, 0); PG8_STAGE(PG8_SA(0, 1), a2 + hstep, voffA);
;             PG8_WAIT_V(8); PG8_WAIT_L(0); PG8_BAR; PG8_MMA(0, 0, At, B0); PG8_MMA(0, 1, At, B1); PG8_BAR; PG8_SCHED;
;             PG8_LDA(At, 1, 1); PG8_STAGE(PG8_SB(1, 0), b3, voffB); PG8_STAGE(PG8_SB(1, 1), b3 + hstep, voffB); PG8_STAGE(PG8_SA(1, 0), a3, voffA);
;             PG8_WAIT_V(8); PG8_WAIT_L(0); PG8_BAR; PG8_MMA(1, 0, At, B0); PG8_MMA(1, 1, At, B1); PG8_BAR; PG8_SCHED;
	s_add_i32 s23, s23, s46
	v_lshl_add_u64 v[174:175], v[174:175], 0, s[10:11]
	s_mov_b32 m0, s23
	s_nop 0
	global_load_lds_dwordx4 v[174:175], off
	s_add_i32 m0, s23, 0x2000
	s_add_u32 s42, s42, 0x40080
	v_lshl_add_u64 v[174:175], v[186:187], 0, s[10:11]
	s_addc_u32 s43, s43, 0
	s_add_i32 s23, s54, s46
	global_load_lds_dwordx4 v[174:175], off
	v_lshl_add_u64 v[174:175], s[42:43], 0, v[146:147]
	s_mov_b32 m0, s23
	s_nop 0
	global_load_lds_dwordx4 v[174:175], off
	v_lshl_add_u64 v[174:175], s[42:43], 0, v[150:151]
	s_add_i32 m0, s23, 0x2000
	s_nop 0
	global_load_lds_dwordx4 v[174:175], off
	v_lshl_add_u64 v[174:175], v[230:231], 0, s[10:11]
	s_mov_b32 m0, s80
	s_nop 0
	global_load_lds_dwordx4 v[174:175], off
	v_lshl_add_u64 v[174:175], v[232:233], 0, s[10:11]
	s_mov_b32 m0, s81
	s_nop 0
	global_load_lds_dwordx4 v[174:175], off
	ds_read_b128 v[198:201], v181 offset:49152
	ds_read_b128 v[202:205], v181 offset:50176
	ds_read_b128 v[206:209], v181 offset:51200
	ds_read_b128 v[210:213], v181 offset:52224
	ds_read_b128 v[214:217], v181 offset:53248
	ds_read_b128 v[218:221], v181 offset:54272
	ds_read_b128 v[222:225], v181 offset:55296
	ds_read_b128 v[226:229], v181 offset:56320
	s_waitcnt vmcnt(8)
	s_waitcnt lgkmcnt(0)
	s_barrier
	s_setprio 1
	v_mfma_f32_16x16x32_bf16 v[60:63], v[128:131], v[198:201], v[60:63]
	v_mfma_f32_16x16x32_bf16 v[56:59], v[136:139], v[198:201], v[56:59]
	v_mfma_f32_16x16x32_bf16 v[44:47], v[128:131], v[206:209], v[44:47]
	v_mfma_f32_16x16x32_bf16 v[40:43], v[136:139], v[206:209], v[40:43]
	v_mfma_f32_16x16x32_bf16 v[28:31], v[128:131], v[214:217], v[28:31]
	v_mfma_f32_16x16x32_bf16 v[24:27], v[136:139], v[214:217], v[24:27]
	v_mfma_f32_16x16x32_bf16 v[12:15], v[128:131], v[222:225], v[12:15]
	v_mfma_f32_16x16x32_bf16 v[8:11], v[136:139], v[222:225], v[8:11]
	v_mfma_f32_16x16x32_bf16 v[60:63], v[132:135], v[202:205], v[60:63]
	v_mfma_f32_16x16x32_bf16 v[56:59], v[140:143], v[202:205], v[56:59]
	v_mfma_f32_16x16x32_bf16 v[44:47], v[132:135], v[210:213], v[44:47]
	v_mfma_f32_16x16x32_bf16 v[40:43], v[140:143], v[210:213], v[40:43]
	v_mfma_f32_16x16x32_bf16 v[28:31], v[132:135], v[218:221], v[28:31]
	v_mfma_f32_16x16x32_bf16 v[24:27], v[140:143], v[218:221], v[24:27]
	v_mfma_f32_16x16x32_bf16 v[12:15], v[132:135], v[226:229], v[12:15]
	v_mfma_f32_16x16x32_bf16 v[8:11], v[140:143], v[226:229], v[8:11]
	v_mfma_f32_16x16x32_bf16 v[52:55], v[166:169], v[198:201], v[52:55]
	v_mfma_f32_16x16x32_bf16 v[48:51], v[190:193], v[198:201], v[48:51]
	v_mfma_f32_16x16x32_bf16 v[36:39], v[166:169], v[206:209], v[36:39]
	v_mfma_f32_16x16x32_bf16 v[32:35], v[190:193], v[206:209], v[32:35]
	v_mfma_f32_16x16x32_bf16 v[20:23], v[166:169], v[214:217], v[20:23]
	v_mfma_f32_16x16x32_bf16 v[16:19], v[190:193], v[214:217], v[16:19]
	v_mfma_f32_16x16x32_bf16 v[4:7], v[166:169], v[222:225], v[4:7]
	v_mfma_f32_16x16x32_bf16 v[0:3], v[190:193], v[222:225], v[0:3]
	v_mfma_f32_16x16x32_bf16 v[52:55], v[170:173], v[202:205], v[52:55]
	v_mfma_f32_16x16x32_bf16 v[48:51], v[194:197], v[202:205], v[48:51]
	v_mfma_f32_16x16x32_bf16 v[36:39], v[170:173], v[210:213], v[36:39]
	v_mfma_f32_16x16x32_bf16 v[32:35], v[194:197], v[210:213], v[32:35]
	v_mfma_f32_16x16x32_bf16 v[20:23], v[170:173], v[218:221], v[20:23]
	v_mfma_f32_16x16x32_bf16 v[16:19], v[194:197], v[218:221], v[16:19]
	v_mfma_f32_16x16x32_bf16 v[4:7], v[170:173], v[226:229], v[4:7]
	v_mfma_f32_16x16x32_bf16 v[0:3], v[194:197], v[226:229], v[0:3]
	s_setprio 0
	s_barrier
	s_add_i32 s25, s25, 2
	s_add_u32 s40, s40, 0x100
	s_addc_u32 s41, s41, 0
	s_add_u32 vcc_hi, vcc_hi, 0x100
	s_addc_u32 s24, s24, 0
	s_cmp_gt_u32 s25, 13
	s_cbranch_scc0 .LBB0_358
	s_and_b64 vcc, exec, s[12:13]
	s_cbranch_vccz .LBB0_361
	s_barrier

;     __host__ __device__ bool next(int i, Unit& u) const { const long L = (long)i * G + c; if (L >= nwg) return false; return unit_of((int)L, u); }
;     __host__ __device__ bool next(int i, Unit& u) const { const int L = i == 0 ? l0 : (i == 1 ? l1 : (i == 2 ? l2 : -1)); if (L < 0 || L >= s.nwg) return false; return s.unit_of(L, u); }
;     __host__ __device__ bool next(int i, Unit& u) const { const bool ok = s.next(i >> 1, u); u.kh = i & 1; return ok; }
; #define PG8_STAGE(bufoff, gbase, voff) do { _Pragma("unroll") for (int _i = 0; _i < 2; ++_i) \
;         __builtin_amdgcn_global_load_lds((const unsigned*)((const char*)(gbase) + (voff)[_i]), (PG8_LAS unsigned*)(lds + (bufoff) + ldsw + _i * 8192), 16, 0, 0); } while (0)
; #define PG8_LDA(dst, b, h) do { _Pragma("unroll") for (int m = 0; m < 4; ++m) _Pragma("unroll") for (int k = 0; k < 2; ++k) dst[m][k] = *(const PG8_LAS bf16x8*)(lds + PG8_SA(b, h) + aoff + m * 2048 + k * 1024); } while (0)
; template <class Epi, class Sched, bool ALIGN_EPI = false, bool SP2 = false>
; __device__ __forceinline__ void gemm_phase(PG8_LAS unsigned char* lds, const Gemm g, const Sched& S, const Epi& E) {
;     ...
;         const bool has_next = S.next(ui + 1, nxt);
;         const char* nA = has_next ? (const char*)g.A + (size_t)nxt.pm * tstep + nxt.kh * khb : cA; const char* nB = has_next ? (const char*)g.Bt + (size_t)nxt.pn * tstep + nxt.kh * khb : cB;
;         for (int t = 0; t < nt; t += 2) {
;             const bool last = (t == nt - 2);
;             const char* a1 = cA + (size_t)(t + 1) * kstep;
;             const char* a2 = last ? nA : cA + (size_t)(t + 2) * kstep; const char* b2 = last ? nB : cB + (size_t)(t + 2) * kstep;
;             const char* a3 = a2 + kstep; const char* b3 = b2 + kstep;
;             if (last && has_next) S.a_ready(nxt);
;             if constexpr (SP2) {
;             PG8_LDB(B0, 0, 0); PG8_LDB(B1, 0, 1); PG8_SCHED; PG8_LDA(At, 0, 0); PG8_STAGE(PG8_SA(1, 1), a1 + hstep, voffA);
;             PG8_WAIT_V(8); PG8_WAIT_L(0); PG8_BAR; PG8_MMA(0, 0, At, B0); PG8_MMA(0, 1, At, B1); PG8_BAR; PG8_SCHED;
;             PG8_LDA(At, 0, 1); PG8_STAGE(PG8_SB(0, 0), b2, voffB); PG8_STAGE(PG8_SB(0, 1), b2 + hstep, voffB); PG8_STAGE(PG8_SA(0, 0), a2, voffA);
;             PG8_WAIT_V(8); PG8_WAIT_L(0); PG8_BAR; PG8_MMA(1, 0, At, B0); PG8_MMA(1, 1, At, B1); PG8_BAR; PG8_SCHED;
.LBB0_683:
	s_ashr_i32 s3, s2, 31
	s_lshl_b64 s[12:13], s[2:3], 19
	v_readlane_b32 s3, v254, 13
	s_add_u32 s16, s3, s12
	v_readlane_b32 s3, v254, 17
	s_addc_u32 s17, s3, s13
	s_and_b64 s[12:13], s[38:39], exec
	s_cselect_b32 s3, s17, s1
	s_cselect_b32 s94, s16, s0
	s_ashr_i32 s5, s4, 31
	s_lshl_b64 s[12:13], s[4:5], 19
	v_readlane_b32 s5, v254, 15
	s_add_u32 s12, s5, s12
	s_addc_u32 s13, s50, s13
	s_and_b64 s[42:43], s[38:39], exec
	s_cselect_b32 s5, s13, s41
	s_cselect_b32 s95, s12, s40
	s_add_u32 s0, s0, 0x40080
	s_addc_u32 s1, s1, 0
	s_add_u32 s96, s40, 0x100
	s_addc_u32 s97, s41, 0
	s_mov_b32 vcc_lo, -2
	ds_read_b128 v[128:131], v174
	ds_read_b128 v[132:135], v174 offset:1024
	ds_read_b128 v[136:139], v174 offset:2048
	ds_read_b128 v[140:143], v174 offset:3072
	ds_read_b128 v[162:165], v175
	ds_read_b128 v[166:169], v175 offset:1024
	ds_read_b128 v[180:183], v175 offset:2048
	ds_read_b128 v[184:187], v175 offset:3072
	s_add_u32 s8, s0, 0xfffc0080
	s_addc_u32 s9, s1, -1
	s_cmp_eq_u32 vcc_lo, 12
	s_cselect_b32 s43, s3, s9
	s_cselect_b32 s42, s94, s8
	s_cselect_b32 s41, s5, s97
	s_cselect_b32 s40, s95, s96
	s_add_i32 m0, s47, 0xc000
	ds_read_b128 v[190:193], v176
	ds_read_b128 v[194:197], v176 offset:1024
	ds_read_b128 v[198:201], v176 offset:2048
	ds_read_b128 v[202:205], v176 offset:3072
	ds_read_b128 v[206:209], v176 offset:4096
	ds_read_b128 v[210:213], v176 offset:5120
	ds_read_b128 v[214:217], v176 offset:6144
	ds_read_b128 v[218:221], v176 offset:7168
	global_load_lds_dwordx4 v158, s[0:1]
	s_add_i32 m0, s47, 0xe000
	s_nop 0
	global_load_lds_dwordx4 v160, s[0:1]
	s_waitcnt vmcnt(8)
	s_waitcnt lgkmcnt(0)
	s_barrier
	s_setprio 1
	v_mfma_f32_16x16x32_bf16 v[124:127], v[128:131], v[190:193], 0
	v_mfma_f32_16x16x32_bf16 v[120:123], v[136:139], v[190:193], 0
	v_mfma_f32_16x16x32_bf16 v[108:111], v[128:131], v[198:201], 0
	v_mfma_f32_16x16x32_bf16 v[104:107], v[136:139], v[198:201], 0
	v_mfma_f32_16x16x32_bf16 v[92:95], v[128:131], v[206:209], 0
	v_mfma_f32_16x16x32_bf16 v[88:91], v[136:139], v[206:209], 0
	v_mfma_f32_16x16x32_bf16 v[76:79], v[128:131], v[214:217], 0
	v_mfma_f32_16x16x32_bf16 v[72:75], v[136:139], v[214:217], 0
	v_mfma_f32_16x16x32_bf16 v[124:127], v[132:135], v[194:197], v[124:127]
	v_mfma_f32_16x16x32_bf16 v[120:123], v[140:143], v[194:197], v[120:123]
	v_mfma_f32_16x16x32_bf16 v[108:111], v[132:135], v[202:205], v[108:111]
	v_mfma_f32_16x16x32_bf16 v[104:107], v[140:143], v[202:205], v[104:107]
	v_mfma_f32_16x16x32_bf16 v[92:95], v[132:135], v[210:213], v[92:95]
	v_mfma_f32_16x16x32_bf16 v[88:91], v[140:143], v[210:213], v[88:91]
	v_mfma_f32_16x16x32_bf16 v[76:79], v[132:135], v[218:221], v[76:79]
	v_mfma_f32_16x16x32_bf16 v[72:75], v[140:143], v[218:221], v[72:75]
	v_mfma_f32_16x16x32_bf16 v[116:119], v[162:165], v[190:193], 0
	v_mfma_f32_16x16x32_bf16 v[112:115], v[180:183], v[190:193], 0
	v_mfma_f32_16x16x32_bf16 v[100:103], v[162:165], v[198:201], 0
	v_mfma_f32_16x16x32_bf16 v[96:99], v[180:183], v[198:201], 0
	v_mfma_f32_16x16x32_bf16 v[84:87], v[162:165], v[206:209], 0
	v_mfma_f32_16x16x32_bf16 v[80:83], v[180:183], v[206:209], 0
	v_mfma_f32_16x16x32_bf16 v[68:71], v[162:165], v[214:217], 0
	v_mfma_f32_16x16x32_bf16 v[64:67], v[180:183], v[214:217], 0
	v_mfma_f32_16x16x32_bf16 v[116:119], v[166:169], v[194:197], v[116:119]
	v_mfma_f32_16x16x32_bf16 v[112:115], v[184:187], v[194:197], v[112:115]
	v_mfma_f32_16x16x32_bf16 v[100:103], v[166:169], v[202:205], v[100:103]
	v_mfma_f32_16x16x32_bf16 v[96:99], v[184:187], v[202:205], v[96:99]
	v_mfma_f32_16x16x32_bf16 v[84:87], v[166:169], v[210:213], v[84:87]
	v_mfma_f32_16x16x32_bf16 v[80:83], v[184:187], v[210:213], v[80:83]
	v_mfma_f32_16x16x32_bf16 v[68:71], v[166:169], v[218:221], v[68:71]
	v_mfma_f32_16x16x32_bf16 v[64:67], v[184:187], v[218:221], v[64:67]
	s_setprio 0
	s_barrier
	s_add_u32 s98, s40, s14
	s_addc_u32 s99, s41, s15
	s_add_u32 s100, s42, s14
	s_addc_u32 s101, s43, s15
	s_add_i32 s8, s76, s46
	s_mov_b32 m0, s8
	s_nop 0
	global_load_lds_dwordx4 v146, s[40:41]
	s_add_i32 m0, s8, 0x2000
	s_add_u32 s8, s40, 0x40000
	s_addc_u32 s9, s41, 0
	s_add_i32 s54, s77, s46
	global_load_lds_dwordx4 v150, s[40:41]
	s_mov_b32 m0, s54
	s_nop 0
	global_load_lds_dwordx4 v146, s[8:9]
	s_add_i32 m0, s54, 0x2000
	s_nop 0
	global_load_lds_dwordx4 v150, s[8:9]
	s_mov_b32 m0, s47
	s_nop 0
	global_load_lds_dwordx4 v144, s[42:43]
	s_mov_b32 m0, s48
	s_nop 0
	global_load_lds_dwordx4 v148, s[42:43]
	ds_read_b128 v[190:193], v176 offset:16384
	ds_read_b128 v[194:197], v176 offset:17408
	ds_read_b128 v[198:201], v176 offset:18432
	ds_read_b128 v[202:205], v176 offset:19456
	ds_read_b128 v[206:209], v176 offset:20480
	ds_read_b128 v[210:213], v176 offset:21504
	ds_read_b128 v[214:217], v176 offset:22528
	ds_read_b128 v[218:221], v176 offset:23552
	s_waitcnt vmcnt(8)
	s_waitcnt lgkmcnt(0)
	s_barrier
	s_setprio 1
	v_mfma_f32_16x16x32_bf16 v[60:63], v[128:131], v[190:193], 0
	v_mfma_f32_16x16x32_bf16 v[56:59], v[136:139], v[190:193], 0
	v_mfma_f32_16x16x32_bf16 v[44:47], v[128:131], v[198:201], 0
	v_mfma_f32_16x16x32_bf16 v[40:43], v[136:139], v[198:201], 0
	v_mfma_f32_16x16x32_bf16 v[28:31], v[128:131], v[206:209], 0
	v_mfma_f32_16x16x32_bf16 v[24:27], v[136:139], v[206:209], 0
	v_mfma_f32_16x16x32_bf16 v[12:15], v[128:131], v[214:217], 0
	v_mfma_f32_16x16x32_bf16 v[8:11], v[136:139], v[214:217], 0
	v_mfma_f32_16x16x32_bf16 v[60:63], v[132:135], v[194:197], v[60:63]
	v_mfma_f32_16x16x32_bf16 v[56:59], v[140:143], v[194:197], v[56:59]
	v_mfma_f32_16x16x32_bf16 v[44:47], v[132:135], v[202:205], v[44:47]
	v_mfma_f32_16x16x32_bf16 v[40:43], v[140:143], v[202:205], v[40:43]
	v_mfma_f32_16x16x32_bf16 v[28:31], v[132:135], v[210:213], v[28:31]
	v_mfma_f32_16x16x32_bf16 v[24:27], v[140:143], v[210:213], v[24:27]
	v_mfma_f32_16x16x32_bf16 v[12:15], v[132:135], v[218:221], v[12:15]
	v_mfma_f32_16x16x32_bf16 v[8:11], v[140:143], v[218:221], v[8:11]
	v_mfma_f32_16x16x32_bf16 v[52:55], v[162:165], v[190:193], 0
	v_mfma_f32_16x16x32_bf16 v[48:51], v[180:183], v[190:193], 0
	v_mfma_f32_16x16x32_bf16 v[36:39], v[162:165], v[198:201], 0
	v_mfma_f32_16x16x32_bf16 v[32:35], v[180:183], v[198:201], 0
	v_mfma_f32_16x16x32_bf16 v[20:23], v[162:165], v[206:209], 0
	v_mfma_f32_16x16x32_bf16 v[16:19], v[180:183], v[206:209], 0
	v_mfma_f32_16x16x32_bf16 v[4:7], v[162:165], v[214:217], 0
	v_mfma_f32_16x16x32_bf16 v[0:3], v[180:183], v[214:217], 0
	v_mfma_f32_16x16x32_bf16 v[52:55], v[166:169], v[194:197], v[52:55]
	v_mfma_f32_16x16x32_bf16 v[48:51], v[184:187], v[194:197], v[48:51]
	v_mfma_f32_16x16x32_bf16 v[36:39], v[166:169], v[202:205], v[36:39]
	v_mfma_f32_16x16x32_bf16 v[32:35], v[184:187], v[202:205], v[32:35]
	v_mfma_f32_16x16x32_bf16 v[20:23], v[166:169], v[210:213], v[20:23]
	v_mfma_f32_16x16x32_bf16 v[16:19], v[184:187], v[210:213], v[16:19]
	v_mfma_f32_16x16x32_bf16 v[4:7], v[166:169], v[218:221], v[4:7]
	v_mfma_f32_16x16x32_bf16 v[0:3], v[184:187], v[218:221], v[0:3]
	s_setprio 0
	s_barrier
	s_branch .Lmy_peel_684_mid
; #define PG8_STAGE(bufoff, gbase, voff) do { _Pragma("unroll") for (int _i = 0; _i < 2; ++_i) \
;         __builtin_amdgcn_global_load_lds((const unsigned*)((const char*)(gbase) + (voff)[_i]), (PG8_LAS unsigned*)(lds + (bufoff) + ldsw + _i * 8192), 16, 0, 0); } while (0)
; #define PG8_LDA(dst, b, h) do { _Pragma("unroll") for (int m = 0; m < 4; ++m) _Pragma("unroll") for (int k = 0; k < 2; ++k) dst[m][k] = *(const PG8_LAS bf16x8*)(lds + PG8_SA(b, h) + aoff + m * 2048 + k * 1024); } while (0)
; #define PG8_LDB(dst, b, h) do { _Pragma("unroll") for (int n = 0; n < 2; ++n) _Pragma("unroll") for (int k = 0; k < 2; ++k) dst[n][k] = *(const PG8_LAS bf16x8*)(lds + PG8_SB(b, h) + boff + n * 2048 + k * 1024); } while (0)
; #define PG8_MMA(ai, bj, At, Bt) do { __builtin_amdgcn_s_setprio(1); _Pragma("unroll") for (int m = 0; m < 4; ++m) _Pragma("unroll") for (int n = 0; n < 2; ++n) _Pragma("unroll") for (int k = 0; k < 2; ++k) \
;         acc[ai][bj][m][n] = __builtin_amdgcn_mfma_f32_16x16x32_bf16(Bt[n][k], At[m][k], acc[ai][bj][m][n], 0, 0, 0); __builtin_amdgcn_s_setprio(0); } while (0)
; #define PG8_WAIT_V(n) asm volatile("s_waitcnt vmcnt(" #n ")" ::: "memory")
; #define PG8_WAIT_L(n) asm volatile("s_waitcnt lgkmcnt(" #n ")" ::: "memory")
; #define PG8_BAR __builtin_amdgcn_s_barrier()
; #define PG8_SCHED __builtin_amdgcn_sched_barrier(0)
; template <class Epi, class Sched, bool ALIGN_EPI = false, bool SP2 = false>
; __device__ __forceinline__ void gemm_phase(PG8_LAS unsigned char* lds, const Gemm g, const Sched& S, const Epi& E) {
;     ...
;             PG8_LDB(B0, 0, 0); PG8_LDB(B1, 0, 1); PG8_SCHED; PG8_LDA(At, 0, 0); PG8_STAGE(PG8_SA(1, 1), a1 + hstep, voffA);
;             PG8_WAIT_V(8); PG8_WAIT_L(0); PG8_BAR; PG8_MMA(0, 0, At, B0); PG8_MMA(0, 1, At, B1); PG8_BAR; PG8_SCHED;
;             PG8_LDA(At, 0, 1); PG8_STAGE(PG8_SB(0, 0), b2, voffB); PG8_STAGE(PG8_SB(0, 1), b2 + hstep, voffB); PG8_STAGE(PG8_SA(0, 0), a2, voffA);
;             PG8_WAIT_V(8); PG8_WAIT_L(0); PG8_BAR; PG8_MMA(1, 0, At, B0); PG8_MMA(1, 1, At, B1); PG8_BAR; PG8_SCHED;
.LBB0_684:
	ds_read_b128 v[128:131], v174
	ds_read_b128 v[132:135], v174 offset:1024
	ds_read_b128 v[136:139], v174 offset:2048
	ds_read_b128 v[140:143], v174 offset:3072
	ds_read_b128 v[162:165], v175
	ds_read_b128 v[166:169], v175 offset:1024
	ds_read_b128 v[180:183], v175 offset:2048
	ds_read_b128 v[184:187], v175 offset:3072
	s_add_u32 s8, s0, 0xfffc0080
	s_addc_u32 s9, s1, -1
	s_cmp_eq_u32 vcc_lo, 12
	s_cselect_b32 s43, s3, s9
	s_cselect_b32 s42, s94, s8
	s_cselect_b32 s41, s5, s97
	s_cselect_b32 s40, s95, s96
	s_add_i32 m0, s47, 0xc000
	ds_read_b128 v[190:193], v176
	ds_read_b128 v[194:197], v176 offset:1024
	ds_read_b128 v[198:201], v176 offset:2048
	ds_read_b128 v[202:205], v176 offset:3072
	ds_read_b128 v[206:209], v176 offset:4096
	ds_read_b128 v[210:213], v176 offset:5120
	ds_read_b128 v[214:217], v176 offset:6144
	ds_read_b128 v[218:221], v176 offset:7168
	global_load_lds_dwordx4 v158, s[0:1]
	s_add_i32 m0, s47, 0xe000
	s_nop 0
	global_load_lds_dwordx4 v160, s[0:1]
	s_waitcnt vmcnt(8)
	s_waitcnt lgkmcnt(0)
	s_barrier
	s_setprio 1
	v_mfma_f32_16x16x32_bf16 v[124:127], v[128:131], v[190:193], v[124:127]
	v_mfma_f32_16x16x32_bf16 v[120:123], v[136:139], v[190:193], v[120:123]
	v_mfma_f32_16x16x32_bf16 v[108:111], v[128:131], v[198:201], v[108:111]
	v_mfma_f32_16x16x32_bf16 v[104:107], v[136:139], v[198:201], v[104:107]
	v_mfma_f32_16x16x32_bf16 v[92:95], v[128:131], v[206:209], v[92:95]
	v_mfma_f32_16x16x32_bf16 v[88:91], v[136:139], v[206:209], v[88:91]
	v_mfma_f32_16x16x32_bf16 v[76:79], v[128:131], v[214:217], v[76:79]
	v_mfma_f32_16x16x32_bf16 v[72:75], v[136:139], v[214:217], v[72:75]
	v_mfma_f32_16x16x32_bf16 v[124:127], v[132:135], v[194:197], v[124:127]
	v_mfma_f32_16x16x32_bf16 v[120:123], v[140:143], v[194:197], v[120:123]
	v_mfma_f32_16x16x32_bf16 v[108:111], v[132:135], v[202:205], v[108:111]
	v_mfma_f32_16x16x32_bf16 v[104:107], v[140:143], v[202:205], v[104:107]
	v_mfma_f32_16x16x32_bf16 v[92:95], v[132:135], v[210:213], v[92:95]
	v_mfma_f32_16x16x32_bf16 v[88:91], v[140:143], v[210:213], v[88:91]
	v_mfma_f32_16x16x32_bf16 v[76:79], v[132:135], v[218:221], v[76:79]
	v_mfma_f32_16x16x32_bf16 v[72:75], v[140:143], v[218:221], v[72:75]
	v_mfma_f32_16x16x32_bf16 v[116:119], v[162:165], v[190:193], v[116:119]
	v_mfma_f32_16x16x32_bf16 v[112:115], v[180:183], v[190:193], v[112:115]
	v_mfma_f32_16x16x32_bf16 v[100:103], v[162:165], v[198:201], v[100:103]
	v_mfma_f32_16x16x32_bf16 v[96:99], v[180:183], v[198:201], v[96:99]
	v_mfma_f32_16x16x32_bf16 v[84:87], v[162:165], v[206:209], v[84:87]
	v_mfma_f32_16x16x32_bf16 v[80:83], v[180:183], v[206:209], v[80:83]
	v_mfma_f32_16x16x32_bf16 v[68:71], v[162:165], v[214:217], v[68:71]
	v_mfma_f32_16x16x32_bf16 v[64:67], v[180:183], v[214:217], v[64:67]
	v_mfma_f32_16x16x32_bf16 v[116:119], v[166:169], v[194:197], v[116:119]
	v_mfma_f32_16x16x32_bf16 v[112:115], v[184:187], v[194:197], v[112:115]
	v_mfma_f32_16x16x32_bf16 v[100:103], v[166:169], v[202:205], v[100:103]
	v_mfma_f32_16x16x32_bf16 v[96:99], v[184:187], v[202:205], v[96:99]
	v_mfma_f32_16x16x32_bf16 v[84:87], v[166:169], v[210:213], v[84:87]
	v_mfma_f32_16x16x32_bf16 v[80:83], v[184:187], v[210:213], v[80:83]
	v_mfma_f32_16x16x32_bf16 v[68:71], v[166:169], v[218:221], v[68:71]
	v_mfma_f32_16x16x32_bf16 v[64:67], v[184:187], v[218:221], v[64:67]
	s_setprio 0
	s_barrier
	s_add_u32 s98, s40, s14
	s_addc_u32 s99, s41, s15
	s_add_u32 s100, s42, s14
	s_addc_u32 s101, s43, s15
	s_add_i32 s8, s76, s46
	s_mov_b32 m0, s8
	s_nop 0
	global_load_lds_dwordx4 v146, s[40:41]
	s_add_i32 m0, s8, 0x2000
	s_add_u32 s8, s40, 0x40000
	s_addc_u32 s9, s41, 0
	s_add_i32 s54, s77, s46
	global_load_lds_dwordx4 v150, s[40:41]
	s_mov_b32 m0, s54
	s_nop 0
	global_load_lds_dwordx4 v146, s[8:9]
	s_add_i32 m0, s54, 0x2000
	s_nop 0
	global_load_lds_dwordx4 v150, s[8:9]
	s_mov_b32 m0, s47
	s_nop 0
	global_load_lds_dwordx4 v144, s[42:43]
	s_mov_b32 m0, s48
	s_nop 0
	global_load_lds_dwordx4 v148, s[42:43]
	ds_read_b128 v[190:193], v176 offset:16384
	ds_read_b128 v[194:197], v176 offset:17408
	ds_read_b128 v[198:201], v176 offset:18432
	ds_read_b128 v[202:205], v176 offset:19456
	ds_read_b128 v[206:209], v176 offset:20480
	ds_read_b128 v[210:213], v176 offset:21504
	ds_read_b128 v[214:217], v176 offset:22528
	ds_read_b128 v[218:221], v176 offset:23552
	s_waitcnt vmcnt(8)
	s_waitcnt lgkmcnt(0)
	s_barrier
	s_setprio 1
	v_mfma_f32_16x16x32_bf16 v[60:63], v[128:131], v[190:193], v[60:63]
	v_mfma_f32_16x16x32_bf16 v[56:59], v[136:139], v[190:193], v[56:59]
	v_mfma_f32_16x16x32_bf16 v[44:47], v[128:131], v[198:201], v[44:47]
	v_mfma_f32_16x16x32_bf16 v[40:43], v[136:139], v[198:201], v[40:43]
	v_mfma_f32_16x16x32_bf16 v[28:31], v[128:131], v[206:209], v[28:31]
	v_mfma_f32_16x16x32_bf16 v[24:27], v[136:139], v[206:209], v[24:27]
	v_mfma_f32_16x16x32_bf16 v[12:15], v[128:131], v[214:217], v[12:15]
	v_mfma_f32_16x16x32_bf16 v[8:11], v[136:139], v[214:217], v[8:11]
	v_mfma_f32_16x16x32_bf16 v[60:63], v[132:135], v[194:197], v[60:63]
	v_mfma_f32_16x16x32_bf16 v[56:59], v[140:143], v[194:197], v[56:59]
	v_mfma_f32_16x16x32_bf16 v[44:47], v[132:135], v[202:205], v[44:47]
	v_mfma_f32_16x16x32_bf16 v[40:43], v[140:143], v[202:205], v[40:43]
	v_mfma_f32_16x16x32_bf16 v[28:31], v[132:135], v[210:213], v[28:31]
	v_mfma_f32_16x16x32_bf16 v[24:27], v[140:143], v[210:213], v[24:27]
	v_mfma_f32_16x16x32_bf16 v[12:15], v[132:135], v[218:221], v[12:15]
	v_mfma_f32_16x16x32_bf16 v[8:11], v[140:143], v[218:221], v[8:11]
	v_mfma_f32_16x16x32_bf16 v[52:55], v[162:165], v[190:193], v[52:55]
	v_mfma_f32_16x16x32_bf16 v[48:51], v[180:183], v[190:193], v[48:51]
	v_mfma_f32_16x16x32_bf16 v[36:39], v[162:165], v[198:201], v[36:39]
	v_mfma_f32_16x16x32_bf16 v[32:35], v[180:183], v[198:201], v[32:35]
	v_mfma_f32_16x16x32_bf16 v[20:23], v[162:165], v[206:209], v[20:23]
	v_mfma_f32_16x16x32_bf16 v[16:19], v[180:183], v[206:209], v[16:19]
	v_mfma_f32_16x16x32_bf16 v[4:7], v[162:165], v[214:217], v[4:7]
	v_mfma_f32_16x16x32_bf16 v[0:3], v[180:183], v[214:217], v[0:3]
	v_mfma_f32_16x16x32_bf16 v[52:55], v[166:169], v[194:197], v[52:55]
	v_mfma_f32_16x16x32_bf16 v[48:51], v[184:187], v[194:197], v[48:51]
	v_mfma_f32_16x16x32_bf16 v[36:39], v[166:169], v[202:205], v[36:39]
	v_mfma_f32_16x16x32_bf16 v[32:35], v[184:187], v[202:205], v[32:35]
	v_mfma_f32_16x16x32_bf16 v[20:23], v[166:169], v[210:213], v[20:23]
	v_mfma_f32_16x16x32_bf16 v[16:19], v[184:187], v[210:213], v[16:19]
	v_mfma_f32_16x16x32_bf16 v[4:7], v[166:169], v[218:221], v[4:7]
	v_mfma_f32_16x16x32_bf16 v[0:3], v[184:187], v[218:221], v[0:3]
	s_setprio 0
	s_barrier
; #define PG8_STAGE(bufoff, gbase, voff) do { _Pragma("unroll") for (int _i = 0; _i < 2; ++_i) \
;         __builtin_amdgcn_global_load_lds((const unsigned*)((const char*)(gbase) + (voff)[_i]), (PG8_LAS unsigned*)(lds + (bufoff) + ldsw + _i * 8192), 16, 0, 0); } while (0)
; #define PG8_LDA(dst, b, h) do { _Pragma("unroll") for (int m = 0; m < 4; ++m) _Pragma("unroll") for (int k = 0; k < 2; ++k) dst[m][k] = *(const PG8_LAS bf16x8*)(lds + PG8_SA(b, h) + aoff + m * 2048 + k * 1024); } while (0)
; #define PG8_LDB(dst, b, h) do { _Pragma("unroll") for (int n = 0; n < 2; ++n) _Pragma("unroll") for (int k = 0; k < 2; ++k) dst[n][k] = *(const PG8_LAS bf16x8*)(lds + PG8_SB(b, h) + boff + n * 2048 + k * 1024); } while (0)
; #define PG8_MMA(ai, bj, At, Bt) do { __builtin_amdgcn_s_setprio(1); _Pragma("unroll") for (int m = 0; m < 4; ++m) _Pragma("unroll") for (int n = 0; n < 2; ++n) _Pragma("unroll") for (int k = 0; k < 2; ++k) \
;         acc[ai][bj][m][n] = __builtin_amdgcn_mfma_f32_16x16x32_bf16(Bt[n][k], At[m][k], acc[ai][bj][m][n], 0, 0, 0); __builtin_amdgcn_s_setprio(0); } while (0)
; #define PG8_WAIT_V(n) asm volatile("s_waitcnt vmcnt(" #n ")" ::: "memory")
; #define PG8_WAIT_L(n) asm volatile("s_waitcnt lgkmcnt(" #n ")" ::: "memory")
; #define PG8_BAR __builtin_amdgcn_s_barrier()
; #define PG8_SCHED __builtin_amdgcn_sched_barrier(0)
; template <class Epi, class Sched, bool ALIGN_EPI = false, bool SP2 = false>
; __device__ __forceinline__ void gemm_phase(PG8_LAS unsigned char* lds, const Gemm g, const Sched& S, const Epi& E) {
;     ...
;             PG8_LDB(B0, 1, 0); PG8_LDB(B1, 1, 1); PG8_SCHED; PG8_LDA(At, 1, 0); PG8_STAGE(PG8_SA(0, 1), a2 + hstep, voffA);
;             PG8_WAIT_V(8); PG8_WAIT_L(0); PG8_BAR; PG8_MMA(0, 0, At, B0); PG8_MMA(0, 1, At, B1); PG8_BAR; PG8_SCHED;
;             PG8_LDA(At, 1, 1); PG8_STAGE(PG8_SB(1, 0), b3, voffB); PG8_STAGE(PG8_SB(1, 1), b3 + hstep, voffB); PG8_STAGE(PG8_SA(1, 0), a3, voffA);
;             PG8_WAIT_V(8); PG8_WAIT_L(0); PG8_BAR; PG8_MMA(1, 0, At, B0); PG8_MMA(1, 1, At, B1); PG8_BAR; PG8_SCHED;
;     ...
;         if constexpr (ALIGN_EPI) { if (wr == 0) PG8_BAR; }
.Lmy_peel_684_mid:
	s_add_i32 s54, 0, 0x18000
	s_add_i32 s55, 0, 0x1c000
	v_add_u32_e32 v140, s54, v172
	v_add_u32_e32 v152, s55, v172
	ds_read_b128 v[128:131], v140
	ds_read_b128 v[132:135], v140 offset:1024
	ds_read_b128 v[136:139], v140 offset:2048
	ds_read_b128 v[140:143], v140 offset:3072
	ds_read_b128 v[162:165], v152
	ds_read_b128 v[166:169], v152 offset:1024
	ds_read_b128 v[180:183], v152 offset:2048
	ds_read_b128 v[184:187], v152 offset:3072
	s_add_u32 s8, s42, 0x40000
	s_addc_u32 s9, s43, 0
	s_mov_b32 m0, s49
	ds_read_b128 v[190:193], v176 offset:32768
	ds_read_b128 v[194:197], v176 offset:33792
	ds_read_b128 v[198:201], v176 offset:34816
	ds_read_b128 v[202:205], v176 offset:35840
	ds_read_b128 v[206:209], v176 offset:36864
	ds_read_b128 v[210:213], v176 offset:37888
	ds_read_b128 v[214:217], v176 offset:38912
	ds_read_b128 v[218:221], v176 offset:39936
	global_load_lds_dwordx4 v144, s[8:9]
	s_mov_b32 m0, s51
	s_nop 0
	global_load_lds_dwordx4 v148, s[8:9]
	s_waitcnt vmcnt(8)
	s_waitcnt lgkmcnt(0)
	s_barrier
	s_setprio 1
	v_mfma_f32_16x16x32_bf16 v[124:127], v[128:131], v[190:193], v[124:127]
	v_mfma_f32_16x16x32_bf16 v[120:123], v[136:139], v[190:193], v[120:123]
	v_mfma_f32_16x16x32_bf16 v[108:111], v[128:131], v[198:201], v[108:111]
	v_mfma_f32_16x16x32_bf16 v[104:107], v[136:139], v[198:201], v[104:107]
	v_mfma_f32_16x16x32_bf16 v[92:95], v[128:131], v[206:209], v[92:95]
	v_mfma_f32_16x16x32_bf16 v[88:91], v[136:139], v[206:209], v[88:91]
	v_mfma_f32_16x16x32_bf16 v[76:79], v[128:131], v[214:217], v[76:79]
	v_mfma_f32_16x16x32_bf16 v[72:75], v[136:139], v[214:217], v[72:75]
	v_mfma_f32_16x16x32_bf16 v[124:127], v[132:135], v[194:197], v[124:127]
	v_mfma_f32_16x16x32_bf16 v[120:123], v[140:143], v[194:197], v[120:123]
	v_mfma_f32_16x16x32_bf16 v[108:111], v[132:135], v[202:205], v[108:111]
	v_mfma_f32_16x16x32_bf16 v[104:107], v[140:143], v[202:205], v[104:107]
	v_mfma_f32_16x16x32_bf16 v[92:95], v[132:135], v[210:213], v[92:95]
	v_mfma_f32_16x16x32_bf16 v[88:91], v[140:143], v[210:213], v[88:91]
	v_mfma_f32_16x16x32_bf16 v[76:79], v[132:135], v[218:221], v[76:79]
	v_mfma_f32_16x16x32_bf16 v[72:75], v[140:143], v[218:221], v[72:75]
	v_mfma_f32_16x16x32_bf16 v[116:119], v[162:165], v[190:193], v[116:119]
	v_mfma_f32_16x16x32_bf16 v[112:115], v[180:183], v[190:193], v[112:115]
	v_mfma_f32_16x16x32_bf16 v[100:103], v[162:165], v[198:201], v[100:103]
	v_mfma_f32_16x16x32_bf16 v[96:99], v[180:183], v[198:201], v[96:99]
	v_mfma_f32_16x16x32_bf16 v[84:87], v[162:165], v[206:209], v[84:87]
	v_mfma_f32_16x16x32_bf16 v[80:83], v[180:183], v[206:209], v[80:83]
	v_mfma_f32_16x16x32_bf16 v[68:71], v[162:165], v[214:217], v[68:71]
	v_mfma_f32_16x16x32_bf16 v[64:67], v[180:183], v[214:217], v[64:67]
	v_mfma_f32_16x16x32_bf16 v[116:119], v[166:169], v[194:197], v[116:119]
	v_mfma_f32_16x16x32_bf16 v[112:115], v[184:187], v[194:197], v[112:115]
	v_mfma_f32_16x16x32_bf16 v[100:103], v[166:169], v[202:205], v[100:103]
	v_mfma_f32_16x16x32_bf16 v[96:99], v[184:187], v[202:205], v[96:99]
	v_mfma_f32_16x16x32_bf16 v[84:87], v[166:169], v[210:213], v[84:87]
	v_mfma_f32_16x16x32_bf16 v[80:83], v[184:187], v[210:213], v[80:83]
	v_mfma_f32_16x16x32_bf16 v[68:71], v[166:169], v[218:221], v[68:71]
	v_mfma_f32_16x16x32_bf16 v[64:67], v[184:187], v[218:221], v[64:67]
	s_setprio 0
	s_barrier
	s_add_i32 s8, s54, s46
	s_mov_b32 m0, s8
	s_nop 0
	global_load_lds_dwordx4 v146, s[98:99]
	s_add_i32 m0, s8, 0x2000
	s_add_u32 s8, s40, 0x40080
	s_addc_u32 s9, s41, 0
	s_add_i32 s40, s55, s46
	global_load_lds_dwordx4 v150, s[98:99]
	s_mov_b32 m0, s40
	s_nop 0
	global_load_lds_dwordx4 v146, s[8:9]
	s_add_i32 m0, s40, 0x2000
	s_nop 0
	global_load_lds_dwordx4 v150, s[8:9]
	s_mov_b32 m0, s66
	s_nop 0
	global_load_lds_dwordx4 v144, s[100:101]
	s_mov_b32 m0, s67
	s_nop 0
	global_load_lds_dwordx4 v148, s[100:101]
	ds_read_b128 v[190:193], v176 offset:49152
	ds_read_b128 v[194:197], v176 offset:50176
	ds_read_b128 v[198:201], v176 offset:51200
	ds_read_b128 v[202:205], v176 offset:52224
	ds_read_b128 v[206:209], v176 offset:53248
	ds_read_b128 v[210:213], v176 offset:54272
	ds_read_b128 v[214:217], v176 offset:55296
	ds_read_b128 v[218:221], v176 offset:56320
	s_waitcnt vmcnt(8)
	s_waitcnt lgkmcnt(0)
	s_barrier
	s_setprio 1
	v_mfma_f32_16x16x32_bf16 v[60:63], v[128:131], v[190:193], v[60:63]
	v_mfma_f32_16x16x32_bf16 v[56:59], v[136:139], v[190:193], v[56:59]
	v_mfma_f32_16x16x32_bf16 v[44:47], v[128:131], v[198:201], v[44:47]
	v_mfma_f32_16x16x32_bf16 v[40:43], v[136:139], v[198:201], v[40:43]
	v_mfma_f32_16x16x32_bf16 v[28:31], v[128:131], v[206:209], v[28:31]
	v_mfma_f32_16x16x32_bf16 v[24:27], v[136:139], v[206:209], v[24:27]
	v_mfma_f32_16x16x32_bf16 v[12:15], v[128:131], v[214:217], v[12:15]
	v_mfma_f32_16x16x32_bf16 v[8:11], v[136:139], v[214:217], v[8:11]
	v_mfma_f32_16x16x32_bf16 v[60:63], v[132:135], v[194:197], v[60:63]
	v_mfma_f32_16x16x32_bf16 v[56:59], v[140:143], v[194:197], v[56:59]
	v_mfma_f32_16x16x32_bf16 v[44:47], v[132:135], v[202:205], v[44:47]
	v_mfma_f32_16x16x32_bf16 v[40:43], v[140:143], v[202:205], v[40:43]
	v_mfma_f32_16x16x32_bf16 v[28:31], v[132:135], v[210:213], v[28:31]
	v_mfma_f32_16x16x32_bf16 v[24:27], v[140:143], v[210:213], v[24:27]
	v_mfma_f32_16x16x32_bf16 v[12:15], v[132:135], v[218:221], v[12:15]
	v_mfma_f32_16x16x32_bf16 v[8:11], v[140:143], v[218:221], v[8:11]
	v_mfma_f32_16x16x32_bf16 v[52:55], v[162:165], v[190:193], v[52:55]
	v_mfma_f32_16x16x32_bf16 v[48:51], v[180:183], v[190:193], v[48:51]
	v_mfma_f32_16x16x32_bf16 v[36:39], v[162:165], v[198:201], v[36:39]
	v_mfma_f32_16x16x32_bf16 v[32:35], v[180:183], v[198:201], v[32:35]
	v_mfma_f32_16x16x32_bf16 v[20:23], v[162:165], v[206:209], v[20:23]
	v_mfma_f32_16x16x32_bf16 v[16:19], v[180:183], v[206:209], v[16:19]
	v_mfma_f32_16x16x32_bf16 v[4:7], v[162:165], v[214:217], v[4:7]
	v_mfma_f32_16x16x32_bf16 v[0:3], v[180:183], v[214:217], v[0:3]
	v_mfma_f32_16x16x32_bf16 v[52:55], v[166:169], v[194:197], v[52:55]
	v_mfma_f32_16x16x32_bf16 v[48:51], v[184:187], v[194:197], v[48:51]
	v_mfma_f32_16x16x32_bf16 v[36:39], v[166:169], v[202:205], v[36:39]
	v_mfma_f32_16x16x32_bf16 v[32:35], v[184:187], v[202:205], v[32:35]
	v_mfma_f32_16x16x32_bf16 v[20:23], v[166:169], v[210:213], v[20:23]
	v_mfma_f32_16x16x32_bf16 v[16:19], v[184:187], v[210:213], v[16:19]
	v_mfma_f32_16x16x32_bf16 v[4:7], v[166:169], v[218:221], v[4:7]
	v_mfma_f32_16x16x32_bf16 v[0:3], v[184:187], v[218:221], v[0:3]
	s_setprio 0
	s_barrier
	s_add_i32 vcc_lo, vcc_lo, 2
	s_add_u32 s0, s0, 0x100
	s_addc_u32 s1, s1, 0
	s_add_u32 s96, s96, 0x100
	s_addc_u32 s97, s97, 0
	s_cmp_gt_u32 vcc_lo, 13
	s_cbranch_scc0 .LBB0_684
	s_and_b64 vcc, exec, s[18:19]
	s_cbranch_vccz .LBB0_687
	s_barrier

; #define PG8_STAGE(bufoff, gbase, voff) do { _Pragma("unroll") for (int _i = 0; _i < 2; ++_i) \
;         __builtin_amdgcn_global_load_lds((const unsigned*)((const char*)(gbase) + (voff)[_i]), (PG8_LAS unsigned*)(lds + (bufoff) + ldsw + _i * 8192), 16, 0, 0); } while (0)
; #define PG8_LDA(dst, b, h) do { _Pragma("unroll") for (int m = 0; m < 4; ++m) _Pragma("unroll") for (int k = 0; k < 2; ++k) dst[m][k] = *(const PG8_LAS bf16x8*)(lds + PG8_SA(b, h) + aoff + m * 2048 + k * 1024); } while (0)
; #define PG8_LDB(dst, b, h) do { _Pragma("unroll") for (int n = 0; n < 2; ++n) _Pragma("unroll") for (int k = 0; k < 2; ++k) dst[n][k] = *(const PG8_LAS bf16x8*)(lds + PG8_SB(b, h) + boff + n * 2048 + k * 1024); } while (0)
; #define PG8_MMA(ai, bj, At, Bt) do { __builtin_amdgcn_s_setprio(1); _Pragma("unroll") for (int m = 0; m < 4; ++m) _Pragma("unroll") for (int n = 0; n < 2; ++n) _Pragma("unroll") for (int k = 0; k < 2; ++k) \
;         acc[ai][bj][m][n] = __builtin_amdgcn_mfma_f32_16x16x32_bf16(Bt[n][k], At[m][k], acc[ai][bj][m][n], 0, 0, 0); __builtin_amdgcn_s_setprio(0); } while (0)
; #define PG8_WAIT_V(n) asm volatile("s_waitcnt vmcnt(" #n ")" ::: "memory")
; #define PG8_WAIT_L(n) asm volatile("s_waitcnt lgkmcnt(" #n ")" ::: "memory")
; #define PG8_BAR __builtin_amdgcn_s_barrier()
; #define PG8_SCHED __builtin_amdgcn_sched_barrier(0)
; template <class Epi, class Sched, bool ALIGN_EPI = false, bool SP2 = false>
; __device__ __forceinline__ void gemm_phase(PG8_LAS unsigned char* lds, const Gemm g, const Sched& S, const Epi& E) {
;     ...
;             PG8_LDB(B0, 0, 0); PG8_LDB(B1, 0, 1); PG8_SCHED; PG8_LDA(At, 0, 0); PG8_STAGE(PG8_SA(1, 1), a1 + hstep, voffA);
;             PG8_WAIT_V(8); PG8_WAIT_L(0); PG8_BAR; PG8_MMA(0, 0, At, B0); PG8_MMA(0, 1, At, B1); PG8_BAR; PG8_SCHED;
;             PG8_LDA(At, 0, 1); PG8_STAGE(PG8_SB(0, 0), b2, voffB); PG8_STAGE(PG8_SB(0, 1), b2 + hstep, voffB); PG8_STAGE(PG8_SA(0, 0), a2, voffA);
;             PG8_WAIT_V(8); PG8_WAIT_L(0); PG8_BAR; PG8_MMA(1, 0, At, B0); PG8_MMA(1, 1, At, B1); PG8_BAR; PG8_SCHED;
.LBB0_795:
	v_add_u32_e32 v162, s67, v186
	v_add_u32_e32 v178, s68, v186
	ds_read_b128 v[150:153], v162
	ds_read_b128 v[154:157], v162 offset:1024
	ds_read_b128 v[158:161], v162 offset:2048
	ds_read_b128 v[162:165], v162 offset:3072
	ds_read_b128 v[166:169], v178
	ds_read_b128 v[170:173], v178 offset:1024
	ds_read_b128 v[174:177], v178 offset:2048
	ds_read_b128 v[178:181], v178 offset:3072
	s_add_u32 s54, s46, 0xfff80080
	s_addc_u32 s55, s47, -1
	s_cmp_eq_u32 s82, 12
	s_cselect_b32 s57, s41, s55
	s_cselect_b32 s56, s78, s54
	s_cselect_b32 s55, s39, s81
	s_cselect_b32 s54, s79, s80
	s_add_i32 m0, s61, 0xc000
	ds_read_b128 v[182:185], v187
	ds_read_b128 v[190:193], v187 offset:1024
	ds_read_b128 v[194:197], v187 offset:2048
	ds_read_b128 v[198:201], v187 offset:3072
	ds_read_b128 v[202:205], v187 offset:4096
	ds_read_b128 v[206:209], v187 offset:5120
	ds_read_b128 v[210:213], v187 offset:6144
	ds_read_b128 v[214:217], v187 offset:7168
	global_load_lds_dwordx4 v142, s[46:47]
	s_add_i32 m0, s61, 0xe000
	s_nop 0
	global_load_lds_dwordx4 v144, s[46:47]
	s_waitcnt vmcnt(8)
	s_waitcnt lgkmcnt(0)
	s_barrier
	s_setprio 1
	v_mfma_f32_16x16x32_bf16 v[124:127], v[150:153], v[182:185], v[124:127]
	v_mfma_f32_16x16x32_bf16 v[120:123], v[158:161], v[182:185], v[120:123]
	v_mfma_f32_16x16x32_bf16 v[116:119], v[150:153], v[194:197], v[116:119]
	v_mfma_f32_16x16x32_bf16 v[112:115], v[158:161], v[194:197], v[112:115]
	v_mfma_f32_16x16x32_bf16 v[108:111], v[150:153], v[202:205], v[108:111]
	v_mfma_f32_16x16x32_bf16 v[104:107], v[158:161], v[202:205], v[104:107]
	v_mfma_f32_16x16x32_bf16 v[100:103], v[150:153], v[210:213], v[100:103]
	v_mfma_f32_16x16x32_bf16 v[96:99], v[158:161], v[210:213], v[96:99]
	v_mfma_f32_16x16x32_bf16 v[124:127], v[154:157], v[190:193], v[124:127]
	v_mfma_f32_16x16x32_bf16 v[120:123], v[162:165], v[190:193], v[120:123]
	v_mfma_f32_16x16x32_bf16 v[116:119], v[154:157], v[198:201], v[116:119]
	v_mfma_f32_16x16x32_bf16 v[112:115], v[162:165], v[198:201], v[112:115]
	v_mfma_f32_16x16x32_bf16 v[108:111], v[154:157], v[206:209], v[108:111]
	v_mfma_f32_16x16x32_bf16 v[104:107], v[162:165], v[206:209], v[104:107]
	v_mfma_f32_16x16x32_bf16 v[100:103], v[154:157], v[214:217], v[100:103]
	v_mfma_f32_16x16x32_bf16 v[96:99], v[162:165], v[214:217], v[96:99]
	v_mfma_f32_16x16x32_bf16 v[92:95], v[166:169], v[182:185], v[92:95]
	v_mfma_f32_16x16x32_bf16 v[88:91], v[174:177], v[182:185], v[88:91]
	v_mfma_f32_16x16x32_bf16 v[84:87], v[166:169], v[194:197], v[84:87]
	v_mfma_f32_16x16x32_bf16 v[80:83], v[174:177], v[194:197], v[80:83]
	v_mfma_f32_16x16x32_bf16 v[76:79], v[166:169], v[202:205], v[76:79]
	v_mfma_f32_16x16x32_bf16 v[72:75], v[174:177], v[202:205], v[72:75]
	v_mfma_f32_16x16x32_bf16 v[68:71], v[166:169], v[210:213], v[68:71]
	v_mfma_f32_16x16x32_bf16 v[64:67], v[174:177], v[210:213], v[64:67]
	v_mfma_f32_16x16x32_bf16 v[92:95], v[170:173], v[190:193], v[92:95]
	v_mfma_f32_16x16x32_bf16 v[88:91], v[178:181], v[190:193], v[88:91]
	v_mfma_f32_16x16x32_bf16 v[84:87], v[170:173], v[198:201], v[84:87]
	v_mfma_f32_16x16x32_bf16 v[80:83], v[178:181], v[198:201], v[80:83]
	v_mfma_f32_16x16x32_bf16 v[76:79], v[170:173], v[206:209], v[76:79]
	v_mfma_f32_16x16x32_bf16 v[72:75], v[178:181], v[206:209], v[72:75]
	v_mfma_f32_16x16x32_bf16 v[68:71], v[170:173], v[214:217], v[68:71]
	v_mfma_f32_16x16x32_bf16 v[64:67], v[178:181], v[214:217], v[64:67]
	s_setprio 0
	s_barrier
	s_add_u32 s92, s54, s14
	s_addc_u32 s93, s55, s15
	s_add_u32 s94, s56, s14
	s_addc_u32 s95, s57, s15
	s_add_i32 s83, s67, s60
	s_mov_b32 m0, s83
	s_nop 0
	global_load_lds_dwordx4 v130, s[54:55]
	s_add_i32 m0, s83, 0x2000
	s_add_u32 s86, s54, 0x80000
	s_addc_u32 s87, s55, 0
	s_add_i32 s83, s68, s60
	global_load_lds_dwordx4 v134, s[54:55]
	s_mov_b32 m0, s83
	s_nop 0
	global_load_lds_dwordx4 v130, s[86:87]
	s_add_i32 m0, s83, 0x2000
	s_nop 0
	global_load_lds_dwordx4 v134, s[86:87]
	s_mov_b32 m0, s61
	s_nop 0
	global_load_lds_dwordx4 v128, s[56:57]
	s_mov_b32 m0, s62
	s_nop 0
	global_load_lds_dwordx4 v132, s[56:57]
	ds_read_b128 v[182:185], v187 offset:16384
	ds_read_b128 v[190:193], v187 offset:17408
	ds_read_b128 v[194:197], v187 offset:18432
	ds_read_b128 v[198:201], v187 offset:19456
	ds_read_b128 v[202:205], v187 offset:20480
	ds_read_b128 v[206:209], v187 offset:21504
	ds_read_b128 v[210:213], v187 offset:22528
	ds_read_b128 v[214:217], v187 offset:23552
	s_waitcnt vmcnt(8)
	s_waitcnt lgkmcnt(0)
	s_barrier
	s_setprio 1
	v_mfma_f32_16x16x32_bf16 v[60:63], v[150:153], v[182:185], v[60:63]
	v_mfma_f32_16x16x32_bf16 v[56:59], v[158:161], v[182:185], v[56:59]
	v_mfma_f32_16x16x32_bf16 v[52:55], v[150:153], v[194:197], v[52:55]
	v_mfma_f32_16x16x32_bf16 v[48:51], v[158:161], v[194:197], v[48:51]
	v_mfma_f32_16x16x32_bf16 v[44:47], v[150:153], v[202:205], v[44:47]
	v_mfma_f32_16x16x32_bf16 v[40:43], v[158:161], v[202:205], v[40:43]
	v_mfma_f32_16x16x32_bf16 v[36:39], v[150:153], v[210:213], v[36:39]
	v_mfma_f32_16x16x32_bf16 v[32:35], v[158:161], v[210:213], v[32:35]
	v_mfma_f32_16x16x32_bf16 v[60:63], v[154:157], v[190:193], v[60:63]
	v_mfma_f32_16x16x32_bf16 v[56:59], v[162:165], v[190:193], v[56:59]
	v_mfma_f32_16x16x32_bf16 v[52:55], v[154:157], v[198:201], v[52:55]
	v_mfma_f32_16x16x32_bf16 v[48:51], v[162:165], v[198:201], v[48:51]
	v_mfma_f32_16x16x32_bf16 v[44:47], v[154:157], v[206:209], v[44:47]
	v_mfma_f32_16x16x32_bf16 v[40:43], v[162:165], v[206:209], v[40:43]
	v_mfma_f32_16x16x32_bf16 v[36:39], v[154:157], v[214:217], v[36:39]
	v_mfma_f32_16x16x32_bf16 v[32:35], v[162:165], v[214:217], v[32:35]
	v_mfma_f32_16x16x32_bf16 v[28:31], v[166:169], v[182:185], v[28:31]
	v_mfma_f32_16x16x32_bf16 v[24:27], v[174:177], v[182:185], v[24:27]
	v_mfma_f32_16x16x32_bf16 v[20:23], v[166:169], v[194:197], v[20:23]
	v_mfma_f32_16x16x32_bf16 v[16:19], v[174:177], v[194:197], v[16:19]
	v_mfma_f32_16x16x32_bf16 v[12:15], v[166:169], v[202:205], v[12:15]
	v_mfma_f32_16x16x32_bf16 v[8:11], v[174:177], v[202:205], v[8:11]
	v_mfma_f32_16x16x32_bf16 v[4:7], v[166:169], v[210:213], v[4:7]
	v_mfma_f32_16x16x32_bf16 v[0:3], v[174:177], v[210:213], v[0:3]
	v_mfma_f32_16x16x32_bf16 v[28:31], v[170:173], v[190:193], v[28:31]
	v_mfma_f32_16x16x32_bf16 v[24:27], v[178:181], v[190:193], v[24:27]
	v_mfma_f32_16x16x32_bf16 v[20:23], v[170:173], v[198:201], v[20:23]
	v_mfma_f32_16x16x32_bf16 v[16:19], v[178:181], v[198:201], v[16:19]
	v_mfma_f32_16x16x32_bf16 v[12:15], v[170:173], v[206:209], v[12:15]
	v_mfma_f32_16x16x32_bf16 v[8:11], v[178:181], v[206:209], v[8:11]
	v_mfma_f32_16x16x32_bf16 v[4:7], v[170:173], v[214:217], v[4:7]
	v_mfma_f32_16x16x32_bf16 v[0:3], v[178:181], v[214:217], v[0:3]
	s_setprio 0
	s_barrier
; #define PG8_STAGE(bufoff, gbase, voff) do { _Pragma("unroll") for (int _i = 0; _i < 2; ++_i) \
;         __builtin_amdgcn_global_load_lds((const unsigned*)((const char*)(gbase) + (voff)[_i]), (PG8_LAS unsigned*)(lds + (bufoff) + ldsw + _i * 8192), 16, 0, 0); } while (0)
; #define PG8_LDA(dst, b, h) do { _Pragma("unroll") for (int m = 0; m < 4; ++m) _Pragma("unroll") for (int k = 0; k < 2; ++k) dst[m][k] = *(const PG8_LAS bf16x8*)(lds + PG8_SA(b, h) + aoff + m * 2048 + k * 1024); } while (0)
; #define PG8_LDB(dst, b, h) do { _Pragma("unroll") for (int n = 0; n < 2; ++n) _Pragma("unroll") for (int k = 0; k < 2; ++k) dst[n][k] = *(const PG8_LAS bf16x8*)(lds + PG8_SB(b, h) + boff + n * 2048 + k * 1024); } while (0)
; #define PG8_MMA(ai, bj, At, Bt) do { __builtin_amdgcn_s_setprio(1); _Pragma("unroll") for (int m = 0; m < 4; ++m) _Pragma("unroll") for (int n = 0; n < 2; ++n) _Pragma("unroll") for (int k = 0; k < 2; ++k) \
;         acc[ai][bj][m][n] = __builtin_amdgcn_mfma_f32_16x16x32_bf16(Bt[n][k], At[m][k], acc[ai][bj][m][n], 0, 0, 0); __builtin_amdgcn_s_setprio(0); } while (0)
; #define PG8_WAIT_V(n) asm volatile("s_waitcnt vmcnt(" #n ")" ::: "memory")
; #define PG8_WAIT_L(n) asm volatile("s_waitcnt lgkmcnt(" #n ")" ::: "memory")
; #define PG8_BAR __builtin_amdgcn_s_barrier()
; #define PG8_SCHED __builtin_amdgcn_sched_barrier(0)
; template <class Epi, class Sched, bool ALIGN_EPI = false, bool SP2 = false>
; __device__ __forceinline__ void gemm_phase(PG8_LAS unsigned char* lds, const Gemm g, const Sched& S, const Epi& E) {
;     ...
;             PG8_LDB(B0, 1, 0); PG8_LDB(B1, 1, 1); PG8_SCHED; PG8_LDA(At, 1, 0); PG8_STAGE(PG8_SA(0, 1), a2 + hstep, voffA);
;             PG8_WAIT_V(8); PG8_WAIT_L(0); PG8_BAR; PG8_MMA(0, 0, At, B0); PG8_MMA(0, 1, At, B1); PG8_BAR; PG8_SCHED;
;             PG8_LDA(At, 1, 1); PG8_STAGE(PG8_SB(1, 0), b3, voffB); PG8_STAGE(PG8_SB(1, 1), b3 + hstep, voffB); PG8_STAGE(PG8_SA(1, 0), a3, voffA);
;             PG8_WAIT_V(8); PG8_WAIT_L(0); PG8_BAR; PG8_MMA(1, 0, At, B0); PG8_MMA(1, 1, At, B1); PG8_BAR; PG8_SCHED;
;     ...
;         if constexpr (ALIGN_EPI) { if (wr == 0) PG8_BAR; }
	s_add_i32 s83, 0, 0x18000
	s_add_i32 s86, 0, 0x1c000
	v_add_u32_e32 v162, s83, v186
	v_add_u32_e32 v178, s86, v186
	s_add_u32 s56, s56, 0x80000
	s_addc_u32 s57, s57, 0
	s_mov_b32 m0, s63
	s_nop 0
	global_load_lds_dwordx4 v128, s[56:57]
	s_mov_b32 m0, s64
	s_nop 0
	global_load_lds_dwordx4 v132, s[56:57]
	ds_read_b128 v[150:153], v162
	ds_read_b128 v[154:157], v162 offset:1024
	ds_read_b128 v[158:161], v162 offset:2048
	ds_read_b128 v[162:165], v162 offset:3072
	ds_read_b128 v[166:169], v178
	ds_read_b128 v[170:173], v178 offset:1024
	ds_read_b128 v[174:177], v178 offset:2048
	ds_read_b128 v[178:181], v178 offset:3072
	ds_read_b128 v[182:185], v187 offset:32768
	ds_read_b128 v[190:193], v187 offset:33792
	ds_read_b128 v[194:197], v187 offset:34816
	ds_read_b128 v[198:201], v187 offset:35840
	ds_read_b128 v[202:205], v187 offset:36864
	ds_read_b128 v[206:209], v187 offset:37888
	ds_read_b128 v[210:213], v187 offset:38912
	ds_read_b128 v[214:217], v187 offset:39936
	s_waitcnt vmcnt(8)
	s_waitcnt lgkmcnt(0)
	s_barrier
	s_setprio 1
	v_mfma_f32_16x16x32_bf16 v[124:127], v[150:153], v[182:185], v[124:127]
	v_mfma_f32_16x16x32_bf16 v[120:123], v[158:161], v[182:185], v[120:123]
	v_mfma_f32_16x16x32_bf16 v[116:119], v[150:153], v[194:197], v[116:119]
	v_mfma_f32_16x16x32_bf16 v[112:115], v[158:161], v[194:197], v[112:115]
	v_mfma_f32_16x16x32_bf16 v[108:111], v[150:153], v[202:205], v[108:111]
	v_mfma_f32_16x16x32_bf16 v[104:107], v[158:161], v[202:205], v[104:107]
	v_mfma_f32_16x16x32_bf16 v[100:103], v[150:153], v[210:213], v[100:103]
	v_mfma_f32_16x16x32_bf16 v[96:99], v[158:161], v[210:213], v[96:99]
	v_mfma_f32_16x16x32_bf16 v[124:127], v[154:157], v[190:193], v[124:127]
	v_mfma_f32_16x16x32_bf16 v[120:123], v[162:165], v[190:193], v[120:123]
	v_mfma_f32_16x16x32_bf16 v[116:119], v[154:157], v[198:201], v[116:119]
	v_mfma_f32_16x16x32_bf16 v[112:115], v[162:165], v[198:201], v[112:115]
	v_mfma_f32_16x16x32_bf16 v[108:111], v[154:157], v[206:209], v[108:111]
	v_mfma_f32_16x16x32_bf16 v[104:107], v[162:165], v[206:209], v[104:107]
	v_mfma_f32_16x16x32_bf16 v[100:103], v[154:157], v[214:217], v[100:103]
	v_mfma_f32_16x16x32_bf16 v[96:99], v[162:165], v[214:217], v[96:99]
	v_mfma_f32_16x16x32_bf16 v[92:95], v[166:169], v[182:185], v[92:95]
	v_mfma_f32_16x16x32_bf16 v[88:91], v[174:177], v[182:185], v[88:91]
	v_mfma_f32_16x16x32_bf16 v[84:87], v[166:169], v[194:197], v[84:87]
	v_mfma_f32_16x16x32_bf16 v[80:83], v[174:177], v[194:197], v[80:83]
	v_mfma_f32_16x16x32_bf16 v[76:79], v[166:169], v[202:205], v[76:79]
	v_mfma_f32_16x16x32_bf16 v[72:75], v[174:177], v[202:205], v[72:75]
	v_mfma_f32_16x16x32_bf16 v[68:71], v[166:169], v[210:213], v[68:71]
	v_mfma_f32_16x16x32_bf16 v[64:67], v[174:177], v[210:213], v[64:67]
	v_mfma_f32_16x16x32_bf16 v[92:95], v[170:173], v[190:193], v[92:95]
	v_mfma_f32_16x16x32_bf16 v[88:91], v[178:181], v[190:193], v[88:91]
	v_mfma_f32_16x16x32_bf16 v[84:87], v[170:173], v[198:201], v[84:87]
	v_mfma_f32_16x16x32_bf16 v[80:83], v[178:181], v[198:201], v[80:83]
	v_mfma_f32_16x16x32_bf16 v[76:79], v[170:173], v[206:209], v[76:79]
	v_mfma_f32_16x16x32_bf16 v[72:75], v[178:181], v[206:209], v[72:75]
	v_mfma_f32_16x16x32_bf16 v[68:71], v[170:173], v[214:217], v[68:71]
	v_mfma_f32_16x16x32_bf16 v[64:67], v[178:181], v[214:217], v[64:67]
	s_setprio 0
	s_barrier
	s_add_i32 s56, s83, s60
	s_mov_b32 m0, s56
	s_nop 0
	global_load_lds_dwordx4 v130, s[92:93]
	s_add_i32 m0, s56, 0x2000
	s_add_u32 s54, s54, 0x80080
	s_addc_u32 s55, s55, 0
	s_add_i32 s56, s86, s60
	global_load_lds_dwordx4 v134, s[92:93]
	s_mov_b32 m0, s56
	s_nop 0
	global_load_lds_dwordx4 v130, s[54:55]
	s_add_i32 m0, s56, 0x2000
	s_nop 0
	global_load_lds_dwordx4 v134, s[54:55]
	s_mov_b32 m0, s65
	s_nop 0
	global_load_lds_dwordx4 v128, s[94:95]
	s_mov_b32 m0, s66
	s_nop 0
	global_load_lds_dwordx4 v132, s[94:95]
	ds_read_b128 v[182:185], v187 offset:49152
	ds_read_b128 v[190:193], v187 offset:50176
	ds_read_b128 v[194:197], v187 offset:51200
	ds_read_b128 v[198:201], v187 offset:52224
	ds_read_b128 v[202:205], v187 offset:53248
	ds_read_b128 v[206:209], v187 offset:54272
	ds_read_b128 v[210:213], v187 offset:55296
	ds_read_b128 v[214:217], v187 offset:56320
	s_waitcnt vmcnt(8)
	s_waitcnt lgkmcnt(0)
	s_barrier
	s_setprio 1
	v_mfma_f32_16x16x32_bf16 v[60:63], v[150:153], v[182:185], v[60:63]
	v_mfma_f32_16x16x32_bf16 v[56:59], v[158:161], v[182:185], v[56:59]
	v_mfma_f32_16x16x32_bf16 v[52:55], v[150:153], v[194:197], v[52:55]
	v_mfma_f32_16x16x32_bf16 v[48:51], v[158:161], v[194:197], v[48:51]
	v_mfma_f32_16x16x32_bf16 v[44:47], v[150:153], v[202:205], v[44:47]
	v_mfma_f32_16x16x32_bf16 v[40:43], v[158:161], v[202:205], v[40:43]
	v_mfma_f32_16x16x32_bf16 v[36:39], v[150:153], v[210:213], v[36:39]
	v_mfma_f32_16x16x32_bf16 v[32:35], v[158:161], v[210:213], v[32:35]
	v_mfma_f32_16x16x32_bf16 v[60:63], v[154:157], v[190:193], v[60:63]
	v_mfma_f32_16x16x32_bf16 v[56:59], v[162:165], v[190:193], v[56:59]
	v_mfma_f32_16x16x32_bf16 v[52:55], v[154:157], v[198:201], v[52:55]
	v_mfma_f32_16x16x32_bf16 v[48:51], v[162:165], v[198:201], v[48:51]
	v_mfma_f32_16x16x32_bf16 v[44:47], v[154:157], v[206:209], v[44:47]
	v_mfma_f32_16x16x32_bf16 v[40:43], v[162:165], v[206:209], v[40:43]
	v_mfma_f32_16x16x32_bf16 v[36:39], v[154:157], v[214:217], v[36:39]
	v_mfma_f32_16x16x32_bf16 v[32:35], v[162:165], v[214:217], v[32:35]
	v_mfma_f32_16x16x32_bf16 v[28:31], v[166:169], v[182:185], v[28:31]
	v_mfma_f32_16x16x32_bf16 v[24:27], v[174:177], v[182:185], v[24:27]
	v_mfma_f32_16x16x32_bf16 v[20:23], v[166:169], v[194:197], v[20:23]
	v_mfma_f32_16x16x32_bf16 v[16:19], v[174:177], v[194:197], v[16:19]
	v_mfma_f32_16x16x32_bf16 v[12:15], v[166:169], v[202:205], v[12:15]
	v_mfma_f32_16x16x32_bf16 v[8:11], v[174:177], v[202:205], v[8:11]
	v_mfma_f32_16x16x32_bf16 v[4:7], v[166:169], v[210:213], v[4:7]
	v_mfma_f32_16x16x32_bf16 v[0:3], v[174:177], v[210:213], v[0:3]
	v_mfma_f32_16x16x32_bf16 v[28:31], v[170:173], v[190:193], v[28:31]
	v_mfma_f32_16x16x32_bf16 v[24:27], v[178:181], v[190:193], v[24:27]
	v_mfma_f32_16x16x32_bf16 v[20:23], v[170:173], v[198:201], v[20:23]
	v_mfma_f32_16x16x32_bf16 v[16:19], v[178:181], v[198:201], v[16:19]
	v_mfma_f32_16x16x32_bf16 v[12:15], v[170:173], v[206:209], v[12:15]
	v_mfma_f32_16x16x32_bf16 v[8:11], v[178:181], v[206:209], v[8:11]
	v_mfma_f32_16x16x32_bf16 v[4:7], v[170:173], v[214:217], v[4:7]
	v_mfma_f32_16x16x32_bf16 v[0:3], v[178:181], v[214:217], v[0:3]
	s_setprio 0
	s_barrier
	s_add_i32 s82, s82, 2
	s_add_u32 s46, s46, 0x100
	s_addc_u32 s47, s47, 0
	s_add_u32 s80, s80, 0x100
	s_addc_u32 s81, s81, 0
	s_cmp_gt_u32 s82, 13
	s_cbranch_scc0 .LBB0_795
	s_and_b64 vcc, exec, s[16:17]
	s_cbranch_vccz .LBB0_798
	s_barrier

;     __host__ __device__ bool next(int i, Unit& u) const { const long L = (long)i * G + c; if (L >= nwg) return false; return unit_of((int)L, u); }
;     __host__ __device__ bool next(int i, Unit& u) const { const int L = i == 0 ? l0 : (i == 1 ? l1 : (i == 2 ? l2 : -1)); if (L < 0 || L >= s.nwg) return false; return s.unit_of(L, u); }
;     __host__ __device__ bool next(int i, Unit& u) const { const bool ok = s.next(i >> 1, u); u.kh = i & 1; return ok; }
; #define PG8_STAGE(bufoff, gbase, voff) do { _Pragma("unroll") for (int _i = 0; _i < 2; ++_i) \
;         __builtin_amdgcn_global_load_lds((const unsigned*)((const char*)(gbase) + (voff)[_i]), (PG8_LAS unsigned*)(lds + (bufoff) + ldsw + _i * 8192), 16, 0, 0); } while (0)
; #define PG8_LDA(dst, b, h) do { _Pragma("unroll") for (int m = 0; m < 4; ++m) _Pragma("unroll") for (int k = 0; k < 2; ++k) dst[m][k] = *(const PG8_LAS bf16x8*)(lds + PG8_SA(b, h) + aoff + m * 2048 + k * 1024); } while (0)
; template <class Epi, class Sched, bool ALIGN_EPI = false, bool SP2 = false>
; __device__ __forceinline__ void gemm_phase(PG8_LAS unsigned char* lds, const Gemm g, const Sched& S, const Epi& E) {
;     ...
;         const bool has_next = S.next(ui + 1, nxt);
;         const char* nA = has_next ? (const char*)g.A + (size_t)nxt.pm * tstep + nxt.kh * khb : cA; const char* nB = has_next ? (const char*)g.Bt + (size_t)nxt.pn * tstep + nxt.kh * khb : cB;
;         for (int t = 0; t < nt; t += 2) {
;             const bool last = (t == nt - 2);
;             const char* a1 = cA + (size_t)(t + 1) * kstep;
;             const char* a2 = last ? nA : cA + (size_t)(t + 2) * kstep; const char* b2 = last ? nB : cB + (size_t)(t + 2) * kstep;
;             const char* a3 = a2 + kstep; const char* b3 = b2 + kstep;
;             if (last && has_next) S.a_ready(nxt);
;             if constexpr (SP2) {
;             PG8_LDB(B0, 0, 0); PG8_LDB(B1, 0, 1); PG8_SCHED; PG8_LDA(At, 0, 0); PG8_STAGE(PG8_SA(1, 1), a1 + hstep, voffA);
;             PG8_WAIT_V(8); PG8_WAIT_L(0); PG8_BAR; PG8_MMA(0, 0, At, B0); PG8_MMA(0, 1, At, B1); PG8_BAR; PG8_SCHED;
;             PG8_LDA(At, 0, 1); PG8_STAGE(PG8_SB(0, 0), b2, voffB); PG8_STAGE(PG8_SB(0, 1), b2 + hstep, voffB); PG8_STAGE(PG8_SA(0, 0), a2, voffA);
;             PG8_WAIT_V(8); PG8_WAIT_L(0); PG8_BAR; PG8_MMA(1, 0, At, B0); PG8_MMA(1, 1, At, B1); PG8_BAR; PG8_SCHED;
.LBB0_881:
	s_ashr_i32 s23, s22, 31
	s_lshl_b64 s[24:25], s[22:23], 19
	s_add_u32 s24, s38, s24
	s_addc_u32 s25, s39, s25
	s_and_b64 s[26:27], s[4:5], exec
	s_cselect_b32 s23, s25, s31
	s_cselect_b32 s29, s24, s30
	s_ashr_i32 s21, s20, 31
	s_lshl_b64 s[26:27], s[20:21], 19
	s_add_u32 s26, s40, s26
	s_addc_u32 s27, s41, s27
	s_and_b64 s[36:37], s[4:5], exec
	s_cselect_b32 s21, s27, s35
	s_cselect_b32 s58, s26, s34
	s_add_u32 s30, s30, 0x40080
	s_addc_u32 s31, s31, 0
	s_add_u32 s59, s34, 0x100
	s_addc_u32 s60, s35, 0
	s_mov_b32 s61, -2
	s_waitcnt lgkmcnt(0)
	ds_read_b128 v[128:131], v173
	ds_read_b128 v[132:135], v173 offset:1024
	ds_read_b128 v[136:139], v173 offset:2048
	ds_read_b128 v[140:143], v173 offset:3072
	ds_read_b128 v[164:167], v174
	ds_read_b128 v[168:171], v174 offset:1024
	ds_read_b128 v[178:181], v174 offset:2048
	ds_read_b128 v[182:185], v174 offset:3072
	s_add_u32 s34, s30, 0xfffc0080
	s_addc_u32 s35, s31, -1
	s_cmp_eq_u32 s61, 12
	s_cselect_b32 s37, s23, s35
	s_cselect_b32 s36, s29, s34
	s_cselect_b32 s35, s21, s60
	s_cselect_b32 s34, s58, s59
	s_add_i32 m0, s43, 0xc000
	ds_read_b128 v[190:193], v175
	ds_read_b128 v[194:197], v175 offset:1024
	ds_read_b128 v[198:201], v175 offset:2048
	ds_read_b128 v[202:205], v175 offset:3072
	ds_read_b128 v[206:209], v175 offset:4096
	ds_read_b128 v[210:213], v175 offset:5120
	ds_read_b128 v[214:217], v175 offset:6144
	ds_read_b128 v[218:221], v175 offset:7168
	global_load_lds_dwordx4 v156, s[30:31]
	s_add_i32 m0, s43, 0xe000
	s_nop 0
	global_load_lds_dwordx4 v158, s[30:31]
	s_waitcnt vmcnt(8)
	s_waitcnt lgkmcnt(0)
	s_barrier
	s_setprio 1
	v_mfma_f32_16x16x32_bf16 v[124:127], v[128:131], v[190:193], 0
	v_mfma_f32_16x16x32_bf16 v[120:123], v[136:139], v[190:193], 0
	v_mfma_f32_16x16x32_bf16 v[108:111], v[128:131], v[198:201], 0
	v_mfma_f32_16x16x32_bf16 v[104:107], v[136:139], v[198:201], 0
	v_mfma_f32_16x16x32_bf16 v[92:95], v[128:131], v[206:209], 0
	v_mfma_f32_16x16x32_bf16 v[88:91], v[136:139], v[206:209], 0
	v_mfma_f32_16x16x32_bf16 v[76:79], v[128:131], v[214:217], 0
	v_mfma_f32_16x16x32_bf16 v[72:75], v[136:139], v[214:217], 0
	v_mfma_f32_16x16x32_bf16 v[124:127], v[132:135], v[194:197], v[124:127]
	v_mfma_f32_16x16x32_bf16 v[120:123], v[140:143], v[194:197], v[120:123]
	v_mfma_f32_16x16x32_bf16 v[108:111], v[132:135], v[202:205], v[108:111]
	v_mfma_f32_16x16x32_bf16 v[104:107], v[140:143], v[202:205], v[104:107]
	v_mfma_f32_16x16x32_bf16 v[92:95], v[132:135], v[210:213], v[92:95]
	v_mfma_f32_16x16x32_bf16 v[88:91], v[140:143], v[210:213], v[88:91]
	v_mfma_f32_16x16x32_bf16 v[76:79], v[132:135], v[218:221], v[76:79]
	v_mfma_f32_16x16x32_bf16 v[72:75], v[140:143], v[218:221], v[72:75]
	v_mfma_f32_16x16x32_bf16 v[116:119], v[164:167], v[190:193], 0
	v_mfma_f32_16x16x32_bf16 v[112:115], v[178:181], v[190:193], 0
	v_mfma_f32_16x16x32_bf16 v[100:103], v[164:167], v[198:201], 0
	v_mfma_f32_16x16x32_bf16 v[96:99], v[178:181], v[198:201], 0
	v_mfma_f32_16x16x32_bf16 v[84:87], v[164:167], v[206:209], 0
	v_mfma_f32_16x16x32_bf16 v[80:83], v[178:181], v[206:209], 0
	v_mfma_f32_16x16x32_bf16 v[68:71], v[164:167], v[214:217], 0
	v_mfma_f32_16x16x32_bf16 v[64:67], v[178:181], v[214:217], 0
	v_mfma_f32_16x16x32_bf16 v[116:119], v[168:171], v[194:197], v[116:119]
	v_mfma_f32_16x16x32_bf16 v[112:115], v[182:185], v[194:197], v[112:115]
	v_mfma_f32_16x16x32_bf16 v[100:103], v[168:171], v[202:205], v[100:103]
	v_mfma_f32_16x16x32_bf16 v[96:99], v[182:185], v[202:205], v[96:99]
	v_mfma_f32_16x16x32_bf16 v[84:87], v[168:171], v[210:213], v[84:87]
	v_mfma_f32_16x16x32_bf16 v[80:83], v[182:185], v[210:213], v[80:83]
	v_mfma_f32_16x16x32_bf16 v[68:71], v[168:171], v[218:221], v[68:71]
	v_mfma_f32_16x16x32_bf16 v[64:67], v[182:185], v[218:221], v[64:67]
	s_setprio 0
	s_barrier
	s_add_u32 s92, s34, s16
	s_addc_u32 s93, s35, s17
	s_add_u32 s94, s36, s16
	s_addc_u32 s95, s37, s17
	s_add_i32 s62, s55, s42
	s_mov_b32 m0, s62
	s_nop 0
	global_load_lds_dwordx4 v146, s[34:35]
	s_add_i32 m0, s62, 0x2000
	s_add_u32 s62, s34, 0x40000
	s_addc_u32 s63, s35, 0
	s_add_i32 s64, s56, s42
	global_load_lds_dwordx4 v150, s[34:35]
	s_mov_b32 m0, s64
	s_nop 0
	global_load_lds_dwordx4 v146, s[62:63]
	s_add_i32 m0, s64, 0x2000
	s_nop 0
	global_load_lds_dwordx4 v150, s[62:63]
	s_mov_b32 m0, s43
	s_nop 0
	global_load_lds_dwordx4 v144, s[36:37]
	s_mov_b32 m0, s44
	s_nop 0
	global_load_lds_dwordx4 v148, s[36:37]
	ds_read_b128 v[190:193], v175 offset:16384
	ds_read_b128 v[194:197], v175 offset:17408
	ds_read_b128 v[198:201], v175 offset:18432
	ds_read_b128 v[202:205], v175 offset:19456
	ds_read_b128 v[206:209], v175 offset:20480
	ds_read_b128 v[210:213], v175 offset:21504
	ds_read_b128 v[214:217], v175 offset:22528
	ds_read_b128 v[218:221], v175 offset:23552
	s_waitcnt vmcnt(8)
	s_waitcnt lgkmcnt(0)
	s_barrier
	s_setprio 1
	v_mfma_f32_16x16x32_bf16 v[60:63], v[128:131], v[190:193], 0
	v_mfma_f32_16x16x32_bf16 v[56:59], v[136:139], v[190:193], 0
	v_mfma_f32_16x16x32_bf16 v[44:47], v[128:131], v[198:201], 0
	v_mfma_f32_16x16x32_bf16 v[40:43], v[136:139], v[198:201], 0
	v_mfma_f32_16x16x32_bf16 v[28:31], v[128:131], v[206:209], 0
	v_mfma_f32_16x16x32_bf16 v[24:27], v[136:139], v[206:209], 0
	v_mfma_f32_16x16x32_bf16 v[12:15], v[128:131], v[214:217], 0
	v_mfma_f32_16x16x32_bf16 v[8:11], v[136:139], v[214:217], 0
	v_mfma_f32_16x16x32_bf16 v[60:63], v[132:135], v[194:197], v[60:63]
	v_mfma_f32_16x16x32_bf16 v[56:59], v[140:143], v[194:197], v[56:59]
	v_mfma_f32_16x16x32_bf16 v[44:47], v[132:135], v[202:205], v[44:47]
	v_mfma_f32_16x16x32_bf16 v[40:43], v[140:143], v[202:205], v[40:43]
	v_mfma_f32_16x16x32_bf16 v[28:31], v[132:135], v[210:213], v[28:31]
	v_mfma_f32_16x16x32_bf16 v[24:27], v[140:143], v[210:213], v[24:27]
	v_mfma_f32_16x16x32_bf16 v[12:15], v[132:135], v[218:221], v[12:15]
	v_mfma_f32_16x16x32_bf16 v[8:11], v[140:143], v[218:221], v[8:11]
	v_mfma_f32_16x16x32_bf16 v[52:55], v[164:167], v[190:193], 0
	v_mfma_f32_16x16x32_bf16 v[48:51], v[178:181], v[190:193], 0
	v_mfma_f32_16x16x32_bf16 v[36:39], v[164:167], v[198:201], 0
	v_mfma_f32_16x16x32_bf16 v[32:35], v[178:181], v[198:201], 0
	v_mfma_f32_16x16x32_bf16 v[20:23], v[164:167], v[206:209], 0
	v_mfma_f32_16x16x32_bf16 v[16:19], v[178:181], v[206:209], 0
	v_mfma_f32_16x16x32_bf16 v[4:7], v[164:167], v[214:217], 0
	v_mfma_f32_16x16x32_bf16 v[0:3], v[178:181], v[214:217], 0
	v_mfma_f32_16x16x32_bf16 v[52:55], v[168:171], v[194:197], v[52:55]
	v_mfma_f32_16x16x32_bf16 v[48:51], v[182:185], v[194:197], v[48:51]
	v_mfma_f32_16x16x32_bf16 v[36:39], v[168:171], v[202:205], v[36:39]
	v_mfma_f32_16x16x32_bf16 v[32:35], v[182:185], v[202:205], v[32:35]
	v_mfma_f32_16x16x32_bf16 v[20:23], v[168:171], v[210:213], v[20:23]
	v_mfma_f32_16x16x32_bf16 v[16:19], v[182:185], v[210:213], v[16:19]
	v_mfma_f32_16x16x32_bf16 v[4:7], v[168:171], v[218:221], v[4:7]
	v_mfma_f32_16x16x32_bf16 v[0:3], v[182:185], v[218:221], v[0:3]
	s_setprio 0
	s_barrier
	s_branch .Lmy_peel_882_mid
; #define PG8_STAGE(bufoff, gbase, voff) do { _Pragma("unroll") for (int _i = 0; _i < 2; ++_i) \
;         __builtin_amdgcn_global_load_lds((const unsigned*)((const char*)(gbase) + (voff)[_i]), (PG8_LAS unsigned*)(lds + (bufoff) + ldsw + _i * 8192), 16, 0, 0); } while (0)
; #define PG8_LDA(dst, b, h) do { _Pragma("unroll") for (int m = 0; m < 4; ++m) _Pragma("unroll") for (int k = 0; k < 2; ++k) dst[m][k] = *(const PG8_LAS bf16x8*)(lds + PG8_SA(b, h) + aoff + m * 2048 + k * 1024); } while (0)
; #define PG8_LDB(dst, b, h) do { _Pragma("unroll") for (int n = 0; n < 2; ++n) _Pragma("unroll") for (int k = 0; k < 2; ++k) dst[n][k] = *(const PG8_LAS bf16x8*)(lds + PG8_SB(b, h) + boff + n * 2048 + k * 1024); } while (0)
; #define PG8_MMA(ai, bj, At, Bt) do { __builtin_amdgcn_s_setprio(1); _Pragma("unroll") for (int m = 0; m < 4; ++m) _Pragma("unroll") for (int n = 0; n < 2; ++n) _Pragma("unroll") for (int k = 0; k < 2; ++k) \
;         acc[ai][bj][m][n] = __builtin_amdgcn_mfma_f32_16x16x32_bf16(Bt[n][k], At[m][k], acc[ai][bj][m][n], 0, 0, 0); __builtin_amdgcn_s_setprio(0); } while (0)
; #define PG8_WAIT_V(n) asm volatile("s_waitcnt vmcnt(" #n ")" ::: "memory")
; #define PG8_WAIT_L(n) asm volatile("s_waitcnt lgkmcnt(" #n ")" ::: "memory")
; #define PG8_BAR __builtin_amdgcn_s_barrier()
; #define PG8_SCHED __builtin_amdgcn_sched_barrier(0)
; template <class Epi, class Sched, bool ALIGN_EPI = false, bool SP2 = false>
; __device__ __forceinline__ void gemm_phase(PG8_LAS unsigned char* lds, const Gemm g, const Sched& S, const Epi& E) {
;     ...
;             PG8_LDB(B0, 0, 0); PG8_LDB(B1, 0, 1); PG8_SCHED; PG8_LDA(At, 0, 0); PG8_STAGE(PG8_SA(1, 1), a1 + hstep, voffA);
;             PG8_WAIT_V(8); PG8_WAIT_L(0); PG8_BAR; PG8_MMA(0, 0, At, B0); PG8_MMA(0, 1, At, B1); PG8_BAR; PG8_SCHED;
;             PG8_LDA(At, 0, 1); PG8_STAGE(PG8_SB(0, 0), b2, voffB); PG8_STAGE(PG8_SB(0, 1), b2 + hstep, voffB); PG8_STAGE(PG8_SA(0, 0), a2, voffA);
;             PG8_WAIT_V(8); PG8_WAIT_L(0); PG8_BAR; PG8_MMA(1, 0, At, B0); PG8_MMA(1, 1, At, B1); PG8_BAR; PG8_SCHED;
.LBB0_882:
	ds_read_b128 v[128:131], v173
	ds_read_b128 v[132:135], v173 offset:1024
	ds_read_b128 v[136:139], v173 offset:2048
	ds_read_b128 v[140:143], v173 offset:3072
	ds_read_b128 v[164:167], v174
	ds_read_b128 v[168:171], v174 offset:1024
	ds_read_b128 v[178:181], v174 offset:2048
	ds_read_b128 v[182:185], v174 offset:3072
	s_add_u32 s34, s30, 0xfffc0080
	s_addc_u32 s35, s31, -1
	s_cmp_eq_u32 s61, 12
	s_cselect_b32 s37, s23, s35
	s_cselect_b32 s36, s29, s34
	s_cselect_b32 s35, s21, s60
	s_cselect_b32 s34, s58, s59
	s_add_i32 m0, s43, 0xc000
	ds_read_b128 v[190:193], v175
	ds_read_b128 v[194:197], v175 offset:1024
	ds_read_b128 v[198:201], v175 offset:2048
	ds_read_b128 v[202:205], v175 offset:3072
	ds_read_b128 v[206:209], v175 offset:4096
	ds_read_b128 v[210:213], v175 offset:5120
	ds_read_b128 v[214:217], v175 offset:6144
	ds_read_b128 v[218:221], v175 offset:7168
	global_load_lds_dwordx4 v156, s[30:31]
	s_add_i32 m0, s43, 0xe000
	s_nop 0
	global_load_lds_dwordx4 v158, s[30:31]
	s_waitcnt vmcnt(8)
	s_waitcnt lgkmcnt(0)
	s_barrier
	s_setprio 1
	v_mfma_f32_16x16x32_bf16 v[124:127], v[128:131], v[190:193], v[124:127]
	v_mfma_f32_16x16x32_bf16 v[120:123], v[136:139], v[190:193], v[120:123]
	v_mfma_f32_16x16x32_bf16 v[108:111], v[128:131], v[198:201], v[108:111]
	v_mfma_f32_16x16x32_bf16 v[104:107], v[136:139], v[198:201], v[104:107]
	v_mfma_f32_16x16x32_bf16 v[92:95], v[128:131], v[206:209], v[92:95]
	v_mfma_f32_16x16x32_bf16 v[88:91], v[136:139], v[206:209], v[88:91]
	v_mfma_f32_16x16x32_bf16 v[76:79], v[128:131], v[214:217], v[76:79]
	v_mfma_f32_16x16x32_bf16 v[72:75], v[136:139], v[214:217], v[72:75]
	v_mfma_f32_16x16x32_bf16 v[124:127], v[132:135], v[194:197], v[124:127]
	v_mfma_f32_16x16x32_bf16 v[120:123], v[140:143], v[194:197], v[120:123]
	v_mfma_f32_16x16x32_bf16 v[108:111], v[132:135], v[202:205], v[108:111]
	v_mfma_f32_16x16x32_bf16 v[104:107], v[140:143], v[202:205], v[104:107]
	v_mfma_f32_16x16x32_bf16 v[92:95], v[132:135], v[210:213], v[92:95]
	v_mfma_f32_16x16x32_bf16 v[88:91], v[140:143], v[210:213], v[88:91]
	v_mfma_f32_16x16x32_bf16 v[76:79], v[132:135], v[218:221], v[76:79]
	v_mfma_f32_16x16x32_bf16 v[72:75], v[140:143], v[218:221], v[72:75]
	v_mfma_f32_16x16x32_bf16 v[116:119], v[164:167], v[190:193], v[116:119]
	v_mfma_f32_16x16x32_bf16 v[112:115], v[178:181], v[190:193], v[112:115]
	v_mfma_f32_16x16x32_bf16 v[100:103], v[164:167], v[198:201], v[100:103]
	v_mfma_f32_16x16x32_bf16 v[96:99], v[178:181], v[198:201], v[96:99]
	v_mfma_f32_16x16x32_bf16 v[84:87], v[164:167], v[206:209], v[84:87]
	v_mfma_f32_16x16x32_bf16 v[80:83], v[178:181], v[206:209], v[80:83]
	v_mfma_f32_16x16x32_bf16 v[68:71], v[164:167], v[214:217], v[68:71]
	v_mfma_f32_16x16x32_bf16 v[64:67], v[178:181], v[214:217], v[64:67]
	v_mfma_f32_16x16x32_bf16 v[116:119], v[168:171], v[194:197], v[116:119]
	v_mfma_f32_16x16x32_bf16 v[112:115], v[182:185], v[194:197], v[112:115]
	v_mfma_f32_16x16x32_bf16 v[100:103], v[168:171], v[202:205], v[100:103]
	v_mfma_f32_16x16x32_bf16 v[96:99], v[182:185], v[202:205], v[96:99]
	v_mfma_f32_16x16x32_bf16 v[84:87], v[168:171], v[210:213], v[84:87]
	v_mfma_f32_16x16x32_bf16 v[80:83], v[182:185], v[210:213], v[80:83]
	v_mfma_f32_16x16x32_bf16 v[68:71], v[168:171], v[218:221], v[68:71]
	v_mfma_f32_16x16x32_bf16 v[64:67], v[182:185], v[218:221], v[64:67]
	s_setprio 0
	s_barrier
	s_add_u32 s92, s34, s16
	s_addc_u32 s93, s35, s17
	s_add_u32 s94, s36, s16
	s_addc_u32 s95, s37, s17
	s_add_i32 s62, s55, s42
	s_mov_b32 m0, s62
	s_nop 0
	global_load_lds_dwordx4 v146, s[34:35]
	s_add_i32 m0, s62, 0x2000
	s_add_u32 s62, s34, 0x40000
	s_addc_u32 s63, s35, 0
	s_add_i32 s64, s56, s42
	global_load_lds_dwordx4 v150, s[34:35]
	s_mov_b32 m0, s64
	s_nop 0
	global_load_lds_dwordx4 v146, s[62:63]
	s_add_i32 m0, s64, 0x2000
	s_nop 0
	global_load_lds_dwordx4 v150, s[62:63]
	s_mov_b32 m0, s43
	s_nop 0
	global_load_lds_dwordx4 v144, s[36:37]
	s_mov_b32 m0, s44
	s_nop 0
	global_load_lds_dwordx4 v148, s[36:37]
	ds_read_b128 v[190:193], v175 offset:16384
	ds_read_b128 v[194:197], v175 offset:17408
	ds_read_b128 v[198:201], v175 offset:18432
	ds_read_b128 v[202:205], v175 offset:19456
	ds_read_b128 v[206:209], v175 offset:20480
	ds_read_b128 v[210:213], v175 offset:21504
	ds_read_b128 v[214:217], v175 offset:22528
	ds_read_b128 v[218:221], v175 offset:23552
	s_waitcnt vmcnt(8)
	s_waitcnt lgkmcnt(0)
	s_barrier
	s_setprio 1
	v_mfma_f32_16x16x32_bf16 v[60:63], v[128:131], v[190:193], v[60:63]
	v_mfma_f32_16x16x32_bf16 v[56:59], v[136:139], v[190:193], v[56:59]
	v_mfma_f32_16x16x32_bf16 v[44:47], v[128:131], v[198:201], v[44:47]
	v_mfma_f32_16x16x32_bf16 v[40:43], v[136:139], v[198:201], v[40:43]
	v_mfma_f32_16x16x32_bf16 v[28:31], v[128:131], v[206:209], v[28:31]
	v_mfma_f32_16x16x32_bf16 v[24:27], v[136:139], v[206:209], v[24:27]
	v_mfma_f32_16x16x32_bf16 v[12:15], v[128:131], v[214:217], v[12:15]
	v_mfma_f32_16x16x32_bf16 v[8:11], v[136:139], v[214:217], v[8:11]
	v_mfma_f32_16x16x32_bf16 v[60:63], v[132:135], v[194:197], v[60:63]
	v_mfma_f32_16x16x32_bf16 v[56:59], v[140:143], v[194:197], v[56:59]
	v_mfma_f32_16x16x32_bf16 v[44:47], v[132:135], v[202:205], v[44:47]
	v_mfma_f32_16x16x32_bf16 v[40:43], v[140:143], v[202:205], v[40:43]
	v_mfma_f32_16x16x32_bf16 v[28:31], v[132:135], v[210:213], v[28:31]
	v_mfma_f32_16x16x32_bf16 v[24:27], v[140:143], v[210:213], v[24:27]
	v_mfma_f32_16x16x32_bf16 v[12:15], v[132:135], v[218:221], v[12:15]
	v_mfma_f32_16x16x32_bf16 v[8:11], v[140:143], v[218:221], v[8:11]
	v_mfma_f32_16x16x32_bf16 v[52:55], v[164:167], v[190:193], v[52:55]
	v_mfma_f32_16x16x32_bf16 v[48:51], v[178:181], v[190:193], v[48:51]
	v_mfma_f32_16x16x32_bf16 v[36:39], v[164:167], v[198:201], v[36:39]
	v_mfma_f32_16x16x32_bf16 v[32:35], v[178:181], v[198:201], v[32:35]
	v_mfma_f32_16x16x32_bf16 v[20:23], v[164:167], v[206:209], v[20:23]
	v_mfma_f32_16x16x32_bf16 v[16:19], v[178:181], v[206:209], v[16:19]
	v_mfma_f32_16x16x32_bf16 v[4:7], v[164:167], v[214:217], v[4:7]
	v_mfma_f32_16x16x32_bf16 v[0:3], v[178:181], v[214:217], v[0:3]
	v_mfma_f32_16x16x32_bf16 v[52:55], v[168:171], v[194:197], v[52:55]
	v_mfma_f32_16x16x32_bf16 v[48:51], v[182:185], v[194:197], v[48:51]
	v_mfma_f32_16x16x32_bf16 v[36:39], v[168:171], v[202:205], v[36:39]
	v_mfma_f32_16x16x32_bf16 v[32:35], v[182:185], v[202:205], v[32:35]
	v_mfma_f32_16x16x32_bf16 v[20:23], v[168:171], v[210:213], v[20:23]
	v_mfma_f32_16x16x32_bf16 v[16:19], v[182:185], v[210:213], v[16:19]
	v_mfma_f32_16x16x32_bf16 v[4:7], v[168:171], v[218:221], v[4:7]
	v_mfma_f32_16x16x32_bf16 v[0:3], v[182:185], v[218:221], v[0:3]
	s_setprio 0
	s_barrier
; #define PG8_STAGE(bufoff, gbase, voff) do { _Pragma("unroll") for (int _i = 0; _i < 2; ++_i) \
;         __builtin_amdgcn_global_load_lds((const unsigned*)((const char*)(gbase) + (voff)[_i]), (PG8_LAS unsigned*)(lds + (bufoff) + ldsw + _i * 8192), 16, 0, 0); } while (0)
; #define PG8_LDA(dst, b, h) do { _Pragma("unroll") for (int m = 0; m < 4; ++m) _Pragma("unroll") for (int k = 0; k < 2; ++k) dst[m][k] = *(const PG8_LAS bf16x8*)(lds + PG8_SA(b, h) + aoff + m * 2048 + k * 1024); } while (0)
; #define PG8_LDB(dst, b, h) do { _Pragma("unroll") for (int n = 0; n < 2; ++n) _Pragma("unroll") for (int k = 0; k < 2; ++k) dst[n][k] = *(const PG8_LAS bf16x8*)(lds + PG8_SB(b, h) + boff + n * 2048 + k * 1024); } while (0)
; #define PG8_MMA(ai, bj, At, Bt) do { __builtin_amdgcn_s_setprio(1); _Pragma("unroll") for (int m = 0; m < 4; ++m) _Pragma("unroll") for (int n = 0; n < 2; ++n) _Pragma("unroll") for (int k = 0; k < 2; ++k) \
;         acc[ai][bj][m][n] = __builtin_amdgcn_mfma_f32_16x16x32_bf16(Bt[n][k], At[m][k], acc[ai][bj][m][n], 0, 0, 0); __builtin_amdgcn_s_setprio(0); } while (0)
; #define PG8_WAIT_V(n) asm volatile("s_waitcnt vmcnt(" #n ")" ::: "memory")
; #define PG8_WAIT_L(n) asm volatile("s_waitcnt lgkmcnt(" #n ")" ::: "memory")
; #define PG8_BAR __builtin_amdgcn_s_barrier()
; #define PG8_SCHED __builtin_amdgcn_sched_barrier(0)
; template <class Epi, class Sched, bool ALIGN_EPI = false, bool SP2 = false>
; __device__ __forceinline__ void gemm_phase(PG8_LAS unsigned char* lds, const Gemm g, const Sched& S, const Epi& E) {
;     ...
;             PG8_LDB(B0, 1, 0); PG8_LDB(B1, 1, 1); PG8_SCHED; PG8_LDA(At, 1, 0); PG8_STAGE(PG8_SA(0, 1), a2 + hstep, voffA);
;             PG8_WAIT_V(8); PG8_WAIT_L(0); PG8_BAR; PG8_MMA(0, 0, At, B0); PG8_MMA(0, 1, At, B1); PG8_BAR; PG8_SCHED;
;             PG8_LDA(At, 1, 1); PG8_STAGE(PG8_SB(1, 0), b3, voffB); PG8_STAGE(PG8_SB(1, 1), b3 + hstep, voffB); PG8_STAGE(PG8_SA(1, 0), a3, voffA);
;             PG8_WAIT_V(8); PG8_WAIT_L(0); PG8_BAR; PG8_MMA(1, 0, At, B0); PG8_MMA(1, 1, At, B1); PG8_BAR; PG8_SCHED;
;     ...
;         if constexpr (ALIGN_EPI) { if (wr == 0) PG8_BAR; }
.Lmy_peel_882_mid:
	s_add_i32 s62, 0, 0x18000
	s_add_i32 s63, 0, 0x1c000
	v_add_u32_e32 v140, s62, v172
	v_add_u32_e32 v177, s63, v172
	ds_read_b128 v[128:131], v140
	ds_read_b128 v[132:135], v140 offset:1024
	ds_read_b128 v[136:139], v140 offset:2048
	ds_read_b128 v[140:143], v140 offset:3072
	ds_read_b128 v[164:167], v177
	ds_read_b128 v[168:171], v177 offset:1024
	ds_read_b128 v[178:181], v177 offset:2048
	ds_read_b128 v[182:185], v177 offset:3072
	s_add_u32 s36, s36, 0x40000
	s_addc_u32 s37, s37, 0
	s_mov_b32 m0, s45
	ds_read_b128 v[190:193], v175 offset:32768
	ds_read_b128 v[194:197], v175 offset:33792
	ds_read_b128 v[198:201], v175 offset:34816
	ds_read_b128 v[202:205], v175 offset:35840
	ds_read_b128 v[206:209], v175 offset:36864
	ds_read_b128 v[210:213], v175 offset:37888
	ds_read_b128 v[214:217], v175 offset:38912
	ds_read_b128 v[218:221], v175 offset:39936
	global_load_lds_dwordx4 v144, s[36:37]
	s_mov_b32 m0, s46
	s_nop 0
	global_load_lds_dwordx4 v148, s[36:37]
	s_waitcnt vmcnt(8)
	s_waitcnt lgkmcnt(0)
	s_barrier
	s_setprio 1
	v_mfma_f32_16x16x32_bf16 v[124:127], v[128:131], v[190:193], v[124:127]
	v_mfma_f32_16x16x32_bf16 v[120:123], v[136:139], v[190:193], v[120:123]
	v_mfma_f32_16x16x32_bf16 v[108:111], v[128:131], v[198:201], v[108:111]
	v_mfma_f32_16x16x32_bf16 v[104:107], v[136:139], v[198:201], v[104:107]
	v_mfma_f32_16x16x32_bf16 v[92:95], v[128:131], v[206:209], v[92:95]
	v_mfma_f32_16x16x32_bf16 v[88:91], v[136:139], v[206:209], v[88:91]
	v_mfma_f32_16x16x32_bf16 v[76:79], v[128:131], v[214:217], v[76:79]
	v_mfma_f32_16x16x32_bf16 v[72:75], v[136:139], v[214:217], v[72:75]
	v_mfma_f32_16x16x32_bf16 v[124:127], v[132:135], v[194:197], v[124:127]
	v_mfma_f32_16x16x32_bf16 v[120:123], v[140:143], v[194:197], v[120:123]
	v_mfma_f32_16x16x32_bf16 v[108:111], v[132:135], v[202:205], v[108:111]
	v_mfma_f32_16x16x32_bf16 v[104:107], v[140:143], v[202:205], v[104:107]
	v_mfma_f32_16x16x32_bf16 v[92:95], v[132:135], v[210:213], v[92:95]
	v_mfma_f32_16x16x32_bf16 v[88:91], v[140:143], v[210:213], v[88:91]
	v_mfma_f32_16x16x32_bf16 v[76:79], v[132:135], v[218:221], v[76:79]
	v_mfma_f32_16x16x32_bf16 v[72:75], v[140:143], v[218:221], v[72:75]
	v_mfma_f32_16x16x32_bf16 v[116:119], v[164:167], v[190:193], v[116:119]
	v_mfma_f32_16x16x32_bf16 v[112:115], v[178:181], v[190:193], v[112:115]
	v_mfma_f32_16x16x32_bf16 v[100:103], v[164:167], v[198:201], v[100:103]
	v_mfma_f32_16x16x32_bf16 v[96:99], v[178:181], v[198:201], v[96:99]
	v_mfma_f32_16x16x32_bf16 v[84:87], v[164:167], v[206:209], v[84:87]
	v_mfma_f32_16x16x32_bf16 v[80:83], v[178:181], v[206:209], v[80:83]
	v_mfma_f32_16x16x32_bf16 v[68:71], v[164:167], v[214:217], v[68:71]
	v_mfma_f32_16x16x32_bf16 v[64:67], v[178:181], v[214:217], v[64:67]
	v_mfma_f32_16x16x32_bf16 v[116:119], v[168:171], v[194:197], v[116:119]
	v_mfma_f32_16x16x32_bf16 v[112:115], v[182:185], v[194:197], v[112:115]
	v_mfma_f32_16x16x32_bf16 v[100:103], v[168:171], v[202:205], v[100:103]
	v_mfma_f32_16x16x32_bf16 v[96:99], v[182:185], v[202:205], v[96:99]
	v_mfma_f32_16x16x32_bf16 v[84:87], v[168:171], v[210:213], v[84:87]
	v_mfma_f32_16x16x32_bf16 v[80:83], v[182:185], v[210:213], v[80:83]
	v_mfma_f32_16x16x32_bf16 v[68:71], v[168:171], v[218:221], v[68:71]
	v_mfma_f32_16x16x32_bf16 v[64:67], v[182:185], v[218:221], v[64:67]
	s_setprio 0
	s_barrier
	s_add_i32 s36, s62, s42
	s_mov_b32 m0, s36
	s_nop 0
	global_load_lds_dwordx4 v146, s[92:93]
	s_add_i32 m0, s36, 0x2000
	s_add_u32 s34, s34, 0x40080
	s_addc_u32 s35, s35, 0
	s_add_i32 s36, s63, s42
	global_load_lds_dwordx4 v150, s[92:93]
	s_mov_b32 m0, s36
	s_nop 0
	global_load_lds_dwordx4 v146, s[34:35]
	s_add_i32 m0, s36, 0x2000
	s_nop 0
	global_load_lds_dwordx4 v150, s[34:35]
	s_mov_b32 m0, s48
	s_nop 0
	global_load_lds_dwordx4 v144, s[94:95]
	s_mov_b32 m0, s49
	s_nop 0
	global_load_lds_dwordx4 v148, s[94:95]
	ds_read_b128 v[190:193], v175 offset:49152
	ds_read_b128 v[194:197], v175 offset:50176
	ds_read_b128 v[198:201], v175 offset:51200
	ds_read_b128 v[202:205], v175 offset:52224
	ds_read_b128 v[206:209], v175 offset:53248
	ds_read_b128 v[210:213], v175 offset:54272
	ds_read_b128 v[214:217], v175 offset:55296
	ds_read_b128 v[218:221], v175 offset:56320
	s_waitcnt vmcnt(8)
	s_waitcnt lgkmcnt(0)
	s_barrier
	s_setprio 1
	v_mfma_f32_16x16x32_bf16 v[60:63], v[128:131], v[190:193], v[60:63]
	v_mfma_f32_16x16x32_bf16 v[56:59], v[136:139], v[190:193], v[56:59]
	v_mfma_f32_16x16x32_bf16 v[44:47], v[128:131], v[198:201], v[44:47]
	v_mfma_f32_16x16x32_bf16 v[40:43], v[136:139], v[198:201], v[40:43]
	v_mfma_f32_16x16x32_bf16 v[28:31], v[128:131], v[206:209], v[28:31]
	v_mfma_f32_16x16x32_bf16 v[24:27], v[136:139], v[206:209], v[24:27]
	v_mfma_f32_16x16x32_bf16 v[12:15], v[128:131], v[214:217], v[12:15]
	v_mfma_f32_16x16x32_bf16 v[8:11], v[136:139], v[214:217], v[8:11]
	v_mfma_f32_16x16x32_bf16 v[60:63], v[132:135], v[194:197], v[60:63]
	v_mfma_f32_16x16x32_bf16 v[56:59], v[140:143], v[194:197], v[56:59]
	v_mfma_f32_16x16x32_bf16 v[44:47], v[132:135], v[202:205], v[44:47]
	v_mfma_f32_16x16x32_bf16 v[40:43], v[140:143], v[202:205], v[40:43]
	v_mfma_f32_16x16x32_bf16 v[28:31], v[132:135], v[210:213], v[28:31]
	v_mfma_f32_16x16x32_bf16 v[24:27], v[140:143], v[210:213], v[24:27]
	v_mfma_f32_16x16x32_bf16 v[12:15], v[132:135], v[218:221], v[12:15]
	v_mfma_f32_16x16x32_bf16 v[8:11], v[140:143], v[218:221], v[8:11]
	v_mfma_f32_16x16x32_bf16 v[52:55], v[164:167], v[190:193], v[52:55]
	v_mfma_f32_16x16x32_bf16 v[48:51], v[178:181], v[190:193], v[48:51]
	v_mfma_f32_16x16x32_bf16 v[36:39], v[164:167], v[198:201], v[36:39]
	v_mfma_f32_16x16x32_bf16 v[32:35], v[178:181], v[198:201], v[32:35]
	v_mfma_f32_16x16x32_bf16 v[20:23], v[164:167], v[206:209], v[20:23]
	v_mfma_f32_16x16x32_bf16 v[16:19], v[178:181], v[206:209], v[16:19]
	v_mfma_f32_16x16x32_bf16 v[4:7], v[164:167], v[214:217], v[4:7]
	v_mfma_f32_16x16x32_bf16 v[0:3], v[178:181], v[214:217], v[0:3]
	v_mfma_f32_16x16x32_bf16 v[52:55], v[168:171], v[194:197], v[52:55]
	v_mfma_f32_16x16x32_bf16 v[48:51], v[182:185], v[194:197], v[48:51]
	v_mfma_f32_16x16x32_bf16 v[36:39], v[168:171], v[202:205], v[36:39]
	v_mfma_f32_16x16x32_bf16 v[32:35], v[182:185], v[202:205], v[32:35]
	v_mfma_f32_16x16x32_bf16 v[20:23], v[168:171], v[210:213], v[20:23]
	v_mfma_f32_16x16x32_bf16 v[16:19], v[182:185], v[210:213], v[16:19]
	v_mfma_f32_16x16x32_bf16 v[4:7], v[168:171], v[218:221], v[4:7]
	v_mfma_f32_16x16x32_bf16 v[0:3], v[182:185], v[218:221], v[0:3]
	s_setprio 0
	s_barrier
	s_add_i32 s61, s61, 2
	s_add_u32 s30, s30, 0x100
	s_addc_u32 s31, s31, 0
	s_add_u32 s59, s59, 0x100
	s_addc_u32 s60, s60, 0
	s_cmp_gt_u32 s61, 13
	s_cbranch_scc0 .LBB0_882
	s_and_b64 vcc, exec, s[18:19]
	s_cbranch_vccz .LBB0_885
	s_barrier

;     __host__ __device__ bool next(int i, Unit& u) const { const long L = (long)i * G + c; if (L >= nwg) return false; return unit_of((int)L, u); }
;     __host__ __device__ bool next(int i, Unit& u) const { const int L = i == 0 ? l0 : (i == 1 ? l1 : (i == 2 ? l2 : -1)); if (L < 0 || L >= s.nwg) return false; return s.unit_of(L, u); }
;     __host__ __device__ bool next(int i, Unit& u) const { const bool ok = s.next(i >> 1, u); u.kh = i & 1; return ok; }
; #define PG8_STAGE(bufoff, gbase, voff) do { _Pragma("unroll") for (int _i = 0; _i < 2; ++_i) \
;         __builtin_amdgcn_global_load_lds((const unsigned*)((const char*)(gbase) + (voff)[_i]), (PG8_LAS unsigned*)(lds + (bufoff) + ldsw + _i * 8192), 16, 0, 0); } while (0)
; #define PG8_LDA(dst, b, h) do { _Pragma("unroll") for (int m = 0; m < 4; ++m) _Pragma("unroll") for (int k = 0; k < 2; ++k) dst[m][k] = *(const PG8_LAS bf16x8*)(lds + PG8_SA(b, h) + aoff + m * 2048 + k * 1024); } while (0)
; template <class Epi, class Sched, bool ALIGN_EPI = false, bool SP2 = false>
; __device__ __forceinline__ void gemm_phase(PG8_LAS unsigned char* lds, const Gemm g, const Sched& S, const Epi& E) {
;     ...
;         const bool has_next = S.next(ui + 1, nxt);
;         const char* nA = has_next ? (const char*)g.A + (size_t)nxt.pm * tstep + nxt.kh * khb : cA; const char* nB = has_next ? (const char*)g.Bt + (size_t)nxt.pn * tstep + nxt.kh * khb : cB;
;         for (int t = 0; t < nt; t += 2) {
;             const bool last = (t == nt - 2);
;             const char* a1 = cA + (size_t)(t + 1) * kstep;
;             const char* a2 = last ? nA : cA + (size_t)(t + 2) * kstep; const char* b2 = last ? nB : cB + (size_t)(t + 2) * kstep;
;             const char* a3 = a2 + kstep; const char* b3 = b2 + kstep;
;             if (last && has_next) S.a_ready(nxt);
;             if constexpr (SP2) {
;             PG8_LDB(B0, 0, 0); PG8_LDB(B1, 0, 1); PG8_SCHED; PG8_LDA(At, 0, 0); PG8_STAGE(PG8_SA(1, 1), a1 + hstep, voffA);
;             PG8_WAIT_V(8); PG8_WAIT_L(0); PG8_BAR; PG8_MMA(0, 0, At, B0); PG8_MMA(0, 1, At, B1); PG8_BAR; PG8_SCHED;
;             PG8_LDA(At, 0, 1); PG8_STAGE(PG8_SB(0, 0), b2, voffB); PG8_STAGE(PG8_SB(0, 1), b2 + hstep, voffB); PG8_STAGE(PG8_SA(0, 0), a2, voffA);
;             PG8_WAIT_V(8); PG8_WAIT_L(0); PG8_BAR; PG8_MMA(1, 0, At, B0); PG8_MMA(1, 1, At, B1); PG8_BAR; PG8_SCHED;
.LBB0_968:
	s_ashr_i32 s17, s16, 31
	s_lshl_b64 s[18:19], s[16:17], 19
	s_add_u32 s18, s30, s18
	s_addc_u32 s19, s31, s19
	s_and_b64 s[20:21], s[2:3], exec
	s_cselect_b32 s17, s19, s25
	s_cselect_b32 s51, s18, s24
	s_ashr_i32 s15, s14, 31
	s_lshl_b64 s[20:21], s[14:15], 19
	s_add_u32 s20, s34, s20
	s_addc_u32 s21, s35, s21
	s_and_b64 s[28:29], s[2:3], exec
	s_cselect_b32 s15, s21, s27
	s_cselect_b32 s54, s20, s26
	s_add_u32 s24, s24, 0x40080
	s_addc_u32 s25, s25, 0
	s_add_u32 s55, s26, 0x100
	s_addc_u32 s56, s27, 0
	s_mov_b32 s57, -2
	ds_read_b128 v[128:131], v191
	ds_read_b128 v[132:135], v191 offset:1024
	ds_read_b128 v[136:139], v191 offset:2048
	ds_read_b128 v[140:143], v191 offset:3072
	ds_read_b128 v[144:147], v192
	ds_read_b128 v[148:151], v192 offset:1024
	ds_read_b128 v[172:175], v192 offset:2048
	ds_read_b128 v[176:179], v192 offset:3072
	s_add_u32 s26, s24, 0xfffc0080
	s_addc_u32 s27, s25, -1
	s_cmp_eq_u32 s57, 12
	s_cselect_b32 s29, s17, s27
	s_cselect_b32 s28, s51, s26
	s_cselect_b32 s27, s15, s56
	s_cselect_b32 s26, s54, s55
	s_add_i32 m0, s39, 0xc000
	ds_read_b128 v[180:183], v193
	ds_read_b128 v[184:187], v193 offset:1024
	ds_read_b128 v[196:199], v193 offset:2048
	ds_read_b128 v[200:203], v193 offset:3072
	ds_read_b128 v[204:207], v193 offset:4096
	ds_read_b128 v[208:211], v193 offset:5120
	ds_read_b128 v[212:215], v193 offset:6144
	ds_read_b128 v[216:219], v193 offset:7168
	global_load_lds_dwordx4 v164, s[24:25]
	s_add_i32 m0, s39, 0xe000
	s_nop 0
	global_load_lds_dwordx4 v166, s[24:25]
	s_waitcnt vmcnt(8)
	s_waitcnt lgkmcnt(0)
	s_barrier
	s_setprio 1
	v_mfma_f32_16x16x32_bf16 v[124:127], v[128:131], v[180:183], 0
	v_mfma_f32_16x16x32_bf16 v[120:123], v[136:139], v[180:183], 0
	v_mfma_f32_16x16x32_bf16 v[108:111], v[128:131], v[196:199], 0
	v_mfma_f32_16x16x32_bf16 v[104:107], v[136:139], v[196:199], 0
	v_mfma_f32_16x16x32_bf16 v[92:95], v[128:131], v[204:207], 0
	v_mfma_f32_16x16x32_bf16 v[84:87], v[136:139], v[204:207], 0
	v_mfma_f32_16x16x32_bf16 v[76:79], v[128:131], v[212:215], 0
	v_mfma_f32_16x16x32_bf16 v[72:75], v[136:139], v[212:215], 0
	v_mfma_f32_16x16x32_bf16 v[124:127], v[132:135], v[184:187], v[124:127]
	v_mfma_f32_16x16x32_bf16 v[120:123], v[140:143], v[184:187], v[120:123]
	v_mfma_f32_16x16x32_bf16 v[108:111], v[132:135], v[200:203], v[108:111]
	v_mfma_f32_16x16x32_bf16 v[104:107], v[140:143], v[200:203], v[104:107]
	v_mfma_f32_16x16x32_bf16 v[92:95], v[132:135], v[208:211], v[92:95]
	v_mfma_f32_16x16x32_bf16 v[84:87], v[140:143], v[208:211], v[84:87]
	v_mfma_f32_16x16x32_bf16 v[76:79], v[132:135], v[216:219], v[76:79]
	v_mfma_f32_16x16x32_bf16 v[72:75], v[140:143], v[216:219], v[72:75]
	v_mfma_f32_16x16x32_bf16 v[116:119], v[144:147], v[180:183], 0
	v_mfma_f32_16x16x32_bf16 v[112:115], v[172:175], v[180:183], 0
	v_mfma_f32_16x16x32_bf16 v[100:103], v[144:147], v[196:199], 0
	v_mfma_f32_16x16x32_bf16 v[96:99], v[172:175], v[196:199], 0
	v_mfma_f32_16x16x32_bf16 v[88:91], v[144:147], v[204:207], 0
	v_mfma_f32_16x16x32_bf16 v[80:83], v[172:175], v[204:207], 0
	v_mfma_f32_16x16x32_bf16 v[68:71], v[144:147], v[212:215], 0
	v_mfma_f32_16x16x32_bf16 v[64:67], v[172:175], v[212:215], 0
	v_mfma_f32_16x16x32_bf16 v[116:119], v[148:151], v[184:187], v[116:119]
	v_mfma_f32_16x16x32_bf16 v[112:115], v[176:179], v[184:187], v[112:115]
	v_mfma_f32_16x16x32_bf16 v[100:103], v[148:151], v[200:203], v[100:103]
	v_mfma_f32_16x16x32_bf16 v[96:99], v[176:179], v[200:203], v[96:99]
	v_mfma_f32_16x16x32_bf16 v[88:91], v[148:151], v[208:211], v[88:91]
	v_mfma_f32_16x16x32_bf16 v[80:83], v[176:179], v[208:211], v[80:83]
	v_mfma_f32_16x16x32_bf16 v[68:71], v[148:151], v[216:219], v[68:71]
	v_mfma_f32_16x16x32_bf16 v[64:67], v[176:179], v[216:219], v[64:67]
	s_setprio 0
	s_barrier
	s_add_u32 s92, s26, s10
	s_addc_u32 s93, s27, s11
	s_add_u32 s94, s28, s10
	s_addc_u32 s95, s29, s11
	s_add_i32 s58, s47, s36
	s_mov_b32 m0, s58
	s_nop 0
	global_load_lds_dwordx4 v156, s[26:27]
	s_add_i32 m0, s58, 0x2000
	s_add_u32 s58, s26, 0x40000
	s_addc_u32 s59, s27, 0
	s_add_i32 s60, s48, s36
	global_load_lds_dwordx4 v152, s[26:27]
	s_mov_b32 m0, s60
	s_nop 0
	global_load_lds_dwordx4 v156, s[58:59]
	s_add_i32 m0, s60, 0x2000
	s_nop 0
	global_load_lds_dwordx4 v152, s[58:59]
	s_mov_b32 m0, s39
	s_nop 0
	global_load_lds_dwordx4 v158, s[28:29]
	s_mov_b32 m0, s40
	s_nop 0
	global_load_lds_dwordx4 v154, s[28:29]
	ds_read_b128 v[180:183], v193 offset:16384
	ds_read_b128 v[184:187], v193 offset:17408
	ds_read_b128 v[196:199], v193 offset:18432
	ds_read_b128 v[200:203], v193 offset:19456
	ds_read_b128 v[204:207], v193 offset:20480
	ds_read_b128 v[208:211], v193 offset:21504
	ds_read_b128 v[212:215], v193 offset:22528
	ds_read_b128 v[216:219], v193 offset:23552
	s_waitcnt vmcnt(8)
	s_waitcnt lgkmcnt(0)
	s_barrier
	s_setprio 1
	v_mfma_f32_16x16x32_bf16 v[60:63], v[128:131], v[180:183], 0
	v_mfma_f32_16x16x32_bf16 v[52:55], v[136:139], v[180:183], 0
	v_mfma_f32_16x16x32_bf16 v[44:47], v[128:131], v[196:199], 0
	v_mfma_f32_16x16x32_bf16 v[40:43], v[136:139], v[196:199], 0
	v_mfma_f32_16x16x32_bf16 v[28:31], v[128:131], v[204:207], 0
	v_mfma_f32_16x16x32_bf16 v[20:23], v[136:139], v[204:207], 0
	v_mfma_f32_16x16x32_bf16 v[12:15], v[128:131], v[212:215], 0
	v_mfma_f32_16x16x32_bf16 v[8:11], v[136:139], v[212:215], 0
	v_mfma_f32_16x16x32_bf16 v[60:63], v[132:135], v[184:187], v[60:63]
	v_mfma_f32_16x16x32_bf16 v[52:55], v[140:143], v[184:187], v[52:55]
	v_mfma_f32_16x16x32_bf16 v[44:47], v[132:135], v[200:203], v[44:47]
	v_mfma_f32_16x16x32_bf16 v[40:43], v[140:143], v[200:203], v[40:43]
	v_mfma_f32_16x16x32_bf16 v[28:31], v[132:135], v[208:211], v[28:31]
	v_mfma_f32_16x16x32_bf16 v[20:23], v[140:143], v[208:211], v[20:23]
	v_mfma_f32_16x16x32_bf16 v[12:15], v[132:135], v[216:219], v[12:15]
	v_mfma_f32_16x16x32_bf16 v[8:11], v[140:143], v[216:219], v[8:11]
	v_mfma_f32_16x16x32_bf16 v[56:59], v[144:147], v[180:183], 0
	v_mfma_f32_16x16x32_bf16 v[48:51], v[172:175], v[180:183], 0
	v_mfma_f32_16x16x32_bf16 v[36:39], v[144:147], v[196:199], 0
	v_mfma_f32_16x16x32_bf16 v[32:35], v[172:175], v[196:199], 0
	v_mfma_f32_16x16x32_bf16 v[24:27], v[144:147], v[204:207], 0
	v_mfma_f32_16x16x32_bf16 v[16:19], v[172:175], v[204:207], 0
	v_mfma_f32_16x16x32_bf16 v[4:7], v[144:147], v[212:215], 0
	v_mfma_f32_16x16x32_bf16 v[0:3], v[172:175], v[212:215], 0
	v_mfma_f32_16x16x32_bf16 v[56:59], v[148:151], v[184:187], v[56:59]
	v_mfma_f32_16x16x32_bf16 v[48:51], v[176:179], v[184:187], v[48:51]
	v_mfma_f32_16x16x32_bf16 v[36:39], v[148:151], v[200:203], v[36:39]
	v_mfma_f32_16x16x32_bf16 v[32:35], v[176:179], v[200:203], v[32:35]
	v_mfma_f32_16x16x32_bf16 v[24:27], v[148:151], v[208:211], v[24:27]
	v_mfma_f32_16x16x32_bf16 v[16:19], v[176:179], v[208:211], v[16:19]
	v_mfma_f32_16x16x32_bf16 v[4:7], v[148:151], v[216:219], v[4:7]
	v_mfma_f32_16x16x32_bf16 v[0:3], v[176:179], v[216:219], v[0:3]
	s_setprio 0
	s_barrier
	s_branch .Lmy_peel_969_mid
; #define PG8_STAGE(bufoff, gbase, voff) do { _Pragma("unroll") for (int _i = 0; _i < 2; ++_i) \
;         __builtin_amdgcn_global_load_lds((const unsigned*)((const char*)(gbase) + (voff)[_i]), (PG8_LAS unsigned*)(lds + (bufoff) + ldsw + _i * 8192), 16, 0, 0); } while (0)
; #define PG8_LDA(dst, b, h) do { _Pragma("unroll") for (int m = 0; m < 4; ++m) _Pragma("unroll") for (int k = 0; k < 2; ++k) dst[m][k] = *(const PG8_LAS bf16x8*)(lds + PG8_SA(b, h) + aoff + m * 2048 + k * 1024); } while (0)
; #define PG8_LDB(dst, b, h) do { _Pragma("unroll") for (int n = 0; n < 2; ++n) _Pragma("unroll") for (int k = 0; k < 2; ++k) dst[n][k] = *(const PG8_LAS bf16x8*)(lds + PG8_SB(b, h) + boff + n * 2048 + k * 1024); } while (0)
; #define PG8_MMA(ai, bj, At, Bt) do { __builtin_amdgcn_s_setprio(1); _Pragma("unroll") for (int m = 0; m < 4; ++m) _Pragma("unroll") for (int n = 0; n < 2; ++n) _Pragma("unroll") for (int k = 0; k < 2; ++k) \
;         acc[ai][bj][m][n] = __builtin_amdgcn_mfma_f32_16x16x32_bf16(Bt[n][k], At[m][k], acc[ai][bj][m][n], 0, 0, 0); __builtin_amdgcn_s_setprio(0); } while (0)
; #define PG8_WAIT_V(n) asm volatile("s_waitcnt vmcnt(" #n ")" ::: "memory")
; #define PG8_WAIT_L(n) asm volatile("s_waitcnt lgkmcnt(" #n ")" ::: "memory")
; #define PG8_BAR __builtin_amdgcn_s_barrier()
; #define PG8_SCHED __builtin_amdgcn_sched_barrier(0)
; template <class Epi, class Sched, bool ALIGN_EPI = false, bool SP2 = false>
; __device__ __forceinline__ void gemm_phase(PG8_LAS unsigned char* lds, const Gemm g, const Sched& S, const Epi& E) {
;     ...
;             PG8_LDB(B0, 0, 0); PG8_LDB(B1, 0, 1); PG8_SCHED; PG8_LDA(At, 0, 0); PG8_STAGE(PG8_SA(1, 1), a1 + hstep, voffA);
;             PG8_WAIT_V(8); PG8_WAIT_L(0); PG8_BAR; PG8_MMA(0, 0, At, B0); PG8_MMA(0, 1, At, B1); PG8_BAR; PG8_SCHED;
;             PG8_LDA(At, 0, 1); PG8_STAGE(PG8_SB(0, 0), b2, voffB); PG8_STAGE(PG8_SB(0, 1), b2 + hstep, voffB); PG8_STAGE(PG8_SA(0, 0), a2, voffA);
;             PG8_WAIT_V(8); PG8_WAIT_L(0); PG8_BAR; PG8_MMA(1, 0, At, B0); PG8_MMA(1, 1, At, B1); PG8_BAR; PG8_SCHED;
.LBB0_969:
	ds_read_b128 v[128:131], v191
	ds_read_b128 v[132:135], v191 offset:1024
	ds_read_b128 v[136:139], v191 offset:2048
	ds_read_b128 v[140:143], v191 offset:3072
	ds_read_b128 v[144:147], v192
	ds_read_b128 v[148:151], v192 offset:1024
	ds_read_b128 v[172:175], v192 offset:2048
	ds_read_b128 v[176:179], v192 offset:3072
	s_add_u32 s26, s24, 0xfffc0080
	s_addc_u32 s27, s25, -1
	s_cmp_eq_u32 s57, 12
	s_cselect_b32 s29, s17, s27
	s_cselect_b32 s28, s51, s26
	s_cselect_b32 s27, s15, s56
	s_cselect_b32 s26, s54, s55
	s_add_i32 m0, s39, 0xc000
	ds_read_b128 v[180:183], v193
	ds_read_b128 v[184:187], v193 offset:1024
	ds_read_b128 v[196:199], v193 offset:2048
	ds_read_b128 v[200:203], v193 offset:3072
	ds_read_b128 v[204:207], v193 offset:4096
	ds_read_b128 v[208:211], v193 offset:5120
	ds_read_b128 v[212:215], v193 offset:6144
	ds_read_b128 v[216:219], v193 offset:7168
	global_load_lds_dwordx4 v164, s[24:25]
	s_add_i32 m0, s39, 0xe000
	s_nop 0
	global_load_lds_dwordx4 v166, s[24:25]
	s_waitcnt vmcnt(8)
	s_waitcnt lgkmcnt(0)
	s_barrier
	s_setprio 1
	v_mfma_f32_16x16x32_bf16 v[124:127], v[128:131], v[180:183], v[124:127]
	v_mfma_f32_16x16x32_bf16 v[120:123], v[136:139], v[180:183], v[120:123]
	v_mfma_f32_16x16x32_bf16 v[108:111], v[128:131], v[196:199], v[108:111]
	v_mfma_f32_16x16x32_bf16 v[104:107], v[136:139], v[196:199], v[104:107]
	v_mfma_f32_16x16x32_bf16 v[92:95], v[128:131], v[204:207], v[92:95]
	v_mfma_f32_16x16x32_bf16 v[84:87], v[136:139], v[204:207], v[84:87]
	v_mfma_f32_16x16x32_bf16 v[76:79], v[128:131], v[212:215], v[76:79]
	v_mfma_f32_16x16x32_bf16 v[72:75], v[136:139], v[212:215], v[72:75]
	v_mfma_f32_16x16x32_bf16 v[124:127], v[132:135], v[184:187], v[124:127]
	v_mfma_f32_16x16x32_bf16 v[120:123], v[140:143], v[184:187], v[120:123]
	v_mfma_f32_16x16x32_bf16 v[108:111], v[132:135], v[200:203], v[108:111]
	v_mfma_f32_16x16x32_bf16 v[104:107], v[140:143], v[200:203], v[104:107]
	v_mfma_f32_16x16x32_bf16 v[92:95], v[132:135], v[208:211], v[92:95]
	v_mfma_f32_16x16x32_bf16 v[84:87], v[140:143], v[208:211], v[84:87]
	v_mfma_f32_16x16x32_bf16 v[76:79], v[132:135], v[216:219], v[76:79]
	v_mfma_f32_16x16x32_bf16 v[72:75], v[140:143], v[216:219], v[72:75]
	v_mfma_f32_16x16x32_bf16 v[116:119], v[144:147], v[180:183], v[116:119]
	v_mfma_f32_16x16x32_bf16 v[112:115], v[172:175], v[180:183], v[112:115]
	v_mfma_f32_16x16x32_bf16 v[100:103], v[144:147], v[196:199], v[100:103]
	v_mfma_f32_16x16x32_bf16 v[96:99], v[172:175], v[196:199], v[96:99]
	v_mfma_f32_16x16x32_bf16 v[88:91], v[144:147], v[204:207], v[88:91]
	v_mfma_f32_16x16x32_bf16 v[80:83], v[172:175], v[204:207], v[80:83]
	v_mfma_f32_16x16x32_bf16 v[68:71], v[144:147], v[212:215], v[68:71]
	v_mfma_f32_16x16x32_bf16 v[64:67], v[172:175], v[212:215], v[64:67]
	v_mfma_f32_16x16x32_bf16 v[116:119], v[148:151], v[184:187], v[116:119]
	v_mfma_f32_16x16x32_bf16 v[112:115], v[176:179], v[184:187], v[112:115]
	v_mfma_f32_16x16x32_bf16 v[100:103], v[148:151], v[200:203], v[100:103]
	v_mfma_f32_16x16x32_bf16 v[96:99], v[176:179], v[200:203], v[96:99]
	v_mfma_f32_16x16x32_bf16 v[88:91], v[148:151], v[208:211], v[88:91]
	v_mfma_f32_16x16x32_bf16 v[80:83], v[176:179], v[208:211], v[80:83]
	v_mfma_f32_16x16x32_bf16 v[68:71], v[148:151], v[216:219], v[68:71]
	v_mfma_f32_16x16x32_bf16 v[64:67], v[176:179], v[216:219], v[64:67]
	s_setprio 0
	s_barrier
	s_add_u32 s92, s26, s10
	s_addc_u32 s93, s27, s11
	s_add_u32 s94, s28, s10
	s_addc_u32 s95, s29, s11
	s_add_i32 s58, s47, s36
	s_mov_b32 m0, s58
	s_nop 0
	global_load_lds_dwordx4 v156, s[26:27]
	s_add_i32 m0, s58, 0x2000
	s_add_u32 s58, s26, 0x40000
	s_addc_u32 s59, s27, 0
	s_add_i32 s60, s48, s36
	global_load_lds_dwordx4 v152, s[26:27]
	s_mov_b32 m0, s60
	s_nop 0
	global_load_lds_dwordx4 v156, s[58:59]
	s_add_i32 m0, s60, 0x2000
	s_nop 0
	global_load_lds_dwordx4 v152, s[58:59]
	s_mov_b32 m0, s39
	s_nop 0
	global_load_lds_dwordx4 v158, s[28:29]
	s_mov_b32 m0, s40
	s_nop 0
	global_load_lds_dwordx4 v154, s[28:29]
	ds_read_b128 v[180:183], v193 offset:16384
	ds_read_b128 v[184:187], v193 offset:17408
	ds_read_b128 v[196:199], v193 offset:18432
	ds_read_b128 v[200:203], v193 offset:19456
	ds_read_b128 v[204:207], v193 offset:20480
	ds_read_b128 v[208:211], v193 offset:21504
	ds_read_b128 v[212:215], v193 offset:22528
	ds_read_b128 v[216:219], v193 offset:23552
	s_waitcnt vmcnt(8)
	s_waitcnt lgkmcnt(0)
	s_barrier
	s_setprio 1
	v_mfma_f32_16x16x32_bf16 v[60:63], v[128:131], v[180:183], v[60:63]
	v_mfma_f32_16x16x32_bf16 v[52:55], v[136:139], v[180:183], v[52:55]
	v_mfma_f32_16x16x32_bf16 v[44:47], v[128:131], v[196:199], v[44:47]
	v_mfma_f32_16x16x32_bf16 v[40:43], v[136:139], v[196:199], v[40:43]
	v_mfma_f32_16x16x32_bf16 v[28:31], v[128:131], v[204:207], v[28:31]
	v_mfma_f32_16x16x32_bf16 v[20:23], v[136:139], v[204:207], v[20:23]
	v_mfma_f32_16x16x32_bf16 v[12:15], v[128:131], v[212:215], v[12:15]
	v_mfma_f32_16x16x32_bf16 v[8:11], v[136:139], v[212:215], v[8:11]
	v_mfma_f32_16x16x32_bf16 v[60:63], v[132:135], v[184:187], v[60:63]
	v_mfma_f32_16x16x32_bf16 v[52:55], v[140:143], v[184:187], v[52:55]
	v_mfma_f32_16x16x32_bf16 v[44:47], v[132:135], v[200:203], v[44:47]
	v_mfma_f32_16x16x32_bf16 v[40:43], v[140:143], v[200:203], v[40:43]
	v_mfma_f32_16x16x32_bf16 v[28:31], v[132:135], v[208:211], v[28:31]
	v_mfma_f32_16x16x32_bf16 v[20:23], v[140:143], v[208:211], v[20:23]
	v_mfma_f32_16x16x32_bf16 v[12:15], v[132:135], v[216:219], v[12:15]
	v_mfma_f32_16x16x32_bf16 v[8:11], v[140:143], v[216:219], v[8:11]
	v_mfma_f32_16x16x32_bf16 v[56:59], v[144:147], v[180:183], v[56:59]
	v_mfma_f32_16x16x32_bf16 v[48:51], v[172:175], v[180:183], v[48:51]
	v_mfma_f32_16x16x32_bf16 v[36:39], v[144:147], v[196:199], v[36:39]
	v_mfma_f32_16x16x32_bf16 v[32:35], v[172:175], v[196:199], v[32:35]
	v_mfma_f32_16x16x32_bf16 v[24:27], v[144:147], v[204:207], v[24:27]
	v_mfma_f32_16x16x32_bf16 v[16:19], v[172:175], v[204:207], v[16:19]
	v_mfma_f32_16x16x32_bf16 v[4:7], v[144:147], v[212:215], v[4:7]
	v_mfma_f32_16x16x32_bf16 v[0:3], v[172:175], v[212:215], v[0:3]
	v_mfma_f32_16x16x32_bf16 v[56:59], v[148:151], v[184:187], v[56:59]
	v_mfma_f32_16x16x32_bf16 v[48:51], v[176:179], v[184:187], v[48:51]
	v_mfma_f32_16x16x32_bf16 v[36:39], v[148:151], v[200:203], v[36:39]
	v_mfma_f32_16x16x32_bf16 v[32:35], v[176:179], v[200:203], v[32:35]
	v_mfma_f32_16x16x32_bf16 v[24:27], v[148:151], v[208:211], v[24:27]
	v_mfma_f32_16x16x32_bf16 v[16:19], v[176:179], v[208:211], v[16:19]
	v_mfma_f32_16x16x32_bf16 v[4:7], v[148:151], v[216:219], v[4:7]
	v_mfma_f32_16x16x32_bf16 v[0:3], v[176:179], v[216:219], v[0:3]
	s_setprio 0
	s_barrier
; #define PG8_STAGE(bufoff, gbase, voff) do { _Pragma("unroll") for (int _i = 0; _i < 2; ++_i) \
;         __builtin_amdgcn_global_load_lds((const unsigned*)((const char*)(gbase) + (voff)[_i]), (PG8_LAS unsigned*)(lds + (bufoff) + ldsw + _i * 8192), 16, 0, 0); } while (0)
; #define PG8_LDA(dst, b, h) do { _Pragma("unroll") for (int m = 0; m < 4; ++m) _Pragma("unroll") for (int k = 0; k < 2; ++k) dst[m][k] = *(const PG8_LAS bf16x8*)(lds + PG8_SA(b, h) + aoff + m * 2048 + k * 1024); } while (0)
; #define PG8_LDB(dst, b, h) do { _Pragma("unroll") for (int n = 0; n < 2; ++n) _Pragma("unroll") for (int k = 0; k < 2; ++k) dst[n][k] = *(const PG8_LAS bf16x8*)(lds + PG8_SB(b, h) + boff + n * 2048 + k * 1024); } while (0)
; #define PG8_MMA(ai, bj, At, Bt) do { __builtin_amdgcn_s_setprio(1); _Pragma("unroll") for (int m = 0; m < 4; ++m) _Pragma("unroll") for (int n = 0; n < 2; ++n) _Pragma("unroll") for (int k = 0; k < 2; ++k) \
;         acc[ai][bj][m][n] = __builtin_amdgcn_mfma_f32_16x16x32_bf16(Bt[n][k], At[m][k], acc[ai][bj][m][n], 0, 0, 0); __builtin_amdgcn_s_setprio(0); } while (0)
; #define PG8_WAIT_V(n) asm volatile("s_waitcnt vmcnt(" #n ")" ::: "memory")
; #define PG8_WAIT_L(n) asm volatile("s_waitcnt lgkmcnt(" #n ")" ::: "memory")
; #define PG8_BAR __builtin_amdgcn_s_barrier()
; #define PG8_SCHED __builtin_amdgcn_sched_barrier(0)
; template <class Epi, class Sched, bool ALIGN_EPI = false, bool SP2 = false>
; __device__ __forceinline__ void gemm_phase(PG8_LAS unsigned char* lds, const Gemm g, const Sched& S, const Epi& E) {
;     ...
;             PG8_LDB(B0, 1, 0); PG8_LDB(B1, 1, 1); PG8_SCHED; PG8_LDA(At, 1, 0); PG8_STAGE(PG8_SA(0, 1), a2 + hstep, voffA);
;             PG8_WAIT_V(8); PG8_WAIT_L(0); PG8_BAR; PG8_MMA(0, 0, At, B0); PG8_MMA(0, 1, At, B1); PG8_BAR; PG8_SCHED;
;             PG8_LDA(At, 1, 1); PG8_STAGE(PG8_SB(1, 0), b3, voffB); PG8_STAGE(PG8_SB(1, 1), b3 + hstep, voffB); PG8_STAGE(PG8_SA(1, 0), a3, voffA);
;             PG8_WAIT_V(8); PG8_WAIT_L(0); PG8_BAR; PG8_MMA(1, 0, At, B0); PG8_MMA(1, 1, At, B1); PG8_BAR; PG8_SCHED;
;     ...
;         if constexpr (ALIGN_EPI) { if (wr == 0) PG8_BAR; }
.Lmy_peel_969_mid:
	s_add_i32 s58, 0, 0x18000
	s_add_i32 s59, 0, 0x1c000
	v_add_u32_e32 v140, s58, v190
	v_add_u32_e32 v176, s59, v190
	ds_read_b128 v[128:131], v140
	ds_read_b128 v[132:135], v140 offset:1024
	ds_read_b128 v[136:139], v140 offset:2048
	ds_read_b128 v[140:143], v140 offset:3072
	ds_read_b128 v[144:147], v176
	ds_read_b128 v[148:151], v176 offset:1024
	ds_read_b128 v[172:175], v176 offset:2048
	ds_read_b128 v[176:179], v176 offset:3072
	s_add_u32 s28, s28, 0x40000
	s_addc_u32 s29, s29, 0
	s_mov_b32 m0, s41
	ds_read_b128 v[180:183], v193 offset:32768
	ds_read_b128 v[184:187], v193 offset:33792
	ds_read_b128 v[196:199], v193 offset:34816
	ds_read_b128 v[200:203], v193 offset:35840
	ds_read_b128 v[204:207], v193 offset:36864
	ds_read_b128 v[208:211], v193 offset:37888
	ds_read_b128 v[212:215], v193 offset:38912
	ds_read_b128 v[216:219], v193 offset:39936
	global_load_lds_dwordx4 v158, s[28:29]
	s_mov_b32 m0, s42
	s_nop 0
	global_load_lds_dwordx4 v154, s[28:29]
	s_waitcnt vmcnt(8)
	s_waitcnt lgkmcnt(0)
	s_barrier
	s_setprio 1
	v_mfma_f32_16x16x32_bf16 v[124:127], v[128:131], v[180:183], v[124:127]
	v_mfma_f32_16x16x32_bf16 v[120:123], v[136:139], v[180:183], v[120:123]
	v_mfma_f32_16x16x32_bf16 v[108:111], v[128:131], v[196:199], v[108:111]
	v_mfma_f32_16x16x32_bf16 v[104:107], v[136:139], v[196:199], v[104:107]
	v_mfma_f32_16x16x32_bf16 v[92:95], v[128:131], v[204:207], v[92:95]
	v_mfma_f32_16x16x32_bf16 v[84:87], v[136:139], v[204:207], v[84:87]
	v_mfma_f32_16x16x32_bf16 v[76:79], v[128:131], v[212:215], v[76:79]
	v_mfma_f32_16x16x32_bf16 v[72:75], v[136:139], v[212:215], v[72:75]
	v_mfma_f32_16x16x32_bf16 v[124:127], v[132:135], v[184:187], v[124:127]
	v_mfma_f32_16x16x32_bf16 v[120:123], v[140:143], v[184:187], v[120:123]
	v_mfma_f32_16x16x32_bf16 v[108:111], v[132:135], v[200:203], v[108:111]
	v_mfma_f32_16x16x32_bf16 v[104:107], v[140:143], v[200:203], v[104:107]
	v_mfma_f32_16x16x32_bf16 v[92:95], v[132:135], v[208:211], v[92:95]
	v_mfma_f32_16x16x32_bf16 v[84:87], v[140:143], v[208:211], v[84:87]
	v_mfma_f32_16x16x32_bf16 v[76:79], v[132:135], v[216:219], v[76:79]
	v_mfma_f32_16x16x32_bf16 v[72:75], v[140:143], v[216:219], v[72:75]
	v_mfma_f32_16x16x32_bf16 v[116:119], v[144:147], v[180:183], v[116:119]
	v_mfma_f32_16x16x32_bf16 v[112:115], v[172:175], v[180:183], v[112:115]
	v_mfma_f32_16x16x32_bf16 v[100:103], v[144:147], v[196:199], v[100:103]
	v_mfma_f32_16x16x32_bf16 v[96:99], v[172:175], v[196:199], v[96:99]
	v_mfma_f32_16x16x32_bf16 v[88:91], v[144:147], v[204:207], v[88:91]
	v_mfma_f32_16x16x32_bf16 v[80:83], v[172:175], v[204:207], v[80:83]
	v_mfma_f32_16x16x32_bf16 v[68:71], v[144:147], v[212:215], v[68:71]
	v_mfma_f32_16x16x32_bf16 v[64:67], v[172:175], v[212:215], v[64:67]
	v_mfma_f32_16x16x32_bf16 v[116:119], v[148:151], v[184:187], v[116:119]
	v_mfma_f32_16x16x32_bf16 v[112:115], v[176:179], v[184:187], v[112:115]
	v_mfma_f32_16x16x32_bf16 v[100:103], v[148:151], v[200:203], v[100:103]
	v_mfma_f32_16x16x32_bf16 v[96:99], v[176:179], v[200:203], v[96:99]
	v_mfma_f32_16x16x32_bf16 v[88:91], v[148:151], v[208:211], v[88:91]
	v_mfma_f32_16x16x32_bf16 v[80:83], v[176:179], v[208:211], v[80:83]
	v_mfma_f32_16x16x32_bf16 v[68:71], v[148:151], v[216:219], v[68:71]
	v_mfma_f32_16x16x32_bf16 v[64:67], v[176:179], v[216:219], v[64:67]
	s_setprio 0
	s_barrier
	s_add_i32 s28, s58, s36
	s_mov_b32 m0, s28
	s_nop 0
	global_load_lds_dwordx4 v156, s[92:93]
	s_add_i32 m0, s28, 0x2000
	s_add_u32 s26, s26, 0x40080
	s_addc_u32 s27, s27, 0
	s_add_i32 s28, s59, s36
	global_load_lds_dwordx4 v152, s[92:93]
	s_mov_b32 m0, s28
	s_nop 0
	global_load_lds_dwordx4 v156, s[26:27]
	s_add_i32 m0, s28, 0x2000
	s_nop 0
	global_load_lds_dwordx4 v152, s[26:27]
	s_mov_b32 m0, s43
	s_nop 0
	global_load_lds_dwordx4 v158, s[94:95]
	s_mov_b32 m0, s44
	s_nop 0
	global_load_lds_dwordx4 v154, s[94:95]
	ds_read_b128 v[180:183], v193 offset:49152
	ds_read_b128 v[184:187], v193 offset:50176
	ds_read_b128 v[196:199], v193 offset:51200
	ds_read_b128 v[200:203], v193 offset:52224
	ds_read_b128 v[204:207], v193 offset:53248
	ds_read_b128 v[208:211], v193 offset:54272
	ds_read_b128 v[212:215], v193 offset:55296
	ds_read_b128 v[216:219], v193 offset:56320
	s_waitcnt vmcnt(8)
	s_waitcnt lgkmcnt(0)
	s_barrier
	s_setprio 1
	v_mfma_f32_16x16x32_bf16 v[60:63], v[128:131], v[180:183], v[60:63]
	v_mfma_f32_16x16x32_bf16 v[52:55], v[136:139], v[180:183], v[52:55]
	v_mfma_f32_16x16x32_bf16 v[44:47], v[128:131], v[196:199], v[44:47]
	v_mfma_f32_16x16x32_bf16 v[40:43], v[136:139], v[196:199], v[40:43]
	v_mfma_f32_16x16x32_bf16 v[28:31], v[128:131], v[204:207], v[28:31]
	v_mfma_f32_16x16x32_bf16 v[20:23], v[136:139], v[204:207], v[20:23]
	v_mfma_f32_16x16x32_bf16 v[12:15], v[128:131], v[212:215], v[12:15]
	v_mfma_f32_16x16x32_bf16 v[8:11], v[136:139], v[212:215], v[8:11]
	v_mfma_f32_16x16x32_bf16 v[60:63], v[132:135], v[184:187], v[60:63]
	v_mfma_f32_16x16x32_bf16 v[52:55], v[140:143], v[184:187], v[52:55]
	v_mfma_f32_16x16x32_bf16 v[44:47], v[132:135], v[200:203], v[44:47]
	v_mfma_f32_16x16x32_bf16 v[40:43], v[140:143], v[200:203], v[40:43]
	v_mfma_f32_16x16x32_bf16 v[28:31], v[132:135], v[208:211], v[28:31]
	v_mfma_f32_16x16x32_bf16 v[20:23], v[140:143], v[208:211], v[20:23]
	v_mfma_f32_16x16x32_bf16 v[12:15], v[132:135], v[216:219], v[12:15]
	v_mfma_f32_16x16x32_bf16 v[8:11], v[140:143], v[216:219], v[8:11]
	v_mfma_f32_16x16x32_bf16 v[56:59], v[144:147], v[180:183], v[56:59]
	v_mfma_f32_16x16x32_bf16 v[48:51], v[172:175], v[180:183], v[48:51]
	v_mfma_f32_16x16x32_bf16 v[36:39], v[144:147], v[196:199], v[36:39]
	v_mfma_f32_16x16x32_bf16 v[32:35], v[172:175], v[196:199], v[32:35]
	v_mfma_f32_16x16x32_bf16 v[24:27], v[144:147], v[204:207], v[24:27]
	v_mfma_f32_16x16x32_bf16 v[16:19], v[172:175], v[204:207], v[16:19]
	v_mfma_f32_16x16x32_bf16 v[4:7], v[144:147], v[212:215], v[4:7]
	v_mfma_f32_16x16x32_bf16 v[0:3], v[172:175], v[212:215], v[0:3]
	v_mfma_f32_16x16x32_bf16 v[56:59], v[148:151], v[184:187], v[56:59]
	v_mfma_f32_16x16x32_bf16 v[48:51], v[176:179], v[184:187], v[48:51]
	v_mfma_f32_16x16x32_bf16 v[36:39], v[148:151], v[200:203], v[36:39]
	v_mfma_f32_16x16x32_bf16 v[32:35], v[176:179], v[200:203], v[32:35]
	v_mfma_f32_16x16x32_bf16 v[24:27], v[148:151], v[208:211], v[24:27]
	v_mfma_f32_16x16x32_bf16 v[16:19], v[176:179], v[208:211], v[16:19]
	v_mfma_f32_16x16x32_bf16 v[4:7], v[148:151], v[216:219], v[4:7]
	v_mfma_f32_16x16x32_bf16 v[0:3], v[176:179], v[216:219], v[0:3]
	s_setprio 0
	s_barrier
	s_add_i32 s57, s57, 2
	s_add_u32 s24, s24, 0x100
	s_addc_u32 s25, s25, 0
	s_add_u32 s55, s55, 0x100
	s_addc_u32 s56, s56, 0
	s_cmp_gt_u32 s57, 13
	s_cbranch_scc0 .LBB0_969
	s_and_b64 vcc, exec, s[12:13]
	s_cbranch_vccz .LBB0_972
	s_barrier

;     __host__ __device__ bool next(int i, Unit& u) const { const long L = (long)i * G + c; if (L >= nwg) return false; return unit_of((int)L, u); }
;     __host__ __device__ bool next(int i, Unit& u) const { const int L = i == 0 ? l0 : (i == 1 ? l1 : (i == 2 ? l2 : -1)); if (L < 0 || L >= s.nwg) return false; return s.unit_of(L, u); }
;     __host__ __device__ bool next(int i, Unit& u) const { const bool ok = s.next(i >> 1, u); u.kh = i & 1; return ok; }
; #define PG8_STAGE(bufoff, gbase, voff) do { _Pragma("unroll") for (int _i = 0; _i < 2; ++_i) \
;         __builtin_amdgcn_global_load_lds((const unsigned*)((const char*)(gbase) + (voff)[_i]), (PG8_LAS unsigned*)(lds + (bufoff) + ldsw + _i * 8192), 16, 0, 0); } while (0)
; #define PG8_LDA(dst, b, h) do { _Pragma("unroll") for (int m = 0; m < 4; ++m) _Pragma("unroll") for (int k = 0; k < 2; ++k) dst[m][k] = *(const PG8_LAS bf16x8*)(lds + PG8_SA(b, h) + aoff + m * 2048 + k * 1024); } while (0)
; template <class Epi, class Sched, bool ALIGN_EPI = false, bool SP2 = false>
; __device__ __forceinline__ void gemm_phase(PG8_LAS unsigned char* lds, const Gemm g, const Sched& S, const Epi& E) {
;     ...
;         const bool has_next = S.next(ui + 1, nxt);
;         const char* nA = has_next ? (const char*)g.A + (size_t)nxt.pm * tstep + nxt.kh * khb : cA; const char* nB = has_next ? (const char*)g.Bt + (size_t)nxt.pn * tstep + nxt.kh * khb : cB;
;         for (int t = 0; t < nt; t += 2) {
;             const bool last = (t == nt - 2);
;             const char* a1 = cA + (size_t)(t + 1) * kstep;
;             const char* a2 = last ? nA : cA + (size_t)(t + 2) * kstep; const char* b2 = last ? nB : cB + (size_t)(t + 2) * kstep;
;             const char* a3 = a2 + kstep; const char* b3 = b2 + kstep;
;             if (last && has_next) S.a_ready(nxt);
;             if constexpr (SP2) {
;             PG8_LDB(B0, 0, 0); PG8_LDB(B1, 0, 1); PG8_SCHED; PG8_LDA(At, 0, 0); PG8_STAGE(PG8_SA(1, 1), a1 + hstep, voffA);
;             PG8_WAIT_V(8); PG8_WAIT_L(0); PG8_BAR; PG8_MMA(0, 0, At, B0); PG8_MMA(0, 1, At, B1); PG8_BAR; PG8_SCHED;
;             PG8_LDA(At, 0, 1); PG8_STAGE(PG8_SB(0, 0), b2, voffB); PG8_STAGE(PG8_SB(0, 1), b2 + hstep, voffB); PG8_STAGE(PG8_SA(0, 0), a2, voffA);
;             PG8_WAIT_V(8); PG8_WAIT_L(0); PG8_BAR; PG8_MMA(1, 0, At, B0); PG8_MMA(1, 1, At, B1); PG8_BAR; PG8_SCHED;
.LBB0_1051:
	s_add_u32 s54, s24, 0x100
	s_addc_u32 s55, s25, 0
	s_mov_b32 s56, -2
	ds_read_b128 v[146:149], v153
	ds_read_b128 v[156:159], v153 offset:1024
	ds_read_b128 v[160:163], v153 offset:2048
	ds_read_b128 v[164:167], v153 offset:3072
	ds_read_b128 v[168:171], v154
	ds_read_b128 v[172:175], v154 offset:1024
	ds_read_b128 v[176:179], v154 offset:2048
	ds_read_b128 v[180:183], v154 offset:3072
	s_add_u32 s24, s22, 0x100
	s_addc_u32 s25, s23, 0
	s_cmp_eq_u32 s56, 40
	s_cselect_b32 s29, s3, s25
	s_cselect_b32 s28, s2, s24
	s_cselect_b32 s27, s21, s55
	s_cselect_b32 s26, s20, s54
	s_add_i32 m0, s38, 0xc000
	ds_read_b128 v[184:187], v155
	ds_read_b128 v[188:191], v155 offset:1024
	ds_read_b128 v[192:195], v155 offset:2048
	ds_read_b128 v[196:199], v155 offset:3072
	ds_read_b128 v[200:203], v155 offset:4096
	ds_read_b128 v[204:207], v155 offset:5120
	ds_read_b128 v[208:211], v155 offset:6144
	ds_read_b128 v[212:215], v155 offset:7168
	global_load_lds_dwordx4 v138, s[22:23]
	s_add_i32 m0, s38, 0xe000
	s_nop 0
	global_load_lds_dwordx4 v140, s[22:23]
	s_waitcnt vmcnt(8)
	s_waitcnt lgkmcnt(0)
	s_barrier
	s_setprio 1
	v_mfma_f32_16x16x32_bf16 v[124:127], v[146:149], v[184:187], 0
	v_mfma_f32_16x16x32_bf16 v[120:123], v[160:163], v[184:187], 0
	v_mfma_f32_16x16x32_bf16 v[116:119], v[146:149], v[192:195], 0
	v_mfma_f32_16x16x32_bf16 v[112:115], v[160:163], v[192:195], 0
	v_mfma_f32_16x16x32_bf16 v[92:95], v[146:149], v[200:203], 0
	v_mfma_f32_16x16x32_bf16 v[88:91], v[160:163], v[200:203], 0
	v_mfma_f32_16x16x32_bf16 v[76:79], v[146:149], v[208:211], 0
	v_mfma_f32_16x16x32_bf16 v[72:75], v[160:163], v[208:211], 0
	v_mfma_f32_16x16x32_bf16 v[124:127], v[156:159], v[188:191], v[124:127]
	v_mfma_f32_16x16x32_bf16 v[120:123], v[164:167], v[188:191], v[120:123]
	v_mfma_f32_16x16x32_bf16 v[116:119], v[156:159], v[196:199], v[116:119]
	v_mfma_f32_16x16x32_bf16 v[112:115], v[164:167], v[196:199], v[112:115]
	v_mfma_f32_16x16x32_bf16 v[92:95], v[156:159], v[204:207], v[92:95]
	v_mfma_f32_16x16x32_bf16 v[88:91], v[164:167], v[204:207], v[88:91]
	v_mfma_f32_16x16x32_bf16 v[76:79], v[156:159], v[212:215], v[76:79]
	v_mfma_f32_16x16x32_bf16 v[72:75], v[164:167], v[212:215], v[72:75]
	v_mfma_f32_16x16x32_bf16 v[108:111], v[168:171], v[184:187], 0
	v_mfma_f32_16x16x32_bf16 v[104:107], v[176:179], v[184:187], 0
	v_mfma_f32_16x16x32_bf16 v[100:103], v[168:171], v[192:195], 0
	v_mfma_f32_16x16x32_bf16 v[96:99], v[176:179], v[192:195], 0
	v_mfma_f32_16x16x32_bf16 v[84:87], v[168:171], v[200:203], 0
	v_mfma_f32_16x16x32_bf16 v[80:83], v[176:179], v[200:203], 0
	v_mfma_f32_16x16x32_bf16 v[68:71], v[168:171], v[208:211], 0
	v_mfma_f32_16x16x32_bf16 v[64:67], v[176:179], v[208:211], 0
	v_mfma_f32_16x16x32_bf16 v[108:111], v[172:175], v[188:191], v[108:111]
	v_mfma_f32_16x16x32_bf16 v[104:107], v[180:183], v[188:191], v[104:107]
	v_mfma_f32_16x16x32_bf16 v[100:103], v[172:175], v[196:199], v[100:103]
	v_mfma_f32_16x16x32_bf16 v[96:99], v[180:183], v[196:199], v[96:99]
	v_mfma_f32_16x16x32_bf16 v[84:87], v[172:175], v[204:207], v[84:87]
	v_mfma_f32_16x16x32_bf16 v[80:83], v[180:183], v[204:207], v[80:83]
	v_mfma_f32_16x16x32_bf16 v[68:71], v[172:175], v[212:215], v[68:71]
	v_mfma_f32_16x16x32_bf16 v[64:67], v[180:183], v[212:215], v[64:67]
	s_setprio 0
	s_barrier
	s_add_u32 s92, s26, s8
	s_addc_u32 s93, s27, s9
	s_add_u32 s94, s28, s8
	s_addc_u32 s95, s29, s9
	s_add_i32 s22, s46, s37
	s_mov_b32 m0, s22
	s_nop 0
	global_load_lds_dwordx4 v130, s[26:27]
	s_add_i32 m0, s22, 0x2000
	s_add_u32 s22, s26, 0xb0000
	s_addc_u32 s23, s27, 0
	s_add_i32 s57, s47, s37
	global_load_lds_dwordx4 v134, s[26:27]
	s_mov_b32 m0, s57
	s_nop 0
	global_load_lds_dwordx4 v130, s[22:23]
	s_add_i32 m0, s57, 0x2000
	s_nop 0
	global_load_lds_dwordx4 v134, s[22:23]
	s_mov_b32 m0, s38
	s_nop 0
	global_load_lds_dwordx4 v128, s[28:29]
	s_mov_b32 m0, s39
	s_nop 0
	global_load_lds_dwordx4 v132, s[28:29]
	ds_read_b128 v[184:187], v155 offset:16384
	ds_read_b128 v[188:191], v155 offset:17408
	ds_read_b128 v[192:195], v155 offset:18432
	ds_read_b128 v[196:199], v155 offset:19456
	ds_read_b128 v[200:203], v155 offset:20480
	ds_read_b128 v[204:207], v155 offset:21504
	ds_read_b128 v[208:211], v155 offset:22528
	ds_read_b128 v[212:215], v155 offset:23552
	s_waitcnt vmcnt(8)
	s_waitcnt lgkmcnt(0)
	s_barrier
	s_setprio 1
	v_mfma_f32_16x16x32_bf16 v[60:63], v[146:149], v[184:187], 0
	v_mfma_f32_16x16x32_bf16 v[56:59], v[160:163], v[184:187], 0
	v_mfma_f32_16x16x32_bf16 v[44:47], v[146:149], v[192:195], 0
	v_mfma_f32_16x16x32_bf16 v[40:43], v[160:163], v[192:195], 0
	v_mfma_f32_16x16x32_bf16 v[28:31], v[146:149], v[200:203], 0
	v_mfma_f32_16x16x32_bf16 v[24:27], v[160:163], v[200:203], 0
	v_mfma_f32_16x16x32_bf16 v[12:15], v[146:149], v[208:211], 0
	v_mfma_f32_16x16x32_bf16 v[8:11], v[160:163], v[208:211], 0
	v_mfma_f32_16x16x32_bf16 v[60:63], v[156:159], v[188:191], v[60:63]
	v_mfma_f32_16x16x32_bf16 v[56:59], v[164:167], v[188:191], v[56:59]
	v_mfma_f32_16x16x32_bf16 v[44:47], v[156:159], v[196:199], v[44:47]
	v_mfma_f32_16x16x32_bf16 v[40:43], v[164:167], v[196:199], v[40:43]
	v_mfma_f32_16x16x32_bf16 v[28:31], v[156:159], v[204:207], v[28:31]
	v_mfma_f32_16x16x32_bf16 v[24:27], v[164:167], v[204:207], v[24:27]
	v_mfma_f32_16x16x32_bf16 v[12:15], v[156:159], v[212:215], v[12:15]
	v_mfma_f32_16x16x32_bf16 v[8:11], v[164:167], v[212:215], v[8:11]
	v_mfma_f32_16x16x32_bf16 v[52:55], v[168:171], v[184:187], 0
	v_mfma_f32_16x16x32_bf16 v[48:51], v[176:179], v[184:187], 0
	v_mfma_f32_16x16x32_bf16 v[36:39], v[168:171], v[192:195], 0
	v_mfma_f32_16x16x32_bf16 v[32:35], v[176:179], v[192:195], 0
	v_mfma_f32_16x16x32_bf16 v[20:23], v[168:171], v[200:203], 0
	v_mfma_f32_16x16x32_bf16 v[16:19], v[176:179], v[200:203], 0
	v_mfma_f32_16x16x32_bf16 v[4:7], v[168:171], v[208:211], 0
	v_mfma_f32_16x16x32_bf16 v[0:3], v[176:179], v[208:211], 0
	v_mfma_f32_16x16x32_bf16 v[52:55], v[172:175], v[188:191], v[52:55]
	v_mfma_f32_16x16x32_bf16 v[48:51], v[180:183], v[188:191], v[48:51]
	v_mfma_f32_16x16x32_bf16 v[36:39], v[172:175], v[196:199], v[36:39]
	v_mfma_f32_16x16x32_bf16 v[32:35], v[180:183], v[196:199], v[32:35]
	v_mfma_f32_16x16x32_bf16 v[20:23], v[172:175], v[204:207], v[20:23]
	v_mfma_f32_16x16x32_bf16 v[16:19], v[180:183], v[204:207], v[16:19]
	v_mfma_f32_16x16x32_bf16 v[4:7], v[172:175], v[212:215], v[4:7]
	v_mfma_f32_16x16x32_bf16 v[0:3], v[180:183], v[212:215], v[0:3]
	s_setprio 0
	s_barrier
	s_branch .Lmy_peel_1052_mid
; #define PG8_STAGE(bufoff, gbase, voff) do { _Pragma("unroll") for (int _i = 0; _i < 2; ++_i) \
;         __builtin_amdgcn_global_load_lds((const unsigned*)((const char*)(gbase) + (voff)[_i]), (PG8_LAS unsigned*)(lds + (bufoff) + ldsw + _i * 8192), 16, 0, 0); } while (0)
; #define PG8_LDA(dst, b, h) do { _Pragma("unroll") for (int m = 0; m < 4; ++m) _Pragma("unroll") for (int k = 0; k < 2; ++k) dst[m][k] = *(const PG8_LAS bf16x8*)(lds + PG8_SA(b, h) + aoff + m * 2048 + k * 1024); } while (0)
; #define PG8_LDB(dst, b, h) do { _Pragma("unroll") for (int n = 0; n < 2; ++n) _Pragma("unroll") for (int k = 0; k < 2; ++k) dst[n][k] = *(const PG8_LAS bf16x8*)(lds + PG8_SB(b, h) + boff + n * 2048 + k * 1024); } while (0)
; #define PG8_MMA(ai, bj, At, Bt) do { __builtin_amdgcn_s_setprio(1); _Pragma("unroll") for (int m = 0; m < 4; ++m) _Pragma("unroll") for (int n = 0; n < 2; ++n) _Pragma("unroll") for (int k = 0; k < 2; ++k) \
;         acc[ai][bj][m][n] = __builtin_amdgcn_mfma_f32_16x16x32_bf16(Bt[n][k], At[m][k], acc[ai][bj][m][n], 0, 0, 0); __builtin_amdgcn_s_setprio(0); } while (0)
; #define PG8_WAIT_V(n) asm volatile("s_waitcnt vmcnt(" #n ")" ::: "memory")
; #define PG8_WAIT_L(n) asm volatile("s_waitcnt lgkmcnt(" #n ")" ::: "memory")
; #define PG8_BAR __builtin_amdgcn_s_barrier()
; #define PG8_SCHED __builtin_amdgcn_sched_barrier(0)
; template <class Epi, class Sched, bool ALIGN_EPI = false, bool SP2 = false>
; __device__ __forceinline__ void gemm_phase(PG8_LAS unsigned char* lds, const Gemm g, const Sched& S, const Epi& E) {
;     ...
;             PG8_LDB(B0, 0, 0); PG8_LDB(B1, 0, 1); PG8_SCHED; PG8_LDA(At, 0, 0); PG8_STAGE(PG8_SA(1, 1), a1 + hstep, voffA);
;             PG8_WAIT_V(8); PG8_WAIT_L(0); PG8_BAR; PG8_MMA(0, 0, At, B0); PG8_MMA(0, 1, At, B1); PG8_BAR; PG8_SCHED;
;             PG8_LDA(At, 0, 1); PG8_STAGE(PG8_SB(0, 0), b2, voffB); PG8_STAGE(PG8_SB(0, 1), b2 + hstep, voffB); PG8_STAGE(PG8_SA(0, 0), a2, voffA);
;             PG8_WAIT_V(8); PG8_WAIT_L(0); PG8_BAR; PG8_MMA(1, 0, At, B0); PG8_MMA(1, 1, At, B1); PG8_BAR; PG8_SCHED;
.LBB0_1052:
	ds_read_b128 v[146:149], v153
	ds_read_b128 v[156:159], v153 offset:1024
	ds_read_b128 v[160:163], v153 offset:2048
	ds_read_b128 v[164:167], v153 offset:3072
	ds_read_b128 v[168:171], v154
	ds_read_b128 v[172:175], v154 offset:1024
	ds_read_b128 v[176:179], v154 offset:2048
	ds_read_b128 v[180:183], v154 offset:3072
	s_add_u32 s24, s22, 0x100
	s_addc_u32 s25, s23, 0
	s_cmp_eq_u32 s56, 40
	s_cselect_b32 s29, s3, s25
	s_cselect_b32 s28, s2, s24
	s_cselect_b32 s27, s21, s55
	s_cselect_b32 s26, s20, s54
	s_add_i32 m0, s38, 0xc000
	ds_read_b128 v[184:187], v155
	ds_read_b128 v[188:191], v155 offset:1024
	ds_read_b128 v[192:195], v155 offset:2048
	ds_read_b128 v[196:199], v155 offset:3072
	ds_read_b128 v[200:203], v155 offset:4096
	ds_read_b128 v[204:207], v155 offset:5120
	ds_read_b128 v[208:211], v155 offset:6144
	ds_read_b128 v[212:215], v155 offset:7168
	global_load_lds_dwordx4 v138, s[22:23]
	s_add_i32 m0, s38, 0xe000
	s_nop 0
	global_load_lds_dwordx4 v140, s[22:23]
	s_waitcnt vmcnt(8)
	s_waitcnt lgkmcnt(0)
	s_barrier
	s_setprio 1
	v_mfma_f32_16x16x32_bf16 v[124:127], v[146:149], v[184:187], v[124:127]
	v_mfma_f32_16x16x32_bf16 v[120:123], v[160:163], v[184:187], v[120:123]
	v_mfma_f32_16x16x32_bf16 v[116:119], v[146:149], v[192:195], v[116:119]
	v_mfma_f32_16x16x32_bf16 v[112:115], v[160:163], v[192:195], v[112:115]
	v_mfma_f32_16x16x32_bf16 v[92:95], v[146:149], v[200:203], v[92:95]
	v_mfma_f32_16x16x32_bf16 v[88:91], v[160:163], v[200:203], v[88:91]
	v_mfma_f32_16x16x32_bf16 v[76:79], v[146:149], v[208:211], v[76:79]
	v_mfma_f32_16x16x32_bf16 v[72:75], v[160:163], v[208:211], v[72:75]
	v_mfma_f32_16x16x32_bf16 v[124:127], v[156:159], v[188:191], v[124:127]
	v_mfma_f32_16x16x32_bf16 v[120:123], v[164:167], v[188:191], v[120:123]
	v_mfma_f32_16x16x32_bf16 v[116:119], v[156:159], v[196:199], v[116:119]
	v_mfma_f32_16x16x32_bf16 v[112:115], v[164:167], v[196:199], v[112:115]
	v_mfma_f32_16x16x32_bf16 v[92:95], v[156:159], v[204:207], v[92:95]
	v_mfma_f32_16x16x32_bf16 v[88:91], v[164:167], v[204:207], v[88:91]
	v_mfma_f32_16x16x32_bf16 v[76:79], v[156:159], v[212:215], v[76:79]
	v_mfma_f32_16x16x32_bf16 v[72:75], v[164:167], v[212:215], v[72:75]
	v_mfma_f32_16x16x32_bf16 v[108:111], v[168:171], v[184:187], v[108:111]
	v_mfma_f32_16x16x32_bf16 v[104:107], v[176:179], v[184:187], v[104:107]
	v_mfma_f32_16x16x32_bf16 v[100:103], v[168:171], v[192:195], v[100:103]
	v_mfma_f32_16x16x32_bf16 v[96:99], v[176:179], v[192:195], v[96:99]
	v_mfma_f32_16x16x32_bf16 v[84:87], v[168:171], v[200:203], v[84:87]
	v_mfma_f32_16x16x32_bf16 v[80:83], v[176:179], v[200:203], v[80:83]
	v_mfma_f32_16x16x32_bf16 v[68:71], v[168:171], v[208:211], v[68:71]
	v_mfma_f32_16x16x32_bf16 v[64:67], v[176:179], v[208:211], v[64:67]
	v_mfma_f32_16x16x32_bf16 v[108:111], v[172:175], v[188:191], v[108:111]
	v_mfma_f32_16x16x32_bf16 v[104:107], v[180:183], v[188:191], v[104:107]
	v_mfma_f32_16x16x32_bf16 v[100:103], v[172:175], v[196:199], v[100:103]
	v_mfma_f32_16x16x32_bf16 v[96:99], v[180:183], v[196:199], v[96:99]
	v_mfma_f32_16x16x32_bf16 v[84:87], v[172:175], v[204:207], v[84:87]
	v_mfma_f32_16x16x32_bf16 v[80:83], v[180:183], v[204:207], v[80:83]
	v_mfma_f32_16x16x32_bf16 v[68:71], v[172:175], v[212:215], v[68:71]
	v_mfma_f32_16x16x32_bf16 v[64:67], v[180:183], v[212:215], v[64:67]
	s_setprio 0
	s_barrier
	s_add_u32 s92, s26, s8
	s_addc_u32 s93, s27, s9
	s_add_u32 s94, s28, s8
	s_addc_u32 s95, s29, s9
	s_add_i32 s22, s46, s37
	s_mov_b32 m0, s22
	s_nop 0
	global_load_lds_dwordx4 v130, s[26:27]
	s_add_i32 m0, s22, 0x2000
	s_add_u32 s22, s26, 0xb0000
	s_addc_u32 s23, s27, 0
	s_add_i32 s57, s47, s37
	global_load_lds_dwordx4 v134, s[26:27]
	s_mov_b32 m0, s57
	s_nop 0
	global_load_lds_dwordx4 v130, s[22:23]
	s_add_i32 m0, s57, 0x2000
	s_nop 0
	global_load_lds_dwordx4 v134, s[22:23]
	s_mov_b32 m0, s38
	s_nop 0
	global_load_lds_dwordx4 v128, s[28:29]
	s_mov_b32 m0, s39
	s_nop 0
	global_load_lds_dwordx4 v132, s[28:29]
	ds_read_b128 v[184:187], v155 offset:16384
	ds_read_b128 v[188:191], v155 offset:17408
	ds_read_b128 v[192:195], v155 offset:18432
	ds_read_b128 v[196:199], v155 offset:19456
	ds_read_b128 v[200:203], v155 offset:20480
	ds_read_b128 v[204:207], v155 offset:21504
	ds_read_b128 v[208:211], v155 offset:22528
	ds_read_b128 v[212:215], v155 offset:23552
	s_waitcnt vmcnt(8)
	s_waitcnt lgkmcnt(0)
	s_barrier
	s_setprio 1
	v_mfma_f32_16x16x32_bf16 v[60:63], v[146:149], v[184:187], v[60:63]
	v_mfma_f32_16x16x32_bf16 v[56:59], v[160:163], v[184:187], v[56:59]
	v_mfma_f32_16x16x32_bf16 v[44:47], v[146:149], v[192:195], v[44:47]
	v_mfma_f32_16x16x32_bf16 v[40:43], v[160:163], v[192:195], v[40:43]
	v_mfma_f32_16x16x32_bf16 v[28:31], v[146:149], v[200:203], v[28:31]
	v_mfma_f32_16x16x32_bf16 v[24:27], v[160:163], v[200:203], v[24:27]
	v_mfma_f32_16x16x32_bf16 v[12:15], v[146:149], v[208:211], v[12:15]
	v_mfma_f32_16x16x32_bf16 v[8:11], v[160:163], v[208:211], v[8:11]
	v_mfma_f32_16x16x32_bf16 v[60:63], v[156:159], v[188:191], v[60:63]
	v_mfma_f32_16x16x32_bf16 v[56:59], v[164:167], v[188:191], v[56:59]
	v_mfma_f32_16x16x32_bf16 v[44:47], v[156:159], v[196:199], v[44:47]
	v_mfma_f32_16x16x32_bf16 v[40:43], v[164:167], v[196:199], v[40:43]
	v_mfma_f32_16x16x32_bf16 v[28:31], v[156:159], v[204:207], v[28:31]
	v_mfma_f32_16x16x32_bf16 v[24:27], v[164:167], v[204:207], v[24:27]
	v_mfma_f32_16x16x32_bf16 v[12:15], v[156:159], v[212:215], v[12:15]
	v_mfma_f32_16x16x32_bf16 v[8:11], v[164:167], v[212:215], v[8:11]
	v_mfma_f32_16x16x32_bf16 v[52:55], v[168:171], v[184:187], v[52:55]
	v_mfma_f32_16x16x32_bf16 v[48:51], v[176:179], v[184:187], v[48:51]
	v_mfma_f32_16x16x32_bf16 v[36:39], v[168:171], v[192:195], v[36:39]
	v_mfma_f32_16x16x32_bf16 v[32:35], v[176:179], v[192:195], v[32:35]
	v_mfma_f32_16x16x32_bf16 v[20:23], v[168:171], v[200:203], v[20:23]
	v_mfma_f32_16x16x32_bf16 v[16:19], v[176:179], v[200:203], v[16:19]
	v_mfma_f32_16x16x32_bf16 v[4:7], v[168:171], v[208:211], v[4:7]
	v_mfma_f32_16x16x32_bf16 v[0:3], v[176:179], v[208:211], v[0:3]
	v_mfma_f32_16x16x32_bf16 v[52:55], v[172:175], v[188:191], v[52:55]
	v_mfma_f32_16x16x32_bf16 v[48:51], v[180:183], v[188:191], v[48:51]
	v_mfma_f32_16x16x32_bf16 v[36:39], v[172:175], v[196:199], v[36:39]
	v_mfma_f32_16x16x32_bf16 v[32:35], v[180:183], v[196:199], v[32:35]
	v_mfma_f32_16x16x32_bf16 v[20:23], v[172:175], v[204:207], v[20:23]
	v_mfma_f32_16x16x32_bf16 v[16:19], v[180:183], v[204:207], v[16:19]
	v_mfma_f32_16x16x32_bf16 v[4:7], v[172:175], v[212:215], v[4:7]
	v_mfma_f32_16x16x32_bf16 v[0:3], v[180:183], v[212:215], v[0:3]
	s_setprio 0
	s_barrier
; #define PG8_STAGE(bufoff, gbase, voff) do { _Pragma("unroll") for (int _i = 0; _i < 2; ++_i) \
;         __builtin_amdgcn_global_load_lds((const unsigned*)((const char*)(gbase) + (voff)[_i]), (PG8_LAS unsigned*)(lds + (bufoff) + ldsw + _i * 8192), 16, 0, 0); } while (0)
; #define PG8_LDA(dst, b, h) do { _Pragma("unroll") for (int m = 0; m < 4; ++m) _Pragma("unroll") for (int k = 0; k < 2; ++k) dst[m][k] = *(const PG8_LAS bf16x8*)(lds + PG8_SA(b, h) + aoff + m * 2048 + k * 1024); } while (0)
; #define PG8_LDB(dst, b, h) do { _Pragma("unroll") for (int n = 0; n < 2; ++n) _Pragma("unroll") for (int k = 0; k < 2; ++k) dst[n][k] = *(const PG8_LAS bf16x8*)(lds + PG8_SB(b, h) + boff + n * 2048 + k * 1024); } while (0)
; #define PG8_MMA(ai, bj, At, Bt) do { __builtin_amdgcn_s_setprio(1); _Pragma("unroll") for (int m = 0; m < 4; ++m) _Pragma("unroll") for (int n = 0; n < 2; ++n) _Pragma("unroll") for (int k = 0; k < 2; ++k) \
;         acc[ai][bj][m][n] = __builtin_amdgcn_mfma_f32_16x16x32_bf16(Bt[n][k], At[m][k], acc[ai][bj][m][n], 0, 0, 0); __builtin_amdgcn_s_setprio(0); } while (0)
; #define PG8_WAIT_V(n) asm volatile("s_waitcnt vmcnt(" #n ")" ::: "memory")
; #define PG8_WAIT_L(n) asm volatile("s_waitcnt lgkmcnt(" #n ")" ::: "memory")
; #define PG8_BAR __builtin_amdgcn_s_barrier()
; #define PG8_SCHED __builtin_amdgcn_sched_barrier(0)
; template <class Epi, class Sched, bool ALIGN_EPI = false, bool SP2 = false>
; __device__ __forceinline__ void gemm_phase(PG8_LAS unsigned char* lds, const Gemm g, const Sched& S, const Epi& E) {
;     ...
;             PG8_LDB(B0, 1, 0); PG8_LDB(B1, 1, 1); PG8_SCHED; PG8_LDA(At, 1, 0); PG8_STAGE(PG8_SA(0, 1), a2 + hstep, voffA);
;             PG8_WAIT_V(8); PG8_WAIT_L(0); PG8_BAR; PG8_MMA(0, 0, At, B0); PG8_MMA(0, 1, At, B1); PG8_BAR; PG8_SCHED;
;             PG8_LDA(At, 1, 1); PG8_STAGE(PG8_SB(1, 0), b3, voffB); PG8_STAGE(PG8_SB(1, 1), b3 + hstep, voffB); PG8_STAGE(PG8_SA(1, 0), a3, voffA);
;             PG8_WAIT_V(8); PG8_WAIT_L(0); PG8_BAR; PG8_MMA(1, 0, At, B0); PG8_MMA(1, 1, At, B1); PG8_BAR; PG8_SCHED;
;     ...
;         if constexpr (ALIGN_EPI) { if (wr == 0) PG8_BAR; }
.Lmy_peel_1052_mid:
	s_add_i32 s57, 0, 0x18000
	s_add_i32 s58, 0, 0x1c000
	v_add_u32_e32 v164, s57, v152
	v_add_u32_e32 v180, s58, v152
	ds_read_b128 v[146:149], v164
	ds_read_b128 v[156:159], v164 offset:1024
	ds_read_b128 v[160:163], v164 offset:2048
	ds_read_b128 v[164:167], v164 offset:3072
	ds_read_b128 v[168:171], v180
	ds_read_b128 v[172:175], v180 offset:1024
	ds_read_b128 v[176:179], v180 offset:2048
	ds_read_b128 v[180:183], v180 offset:3072
	s_add_u32 s22, s28, 0xb0000
	s_addc_u32 s23, s29, 0
	s_mov_b32 m0, s40
	ds_read_b128 v[184:187], v155 offset:32768
	ds_read_b128 v[188:191], v155 offset:33792
	ds_read_b128 v[192:195], v155 offset:34816
	ds_read_b128 v[196:199], v155 offset:35840
	ds_read_b128 v[200:203], v155 offset:36864
	ds_read_b128 v[204:207], v155 offset:37888
	ds_read_b128 v[208:211], v155 offset:38912
	ds_read_b128 v[212:215], v155 offset:39936
	global_load_lds_dwordx4 v128, s[22:23]
	s_mov_b32 m0, s41
	s_nop 0
	global_load_lds_dwordx4 v132, s[22:23]
	s_waitcnt vmcnt(8)
	s_waitcnt lgkmcnt(0)
	s_barrier
	s_setprio 1
	v_mfma_f32_16x16x32_bf16 v[124:127], v[146:149], v[184:187], v[124:127]
	v_mfma_f32_16x16x32_bf16 v[120:123], v[160:163], v[184:187], v[120:123]
	v_mfma_f32_16x16x32_bf16 v[116:119], v[146:149], v[192:195], v[116:119]
	v_mfma_f32_16x16x32_bf16 v[112:115], v[160:163], v[192:195], v[112:115]
	v_mfma_f32_16x16x32_bf16 v[92:95], v[146:149], v[200:203], v[92:95]
	v_mfma_f32_16x16x32_bf16 v[88:91], v[160:163], v[200:203], v[88:91]
	v_mfma_f32_16x16x32_bf16 v[76:79], v[146:149], v[208:211], v[76:79]
	v_mfma_f32_16x16x32_bf16 v[72:75], v[160:163], v[208:211], v[72:75]
	v_mfma_f32_16x16x32_bf16 v[124:127], v[156:159], v[188:191], v[124:127]
	v_mfma_f32_16x16x32_bf16 v[120:123], v[164:167], v[188:191], v[120:123]
	v_mfma_f32_16x16x32_bf16 v[116:119], v[156:159], v[196:199], v[116:119]
	v_mfma_f32_16x16x32_bf16 v[112:115], v[164:167], v[196:199], v[112:115]
	v_mfma_f32_16x16x32_bf16 v[92:95], v[156:159], v[204:207], v[92:95]
	v_mfma_f32_16x16x32_bf16 v[88:91], v[164:167], v[204:207], v[88:91]
	v_mfma_f32_16x16x32_bf16 v[76:79], v[156:159], v[212:215], v[76:79]
	v_mfma_f32_16x16x32_bf16 v[72:75], v[164:167], v[212:215], v[72:75]
	v_mfma_f32_16x16x32_bf16 v[108:111], v[168:171], v[184:187], v[108:111]
	v_mfma_f32_16x16x32_bf16 v[104:107], v[176:179], v[184:187], v[104:107]
	v_mfma_f32_16x16x32_bf16 v[100:103], v[168:171], v[192:195], v[100:103]
	v_mfma_f32_16x16x32_bf16 v[96:99], v[176:179], v[192:195], v[96:99]
	v_mfma_f32_16x16x32_bf16 v[84:87], v[168:171], v[200:203], v[84:87]
	v_mfma_f32_16x16x32_bf16 v[80:83], v[176:179], v[200:203], v[80:83]
	v_mfma_f32_16x16x32_bf16 v[68:71], v[168:171], v[208:211], v[68:71]
	v_mfma_f32_16x16x32_bf16 v[64:67], v[176:179], v[208:211], v[64:67]
	v_mfma_f32_16x16x32_bf16 v[108:111], v[172:175], v[188:191], v[108:111]
	v_mfma_f32_16x16x32_bf16 v[104:107], v[180:183], v[188:191], v[104:107]
	v_mfma_f32_16x16x32_bf16 v[100:103], v[172:175], v[196:199], v[100:103]
	v_mfma_f32_16x16x32_bf16 v[96:99], v[180:183], v[196:199], v[96:99]
	v_mfma_f32_16x16x32_bf16 v[84:87], v[172:175], v[204:207], v[84:87]
	v_mfma_f32_16x16x32_bf16 v[80:83], v[180:183], v[204:207], v[80:83]
	v_mfma_f32_16x16x32_bf16 v[68:71], v[172:175], v[212:215], v[68:71]
	v_mfma_f32_16x16x32_bf16 v[64:67], v[180:183], v[212:215], v[64:67]
	s_setprio 0
	s_barrier
	s_add_i32 s22, s57, s37
	s_mov_b32 m0, s22
	s_nop 0
	global_load_lds_dwordx4 v130, s[92:93]
	s_add_i32 m0, s22, 0x2000
	s_add_u32 s22, s26, 0xb0080
	s_addc_u32 s23, s27, 0
	s_add_i32 s26, s58, s37
	global_load_lds_dwordx4 v134, s[92:93]
	s_mov_b32 m0, s26
	s_nop 0
	global_load_lds_dwordx4 v130, s[22:23]
	s_add_i32 m0, s26, 0x2000
	s_nop 0
	global_load_lds_dwordx4 v134, s[22:23]
	s_mov_b32 m0, s43
	s_nop 0
	global_load_lds_dwordx4 v128, s[94:95]
	s_mov_b32 m0, s44
	s_nop 0
	global_load_lds_dwordx4 v132, s[94:95]
	ds_read_b128 v[184:187], v155 offset:49152
	ds_read_b128 v[188:191], v155 offset:50176
	ds_read_b128 v[192:195], v155 offset:51200
	ds_read_b128 v[196:199], v155 offset:52224
	ds_read_b128 v[200:203], v155 offset:53248
	ds_read_b128 v[204:207], v155 offset:54272
	ds_read_b128 v[208:211], v155 offset:55296
	ds_read_b128 v[212:215], v155 offset:56320
	s_waitcnt vmcnt(8)
	s_waitcnt lgkmcnt(0)
	s_barrier
	s_setprio 1
	v_mfma_f32_16x16x32_bf16 v[60:63], v[146:149], v[184:187], v[60:63]
	v_mfma_f32_16x16x32_bf16 v[56:59], v[160:163], v[184:187], v[56:59]
	v_mfma_f32_16x16x32_bf16 v[44:47], v[146:149], v[192:195], v[44:47]
	v_mfma_f32_16x16x32_bf16 v[40:43], v[160:163], v[192:195], v[40:43]
	v_mfma_f32_16x16x32_bf16 v[28:31], v[146:149], v[200:203], v[28:31]
	v_mfma_f32_16x16x32_bf16 v[24:27], v[160:163], v[200:203], v[24:27]
	v_mfma_f32_16x16x32_bf16 v[12:15], v[146:149], v[208:211], v[12:15]
	v_mfma_f32_16x16x32_bf16 v[8:11], v[160:163], v[208:211], v[8:11]
	v_mfma_f32_16x16x32_bf16 v[60:63], v[156:159], v[188:191], v[60:63]
	v_mfma_f32_16x16x32_bf16 v[56:59], v[164:167], v[188:191], v[56:59]
	v_mfma_f32_16x16x32_bf16 v[44:47], v[156:159], v[196:199], v[44:47]
	v_mfma_f32_16x16x32_bf16 v[40:43], v[164:167], v[196:199], v[40:43]
	v_mfma_f32_16x16x32_bf16 v[28:31], v[156:159], v[204:207], v[28:31]
	v_mfma_f32_16x16x32_bf16 v[24:27], v[164:167], v[204:207], v[24:27]
	v_mfma_f32_16x16x32_bf16 v[12:15], v[156:159], v[212:215], v[12:15]
	v_mfma_f32_16x16x32_bf16 v[8:11], v[164:167], v[212:215], v[8:11]
	v_mfma_f32_16x16x32_bf16 v[52:55], v[168:171], v[184:187], v[52:55]
	v_mfma_f32_16x16x32_bf16 v[48:51], v[176:179], v[184:187], v[48:51]
	v_mfma_f32_16x16x32_bf16 v[36:39], v[168:171], v[192:195], v[36:39]
	v_mfma_f32_16x16x32_bf16 v[32:35], v[176:179], v[192:195], v[32:35]
	v_mfma_f32_16x16x32_bf16 v[20:23], v[168:171], v[200:203], v[20:23]
	v_mfma_f32_16x16x32_bf16 v[16:19], v[176:179], v[200:203], v[16:19]
	v_mfma_f32_16x16x32_bf16 v[4:7], v[168:171], v[208:211], v[4:7]
	v_mfma_f32_16x16x32_bf16 v[0:3], v[176:179], v[208:211], v[0:3]
	v_mfma_f32_16x16x32_bf16 v[52:55], v[172:175], v[188:191], v[52:55]
	v_mfma_f32_16x16x32_bf16 v[48:51], v[180:183], v[188:191], v[48:51]
	v_mfma_f32_16x16x32_bf16 v[36:39], v[172:175], v[196:199], v[36:39]
	v_mfma_f32_16x16x32_bf16 v[32:35], v[180:183], v[196:199], v[32:35]
	v_mfma_f32_16x16x32_bf16 v[20:23], v[172:175], v[204:207], v[20:23]
	v_mfma_f32_16x16x32_bf16 v[16:19], v[180:183], v[204:207], v[16:19]
	v_mfma_f32_16x16x32_bf16 v[4:7], v[172:175], v[212:215], v[4:7]
	v_mfma_f32_16x16x32_bf16 v[0:3], v[180:183], v[212:215], v[0:3]
	s_setprio 0
	s_barrier
	s_add_i32 s56, s56, 2
	s_add_u32 s54, s54, 0x100
	s_addc_u32 s55, s55, 0
	s_cmp_gt_u32 s56, 41
	s_mov_b64 s[22:23], s[24:25]
	s_cbranch_scc0 .LBB0_1052
	s_and_b64 vcc, exec, s[10:11]
	s_cbranch_vccz .LBB0_1055
	s_barrier
